# K-loops (all but P3's): first half iteration peeled with C = 0 on each accumulator's first MFMA, the 128 v_mov clears per unit removed
# speedup vs baseline: 1.0050x; 1.0050x over previous
; #define PG8_STAGE(bufoff, gbase, voff) do { _Pragma("unroll") for (int _i = 0; _i < 2; ++_i) \
;         __builtin_amdgcn_global_load_lds((const unsigned*)((const char*)(gbase) + (voff)[_i]), (PG8_LAS unsigned*)(lds + (bufoff) + ldsw + _i * 8192), 16, 0, 0); } while (0)
; #define PG8_LDA(dst, b, h) do { _Pragma("unroll") for (int m = 0; m < 4; ++m) _Pragma("unroll") for (int k = 0; k < 2; ++k) dst[m][k] = *(const PG8_LAS bf16x8*)(lds + PG8_SA(b, h) + aoff + m * 2048 + k * 1024); } while (0)
; #define PG8_LDB(dst, b, h) do { _Pragma("unroll") for (int n = 0; n < 2; ++n) _Pragma("unroll") for (int k = 0; k < 2; ++k) dst[n][k] = *(const PG8_LAS bf16x8*)(lds + PG8_SB(b, h) + boff + n * 2048 + k * 1024); } while (0)
; #define PG8_WAIT_V(n) asm volatile("s_waitcnt vmcnt(" #n ")" ::: "memory")
; #define PG8_WAIT_L(n) asm volatile("s_waitcnt lgkmcnt(" #n ")" ::: "memory")
; #define PG8_BAR __builtin_amdgcn_s_barrier()
; #define PG8_SCHED __builtin_amdgcn_sched_barrier(0)
; template <class Epi, class Sched, bool ALIGN_EPI = false, bool SP2 = false>
; __device__ __forceinline__ void gemm_phase(PG8_LAS unsigned char* lds, const Gemm g, const Sched& S, const Epi& E) {
;     ...
;         const char* nA = has_next ? (const char*)g.A + (size_t)nxt.pm * tstep + nxt.kh * khb : cA; const char* nB = has_next ? (const char*)g.Bt + (size_t)nxt.pn * tstep + nxt.kh * khb : cB;
;         for (int t = 0; t < nt; t += 2) {
;             const bool last = (t == nt - 2);
;             const char* a1 = cA + (size_t)(t + 1) * kstep;
;             const char* a2 = last ? nA : cA + (size_t)(t + 2) * kstep; const char* b2 = last ? nB : cB + (size_t)(t + 2) * kstep;
;             const char* a3 = a2 + kstep; const char* b3 = b2 + kstep;
;             if (last && has_next) S.a_ready(nxt);
;             if constexpr (SP2) {
;             PG8_LDB(B0, 0, 0); PG8_LDB(B1, 0, 1); PG8_SCHED; PG8_LDA(At, 0, 0); PG8_STAGE(PG8_SA(1, 1), a1 + hstep, voffA);
;             PG8_WAIT_V(8); PG8_WAIT_L(0); PG8_BAR; PG8_MMA(0, 0, At, B0); PG8_MMA(0, 1, At, B1); PG8_BAR; PG8_SCHED;
;     ...
;         for (int a = 0; a < 2; ++a)
; #pragma unroll
;             for (int b = 0; b < 2; ++b)
; #pragma unroll
;                 for (int m = 0; m < 4; ++m)
; #pragma unroll
;                     for (int n = 0; n < 2; ++n) acc[a][b][m][n] = (f32x4){0.f, 0.f, 0.f, 0.f};
.LBB0_95:
	s_waitcnt lgkmcnt(0)
	s_ashr_i32 s55, s54, 31
	s_lshl_b64 s[34:35], s[54:55], 19
	s_add_u32 s76, s50, s34
	s_addc_u32 s77, s51, s35
	s_and_b64 s[34:35], s[2:3], exec
	s_cselect_b32 s8, s77, s81
	s_cselect_b32 s55, s76, s80
	s_ashr_i32 s49, s48, 31
	s_lshl_b64 s[34:35], s[48:49], 19
	s_add_u32 s78, s88, s34
	s_addc_u32 s79, s89, s35
	s_and_b64 s[34:35], s[2:3], exec
	s_cselect_b32 s49, s79, s83
	s_cselect_b32 vcc_lo, s78, s82
	s_add_u32 s80, s80, 0x40080
	s_addc_u32 s81, s81, 0
	s_add_u32 vcc_hi, s82, 0x100
	s_addc_u32 s34, s83, 0
	s_mov_b32 s35, -2
	ds_read_b128 v[128:131], v178
	ds_read_b128 v[132:135], v178 offset:1024
	ds_read_b128 v[136:139], v178 offset:2048
	ds_read_b128 v[140:143], v178 offset:3072
	ds_read_b128 v[166:169], v179
	ds_read_b128 v[170:173], v179 offset:1024
	ds_read_b128 v[190:193], v179 offset:2048
	ds_read_b128 v[194:197], v179 offset:3072
	s_add_u32 s36, s80, 0xfffc0080
	s_addc_u32 s37, s81, -1
	s_cmp_eq_u32 s35, 12
	s_cselect_b32 s87, s8, s37
	s_cselect_b32 s86, s55, s36
	s_cselect_b32 s83, s49, s34
	s_cselect_b32 s82, vcc_lo, vcc_hi
	s_add_i32 m0, s93, 0xc000
	ds_read_b128 v[198:201], v181
	ds_read_b128 v[202:205], v181 offset:1024
	ds_read_b128 v[206:209], v181 offset:2048
	ds_read_b128 v[210:213], v181 offset:3072
	ds_read_b128 v[214:217], v181 offset:4096
	ds_read_b128 v[218:221], v181 offset:5120
	ds_read_b128 v[222:225], v181 offset:6144
	ds_read_b128 v[226:229], v181 offset:7168
	global_load_lds_dwordx4 v158, s[80:81]
	s_add_i32 m0, s93, 0xe000
	s_nop 0
	global_load_lds_dwordx4 v160, s[80:81]
	s_waitcnt vmcnt(8)
	s_waitcnt lgkmcnt(0)
	s_barrier
	s_setprio 1
	v_mfma_f32_16x16x32_bf16 v[124:127], v[128:131], v[198:201], 0
	v_mfma_f32_16x16x32_bf16 v[120:123], v[136:139], v[198:201], 0
	v_mfma_f32_16x16x32_bf16 v[108:111], v[128:131], v[206:209], 0
	v_mfma_f32_16x16x32_bf16 v[104:107], v[136:139], v[206:209], 0
	v_mfma_f32_16x16x32_bf16 v[92:95], v[128:131], v[214:217], 0
	v_mfma_f32_16x16x32_bf16 v[88:91], v[136:139], v[214:217], 0
	v_mfma_f32_16x16x32_bf16 v[76:79], v[128:131], v[222:225], 0
	v_mfma_f32_16x16x32_bf16 v[72:75], v[136:139], v[222:225], 0
	v_mfma_f32_16x16x32_bf16 v[124:127], v[132:135], v[202:205], v[124:127]
	v_mfma_f32_16x16x32_bf16 v[120:123], v[140:143], v[202:205], v[120:123]
	v_mfma_f32_16x16x32_bf16 v[108:111], v[132:135], v[210:213], v[108:111]
	v_mfma_f32_16x16x32_bf16 v[104:107], v[140:143], v[210:213], v[104:107]
	v_mfma_f32_16x16x32_bf16 v[92:95], v[132:135], v[218:221], v[92:95]
	v_mfma_f32_16x16x32_bf16 v[88:91], v[140:143], v[218:221], v[88:91]
	v_mfma_f32_16x16x32_bf16 v[76:79], v[132:135], v[226:229], v[76:79]
	v_mfma_f32_16x16x32_bf16 v[72:75], v[140:143], v[226:229], v[72:75]
	v_mfma_f32_16x16x32_bf16 v[116:119], v[166:169], v[198:201], 0
	v_mfma_f32_16x16x32_bf16 v[112:115], v[190:193], v[198:201], 0
	v_mfma_f32_16x16x32_bf16 v[100:103], v[166:169], v[206:209], 0
	v_mfma_f32_16x16x32_bf16 v[96:99], v[190:193], v[206:209], 0
	v_mfma_f32_16x16x32_bf16 v[84:87], v[166:169], v[214:217], 0
	v_mfma_f32_16x16x32_bf16 v[80:83], v[190:193], v[214:217], 0
	v_mfma_f32_16x16x32_bf16 v[68:71], v[166:169], v[222:225], 0
	v_mfma_f32_16x16x32_bf16 v[64:67], v[190:193], v[222:225], 0
	v_mfma_f32_16x16x32_bf16 v[116:119], v[170:173], v[202:205], v[116:119]
	v_mfma_f32_16x16x32_bf16 v[112:115], v[194:197], v[202:205], v[112:115]
	v_mfma_f32_16x16x32_bf16 v[100:103], v[170:173], v[210:213], v[100:103]
	v_mfma_f32_16x16x32_bf16 v[96:99], v[194:197], v[210:213], v[96:99]
	v_mfma_f32_16x16x32_bf16 v[84:87], v[170:173], v[218:221], v[84:87]
	v_mfma_f32_16x16x32_bf16 v[80:83], v[194:197], v[218:221], v[80:83]
	v_mfma_f32_16x16x32_bf16 v[68:71], v[170:173], v[226:229], v[68:71]
	v_mfma_f32_16x16x32_bf16 v[64:67], v[194:197], v[226:229], v[64:67]
	s_setprio 0
	s_barrier
	s_add_i32 s36, s23, s90
	v_lshl_add_u64 v[174:175], s[82:83], 0, v[148:149]
	s_mov_b32 m0, s36
	ds_read_b128 v[198:201], v181 offset:16384
	ds_read_b128 v[202:205], v181 offset:17408
	ds_read_b128 v[206:209], v181 offset:18432
	ds_read_b128 v[210:213], v181 offset:19456
	ds_read_b128 v[214:217], v181 offset:20480
	ds_read_b128 v[218:221], v181 offset:21504
	ds_read_b128 v[222:225], v181 offset:22528
	ds_read_b128 v[226:229], v181 offset:23552
	global_load_lds_dwordx4 v[174:175], off
	s_add_i32 m0, s36, 0x2000
	s_add_u32 s36, s82, 0x40000
	v_lshl_add_u64 v[186:187], s[82:83], 0, v[144:145]
	s_addc_u32 s37, s83, 0
	s_add_i32 s20, s41, s90
	global_load_lds_dwordx4 v[186:187], off
	s_mov_b32 m0, s20
	v_lshl_add_u64 v[232:233], s[86:87], 0, v[146:147]
	global_load_lds_dwordx4 v148, s[36:37]
	s_add_i32 m0, s20, 0x2000
	s_nop 0
	global_load_lds_dwordx4 v144, s[36:37]
	v_lshl_add_u64 v[230:231], s[86:87], 0, v[150:151]
	s_mov_b32 m0, s93
	s_nop 0
	global_load_lds_dwordx4 v[230:231], off
	s_mov_b32 m0, s94
	s_nop 0
	global_load_lds_dwordx4 v[232:233], off
	s_waitcnt vmcnt(8)
	s_waitcnt lgkmcnt(0)
	s_barrier
; #define PG8_STAGE(bufoff, gbase, voff) do { _Pragma("unroll") for (int _i = 0; _i < 2; ++_i) \
;         __builtin_amdgcn_global_load_lds((const unsigned*)((const char*)(gbase) + (voff)[_i]), (PG8_LAS unsigned*)(lds + (bufoff) + ldsw + _i * 8192), 16, 0, 0); } while (0)
; #define PG8_LDA(dst, b, h) do { _Pragma("unroll") for (int m = 0; m < 4; ++m) _Pragma("unroll") for (int k = 0; k < 2; ++k) dst[m][k] = *(const PG8_LAS bf16x8*)(lds + PG8_SA(b, h) + aoff + m * 2048 + k * 1024); } while (0)
; #define PG8_LDB(dst, b, h) do { _Pragma("unroll") for (int n = 0; n < 2; ++n) _Pragma("unroll") for (int k = 0; k < 2; ++k) dst[n][k] = *(const PG8_LAS bf16x8*)(lds + PG8_SB(b, h) + boff + n * 2048 + k * 1024); } while (0)
; #define PG8_MMA(ai, bj, At, Bt) do { __builtin_amdgcn_s_setprio(1); _Pragma("unroll") for (int m = 0; m < 4; ++m) _Pragma("unroll") for (int n = 0; n < 2; ++n) _Pragma("unroll") for (int k = 0; k < 2; ++k) \
;         acc[ai][bj][m][n] = __builtin_amdgcn_mfma_f32_16x16x32_bf16(Bt[n][k], At[m][k], acc[ai][bj][m][n], 0, 0, 0); __builtin_amdgcn_s_setprio(0); } while (0)
; #define PG8_WAIT_V(n) asm volatile("s_waitcnt vmcnt(" #n ")" ::: "memory")
; #define PG8_WAIT_L(n) asm volatile("s_waitcnt lgkmcnt(" #n ")" ::: "memory")
; #define PG8_BAR __builtin_amdgcn_s_barrier()
; #define PG8_SCHED __builtin_amdgcn_sched_barrier(0)
; template <class Epi, class Sched, bool ALIGN_EPI = false, bool SP2 = false>
; __device__ __forceinline__ void gemm_phase(PG8_LAS unsigned char* lds, const Gemm g, const Sched& S, const Epi& E) {
;     ...
;             PG8_LDB(B0, 0, 0); PG8_LDB(B1, 0, 1); PG8_SCHED; PG8_LDA(At, 0, 0); PG8_STAGE(PG8_SA(1, 1), a1 + hstep, voffA);
;             PG8_WAIT_V(8); PG8_WAIT_L(0); PG8_BAR; PG8_MMA(0, 0, At, B0); PG8_MMA(0, 1, At, B1); PG8_BAR; PG8_SCHED;
;             PG8_LDA(At, 0, 1); PG8_STAGE(PG8_SB(0, 0), b2, voffB); PG8_STAGE(PG8_SB(0, 1), b2 + hstep, voffB); PG8_STAGE(PG8_SA(0, 0), a2, voffA);
;             PG8_WAIT_V(8); PG8_WAIT_L(0); PG8_BAR; PG8_MMA(1, 0, At, B0); PG8_MMA(1, 1, At, B1); PG8_BAR; PG8_SCHED;
	s_setprio 1
	v_mfma_f32_16x16x32_bf16 v[60:63], v[128:131], v[198:201], 0
	v_mfma_f32_16x16x32_bf16 v[56:59], v[136:139], v[198:201], 0
	v_mfma_f32_16x16x32_bf16 v[44:47], v[128:131], v[206:209], 0
	v_mfma_f32_16x16x32_bf16 v[40:43], v[136:139], v[206:209], 0
	v_mfma_f32_16x16x32_bf16 v[28:31], v[128:131], v[214:217], 0
	v_mfma_f32_16x16x32_bf16 v[24:27], v[136:139], v[214:217], 0
	v_mfma_f32_16x16x32_bf16 v[12:15], v[128:131], v[222:225], 0
	v_mfma_f32_16x16x32_bf16 v[8:11], v[136:139], v[222:225], 0
	v_mfma_f32_16x16x32_bf16 v[60:63], v[132:135], v[202:205], v[60:63]
	v_mfma_f32_16x16x32_bf16 v[56:59], v[140:143], v[202:205], v[56:59]
	v_mfma_f32_16x16x32_bf16 v[44:47], v[132:135], v[210:213], v[44:47]
	v_mfma_f32_16x16x32_bf16 v[40:43], v[140:143], v[210:213], v[40:43]
	v_mfma_f32_16x16x32_bf16 v[28:31], v[132:135], v[218:221], v[28:31]
	v_mfma_f32_16x16x32_bf16 v[24:27], v[140:143], v[218:221], v[24:27]
	v_mfma_f32_16x16x32_bf16 v[12:15], v[132:135], v[226:229], v[12:15]
	v_mfma_f32_16x16x32_bf16 v[8:11], v[140:143], v[226:229], v[8:11]
	v_mfma_f32_16x16x32_bf16 v[52:55], v[166:169], v[198:201], 0
	v_mfma_f32_16x16x32_bf16 v[48:51], v[190:193], v[198:201], 0
	v_mfma_f32_16x16x32_bf16 v[36:39], v[166:169], v[206:209], 0
	v_mfma_f32_16x16x32_bf16 v[32:35], v[190:193], v[206:209], 0
	v_mfma_f32_16x16x32_bf16 v[20:23], v[166:169], v[214:217], 0
	v_mfma_f32_16x16x32_bf16 v[16:19], v[190:193], v[214:217], 0
	v_mfma_f32_16x16x32_bf16 v[4:7], v[166:169], v[222:225], 0
	v_mfma_f32_16x16x32_bf16 v[0:3], v[190:193], v[222:225], 0
	v_mfma_f32_16x16x32_bf16 v[52:55], v[170:173], v[202:205], v[52:55]
	v_mfma_f32_16x16x32_bf16 v[48:51], v[194:197], v[202:205], v[48:51]
	v_mfma_f32_16x16x32_bf16 v[36:39], v[170:173], v[210:213], v[36:39]
	v_mfma_f32_16x16x32_bf16 v[32:35], v[194:197], v[210:213], v[32:35]
	v_mfma_f32_16x16x32_bf16 v[20:23], v[170:173], v[218:221], v[20:23]
	v_mfma_f32_16x16x32_bf16 v[16:19], v[194:197], v[218:221], v[16:19]
	v_mfma_f32_16x16x32_bf16 v[4:7], v[170:173], v[226:229], v[4:7]
	v_mfma_f32_16x16x32_bf16 v[0:3], v[194:197], v[226:229], v[0:3]
	s_setprio 0
	s_barrier
	s_branch .Lmy_peel_96_mid
.LBB0_96:
	ds_read_b128 v[128:131], v178
	ds_read_b128 v[132:135], v178 offset:1024
	ds_read_b128 v[136:139], v178 offset:2048
	ds_read_b128 v[140:143], v178 offset:3072
	ds_read_b128 v[166:169], v179
	ds_read_b128 v[170:173], v179 offset:1024
	ds_read_b128 v[190:193], v179 offset:2048
	ds_read_b128 v[194:197], v179 offset:3072
	s_add_u32 s36, s80, 0xfffc0080
	s_addc_u32 s37, s81, -1
	s_cmp_eq_u32 s35, 12
	s_cselect_b32 s87, s8, s37
	s_cselect_b32 s86, s55, s36
	s_cselect_b32 s83, s49, s34
	s_cselect_b32 s82, vcc_lo, vcc_hi
	s_add_i32 m0, s93, 0xc000
	ds_read_b128 v[198:201], v181
	ds_read_b128 v[202:205], v181 offset:1024
	ds_read_b128 v[206:209], v181 offset:2048
	ds_read_b128 v[210:213], v181 offset:3072
	ds_read_b128 v[214:217], v181 offset:4096
	ds_read_b128 v[218:221], v181 offset:5120
	ds_read_b128 v[222:225], v181 offset:6144
	ds_read_b128 v[226:229], v181 offset:7168
	global_load_lds_dwordx4 v158, s[80:81]
	s_add_i32 m0, s93, 0xe000
	s_nop 0
	global_load_lds_dwordx4 v160, s[80:81]
	s_waitcnt vmcnt(8)
	s_waitcnt lgkmcnt(0)
	s_barrier
	s_setprio 1
	v_mfma_f32_16x16x32_bf16 v[124:127], v[128:131], v[198:201], v[124:127]
	v_mfma_f32_16x16x32_bf16 v[120:123], v[136:139], v[198:201], v[120:123]
	v_mfma_f32_16x16x32_bf16 v[108:111], v[128:131], v[206:209], v[108:111]
	v_mfma_f32_16x16x32_bf16 v[104:107], v[136:139], v[206:209], v[104:107]
	v_mfma_f32_16x16x32_bf16 v[92:95], v[128:131], v[214:217], v[92:95]
	v_mfma_f32_16x16x32_bf16 v[88:91], v[136:139], v[214:217], v[88:91]
	v_mfma_f32_16x16x32_bf16 v[76:79], v[128:131], v[222:225], v[76:79]
	v_mfma_f32_16x16x32_bf16 v[72:75], v[136:139], v[222:225], v[72:75]
	v_mfma_f32_16x16x32_bf16 v[124:127], v[132:135], v[202:205], v[124:127]
	v_mfma_f32_16x16x32_bf16 v[120:123], v[140:143], v[202:205], v[120:123]
	v_mfma_f32_16x16x32_bf16 v[108:111], v[132:135], v[210:213], v[108:111]
	v_mfma_f32_16x16x32_bf16 v[104:107], v[140:143], v[210:213], v[104:107]
	v_mfma_f32_16x16x32_bf16 v[92:95], v[132:135], v[218:221], v[92:95]
	v_mfma_f32_16x16x32_bf16 v[88:91], v[140:143], v[218:221], v[88:91]
	v_mfma_f32_16x16x32_bf16 v[76:79], v[132:135], v[226:229], v[76:79]
	v_mfma_f32_16x16x32_bf16 v[72:75], v[140:143], v[226:229], v[72:75]
	v_mfma_f32_16x16x32_bf16 v[116:119], v[166:169], v[198:201], v[116:119]
	v_mfma_f32_16x16x32_bf16 v[112:115], v[190:193], v[198:201], v[112:115]
	v_mfma_f32_16x16x32_bf16 v[100:103], v[166:169], v[206:209], v[100:103]
	v_mfma_f32_16x16x32_bf16 v[96:99], v[190:193], v[206:209], v[96:99]
	v_mfma_f32_16x16x32_bf16 v[84:87], v[166:169], v[214:217], v[84:87]
	v_mfma_f32_16x16x32_bf16 v[80:83], v[190:193], v[214:217], v[80:83]
	v_mfma_f32_16x16x32_bf16 v[68:71], v[166:169], v[222:225], v[68:71]
	v_mfma_f32_16x16x32_bf16 v[64:67], v[190:193], v[222:225], v[64:67]
	v_mfma_f32_16x16x32_bf16 v[116:119], v[170:173], v[202:205], v[116:119]
	v_mfma_f32_16x16x32_bf16 v[112:115], v[194:197], v[202:205], v[112:115]
	v_mfma_f32_16x16x32_bf16 v[100:103], v[170:173], v[210:213], v[100:103]
	v_mfma_f32_16x16x32_bf16 v[96:99], v[194:197], v[210:213], v[96:99]
	v_mfma_f32_16x16x32_bf16 v[84:87], v[170:173], v[218:221], v[84:87]
	v_mfma_f32_16x16x32_bf16 v[80:83], v[194:197], v[218:221], v[80:83]
	v_mfma_f32_16x16x32_bf16 v[68:71], v[170:173], v[226:229], v[68:71]
	v_mfma_f32_16x16x32_bf16 v[64:67], v[194:197], v[226:229], v[64:67]
	s_setprio 0
	s_barrier
; #define PG8_STAGE(bufoff, gbase, voff) do { _Pragma("unroll") for (int _i = 0; _i < 2; ++_i) \
;         __builtin_amdgcn_global_load_lds((const unsigned*)((const char*)(gbase) + (voff)[_i]), (PG8_LAS unsigned*)(lds + (bufoff) + ldsw + _i * 8192), 16, 0, 0); } while (0)
; #define PG8_LDA(dst, b, h) do { _Pragma("unroll") for (int m = 0; m < 4; ++m) _Pragma("unroll") for (int k = 0; k < 2; ++k) dst[m][k] = *(const PG8_LAS bf16x8*)(lds + PG8_SA(b, h) + aoff + m * 2048 + k * 1024); } while (0)
; #define PG8_MMA(ai, bj, At, Bt) do { __builtin_amdgcn_s_setprio(1); _Pragma("unroll") for (int m = 0; m < 4; ++m) _Pragma("unroll") for (int n = 0; n < 2; ++n) _Pragma("unroll") for (int k = 0; k < 2; ++k) \
;         acc[ai][bj][m][n] = __builtin_amdgcn_mfma_f32_16x16x32_bf16(Bt[n][k], At[m][k], acc[ai][bj][m][n], 0, 0, 0); __builtin_amdgcn_s_setprio(0); } while (0)
; #define PG8_WAIT_V(n) asm volatile("s_waitcnt vmcnt(" #n ")" ::: "memory")
; #define PG8_WAIT_L(n) asm volatile("s_waitcnt lgkmcnt(" #n ")" ::: "memory")
; #define PG8_BAR __builtin_amdgcn_s_barrier()
; #define PG8_SCHED __builtin_amdgcn_sched_barrier(0)
; template <class Epi, class Sched, bool ALIGN_EPI = false, bool SP2 = false>
; __device__ __forceinline__ void gemm_phase(PG8_LAS unsigned char* lds, const Gemm g, const Sched& S, const Epi& E) {
;     ...
;             PG8_LDA(At, 0, 1); PG8_STAGE(PG8_SB(0, 0), b2, voffB); PG8_STAGE(PG8_SB(0, 1), b2 + hstep, voffB); PG8_STAGE(PG8_SA(0, 0), a2, voffA);
;             PG8_WAIT_V(8); PG8_WAIT_L(0); PG8_BAR; PG8_MMA(1, 0, At, B0); PG8_MMA(1, 1, At, B1); PG8_BAR; PG8_SCHED;
	s_add_i32 s36, s23, s90
	v_lshl_add_u64 v[174:175], s[82:83], 0, v[148:149]
	s_mov_b32 m0, s36
	ds_read_b128 v[198:201], v181 offset:16384
	ds_read_b128 v[202:205], v181 offset:17408
	ds_read_b128 v[206:209], v181 offset:18432
	ds_read_b128 v[210:213], v181 offset:19456
	ds_read_b128 v[214:217], v181 offset:20480
	ds_read_b128 v[218:221], v181 offset:21504
	ds_read_b128 v[222:225], v181 offset:22528
	ds_read_b128 v[226:229], v181 offset:23552
	global_load_lds_dwordx4 v[174:175], off
	s_add_i32 m0, s36, 0x2000
	s_add_u32 s36, s82, 0x40000
	v_lshl_add_u64 v[186:187], s[82:83], 0, v[144:145]
	s_addc_u32 s37, s83, 0
	s_add_i32 s20, s41, s90
	global_load_lds_dwordx4 v[186:187], off
	s_mov_b32 m0, s20
	v_lshl_add_u64 v[232:233], s[86:87], 0, v[146:147]
	global_load_lds_dwordx4 v148, s[36:37]
	s_add_i32 m0, s20, 0x2000
	s_nop 0
	global_load_lds_dwordx4 v144, s[36:37]
	v_lshl_add_u64 v[230:231], s[86:87], 0, v[150:151]
	s_mov_b32 m0, s93
	s_nop 0
	global_load_lds_dwordx4 v[230:231], off
	s_mov_b32 m0, s94
	s_nop 0
	global_load_lds_dwordx4 v[232:233], off
	s_waitcnt vmcnt(8)
	s_waitcnt lgkmcnt(0)
	s_barrier
	s_setprio 1
	v_mfma_f32_16x16x32_bf16 v[60:63], v[128:131], v[198:201], v[60:63]
	v_mfma_f32_16x16x32_bf16 v[56:59], v[136:139], v[198:201], v[56:59]
	v_mfma_f32_16x16x32_bf16 v[44:47], v[128:131], v[206:209], v[44:47]
	v_mfma_f32_16x16x32_bf16 v[40:43], v[136:139], v[206:209], v[40:43]
	v_mfma_f32_16x16x32_bf16 v[28:31], v[128:131], v[214:217], v[28:31]
	v_mfma_f32_16x16x32_bf16 v[24:27], v[136:139], v[214:217], v[24:27]
	v_mfma_f32_16x16x32_bf16 v[12:15], v[128:131], v[222:225], v[12:15]
	v_mfma_f32_16x16x32_bf16 v[8:11], v[136:139], v[222:225], v[8:11]
	v_mfma_f32_16x16x32_bf16 v[60:63], v[132:135], v[202:205], v[60:63]
	v_mfma_f32_16x16x32_bf16 v[56:59], v[140:143], v[202:205], v[56:59]
	v_mfma_f32_16x16x32_bf16 v[44:47], v[132:135], v[210:213], v[44:47]
	v_mfma_f32_16x16x32_bf16 v[40:43], v[140:143], v[210:213], v[40:43]
	v_mfma_f32_16x16x32_bf16 v[28:31], v[132:135], v[218:221], v[28:31]
	v_mfma_f32_16x16x32_bf16 v[24:27], v[140:143], v[218:221], v[24:27]
	v_mfma_f32_16x16x32_bf16 v[12:15], v[132:135], v[226:229], v[12:15]
	v_mfma_f32_16x16x32_bf16 v[8:11], v[140:143], v[226:229], v[8:11]
	v_mfma_f32_16x16x32_bf16 v[52:55], v[166:169], v[198:201], v[52:55]
	v_mfma_f32_16x16x32_bf16 v[48:51], v[190:193], v[198:201], v[48:51]
	v_mfma_f32_16x16x32_bf16 v[36:39], v[166:169], v[206:209], v[36:39]
	v_mfma_f32_16x16x32_bf16 v[32:35], v[190:193], v[206:209], v[32:35]
	v_mfma_f32_16x16x32_bf16 v[20:23], v[166:169], v[214:217], v[20:23]
	v_mfma_f32_16x16x32_bf16 v[16:19], v[190:193], v[214:217], v[16:19]
	v_mfma_f32_16x16x32_bf16 v[4:7], v[166:169], v[222:225], v[4:7]
	v_mfma_f32_16x16x32_bf16 v[0:3], v[190:193], v[222:225], v[0:3]
	v_mfma_f32_16x16x32_bf16 v[52:55], v[170:173], v[202:205], v[52:55]
	v_mfma_f32_16x16x32_bf16 v[48:51], v[194:197], v[202:205], v[48:51]
	v_mfma_f32_16x16x32_bf16 v[36:39], v[170:173], v[210:213], v[36:39]
	v_mfma_f32_16x16x32_bf16 v[32:35], v[194:197], v[210:213], v[32:35]
	v_mfma_f32_16x16x32_bf16 v[20:23], v[170:173], v[218:221], v[20:23]
	v_mfma_f32_16x16x32_bf16 v[16:19], v[194:197], v[218:221], v[16:19]
	v_mfma_f32_16x16x32_bf16 v[4:7], v[170:173], v[226:229], v[4:7]
	v_mfma_f32_16x16x32_bf16 v[0:3], v[194:197], v[226:229], v[0:3]
	s_setprio 0
	s_barrier
; #define PG8_STAGE(bufoff, gbase, voff) do { _Pragma("unroll") for (int _i = 0; _i < 2; ++_i) \
;         __builtin_amdgcn_global_load_lds((const unsigned*)((const char*)(gbase) + (voff)[_i]), (PG8_LAS unsigned*)(lds + (bufoff) + ldsw + _i * 8192), 16, 0, 0); } while (0)
; #define PG8_LDA(dst, b, h) do { _Pragma("unroll") for (int m = 0; m < 4; ++m) _Pragma("unroll") for (int k = 0; k < 2; ++k) dst[m][k] = *(const PG8_LAS bf16x8*)(lds + PG8_SA(b, h) + aoff + m * 2048 + k * 1024); } while (0)
; #define PG8_LDB(dst, b, h) do { _Pragma("unroll") for (int n = 0; n < 2; ++n) _Pragma("unroll") for (int k = 0; k < 2; ++k) dst[n][k] = *(const PG8_LAS bf16x8*)(lds + PG8_SB(b, h) + boff + n * 2048 + k * 1024); } while (0)
; #define PG8_MMA(ai, bj, At, Bt) do { __builtin_amdgcn_s_setprio(1); _Pragma("unroll") for (int m = 0; m < 4; ++m) _Pragma("unroll") for (int n = 0; n < 2; ++n) _Pragma("unroll") for (int k = 0; k < 2; ++k) \
;         acc[ai][bj][m][n] = __builtin_amdgcn_mfma_f32_16x16x32_bf16(Bt[n][k], At[m][k], acc[ai][bj][m][n], 0, 0, 0); __builtin_amdgcn_s_setprio(0); } while (0)
; #define PG8_WAIT_V(n) asm volatile("s_waitcnt vmcnt(" #n ")" ::: "memory")
; #define PG8_WAIT_L(n) asm volatile("s_waitcnt lgkmcnt(" #n ")" ::: "memory")
; #define PG8_BAR __builtin_amdgcn_s_barrier()
; #define PG8_SCHED __builtin_amdgcn_sched_barrier(0)
; template <class Epi, class Sched, bool ALIGN_EPI = false, bool SP2 = false>
; __device__ __forceinline__ void gemm_phase(PG8_LAS unsigned char* lds, const Gemm g, const Sched& S, const Epi& E) {
;     ...
;         for (int t = 0; t < nt; t += 2) {
;     ...
;             PG8_LDB(B0, 1, 0); PG8_LDB(B1, 1, 1); PG8_SCHED; PG8_LDA(At, 1, 0); PG8_STAGE(PG8_SA(0, 1), a2 + hstep, voffA);
;             PG8_WAIT_V(8); PG8_WAIT_L(0); PG8_BAR; PG8_MMA(0, 0, At, B0); PG8_MMA(0, 1, At, B1); PG8_BAR; PG8_SCHED;
;             PG8_LDA(At, 1, 1); PG8_STAGE(PG8_SB(1, 0), b3, voffB); PG8_STAGE(PG8_SB(1, 1), b3 + hstep, voffB); PG8_STAGE(PG8_SA(1, 0), a3, voffA);
;             PG8_WAIT_V(8); PG8_WAIT_L(0); PG8_BAR; PG8_MMA(1, 0, At, B0); PG8_MMA(1, 1, At, B1); PG8_BAR; PG8_SCHED;
.Lmy_peel_96_mid:
	s_add_i32 s20, 0, 0x18000
	s_add_i32 s21, 0, 0x1c000
	v_add_u32_e32 v140, s20, v176
	v_add_u32_e32 v152, s21, v176
	ds_read_b128 v[128:131], v140
	ds_read_b128 v[132:135], v140 offset:1024
	ds_read_b128 v[136:139], v140 offset:2048
	ds_read_b128 v[140:143], v140 offset:3072
	ds_read_b128 v[166:169], v152
	ds_read_b128 v[170:173], v152 offset:1024
	ds_read_b128 v[190:193], v152 offset:2048
	ds_read_b128 v[194:197], v152 offset:3072
	s_add_u32 s36, s86, 0x40000
	s_addc_u32 s37, s87, 0
	s_mov_b32 m0, s95
	ds_read_b128 v[198:201], v181 offset:32768
	ds_read_b128 v[202:205], v181 offset:33792
	ds_read_b128 v[206:209], v181 offset:34816
	ds_read_b128 v[210:213], v181 offset:35840
	ds_read_b128 v[214:217], v181 offset:36864
	ds_read_b128 v[218:221], v181 offset:37888
	ds_read_b128 v[222:225], v181 offset:38912
	ds_read_b128 v[226:229], v181 offset:39936
	global_load_lds_dwordx4 v150, s[36:37]
	s_mov_b32 m0, s97
	s_nop 0
	global_load_lds_dwordx4 v146, s[36:37]
	s_waitcnt vmcnt(8)
	s_waitcnt lgkmcnt(0)
	s_barrier
	s_setprio 1
	v_mfma_f32_16x16x32_bf16 v[124:127], v[128:131], v[198:201], v[124:127]
	v_mfma_f32_16x16x32_bf16 v[120:123], v[136:139], v[198:201], v[120:123]
	v_mfma_f32_16x16x32_bf16 v[108:111], v[128:131], v[206:209], v[108:111]
	v_mfma_f32_16x16x32_bf16 v[104:107], v[136:139], v[206:209], v[104:107]
	v_mfma_f32_16x16x32_bf16 v[92:95], v[128:131], v[214:217], v[92:95]
	v_mfma_f32_16x16x32_bf16 v[88:91], v[136:139], v[214:217], v[88:91]
	v_mfma_f32_16x16x32_bf16 v[76:79], v[128:131], v[222:225], v[76:79]
	v_mfma_f32_16x16x32_bf16 v[72:75], v[136:139], v[222:225], v[72:75]
	v_mfma_f32_16x16x32_bf16 v[124:127], v[132:135], v[202:205], v[124:127]
	v_mfma_f32_16x16x32_bf16 v[120:123], v[140:143], v[202:205], v[120:123]
	v_mfma_f32_16x16x32_bf16 v[108:111], v[132:135], v[210:213], v[108:111]
	v_mfma_f32_16x16x32_bf16 v[104:107], v[140:143], v[210:213], v[104:107]
	v_mfma_f32_16x16x32_bf16 v[92:95], v[132:135], v[218:221], v[92:95]
	v_mfma_f32_16x16x32_bf16 v[88:91], v[140:143], v[218:221], v[88:91]
	v_mfma_f32_16x16x32_bf16 v[76:79], v[132:135], v[226:229], v[76:79]
	v_mfma_f32_16x16x32_bf16 v[72:75], v[140:143], v[226:229], v[72:75]
	v_mfma_f32_16x16x32_bf16 v[116:119], v[166:169], v[198:201], v[116:119]
	v_mfma_f32_16x16x32_bf16 v[112:115], v[190:193], v[198:201], v[112:115]
	v_mfma_f32_16x16x32_bf16 v[100:103], v[166:169], v[206:209], v[100:103]
	v_mfma_f32_16x16x32_bf16 v[96:99], v[190:193], v[206:209], v[96:99]
	v_mfma_f32_16x16x32_bf16 v[84:87], v[166:169], v[214:217], v[84:87]
	v_mfma_f32_16x16x32_bf16 v[80:83], v[190:193], v[214:217], v[80:83]
	v_mfma_f32_16x16x32_bf16 v[68:71], v[166:169], v[222:225], v[68:71]
	v_mfma_f32_16x16x32_bf16 v[64:67], v[190:193], v[222:225], v[64:67]
	v_mfma_f32_16x16x32_bf16 v[116:119], v[170:173], v[202:205], v[116:119]
	v_mfma_f32_16x16x32_bf16 v[112:115], v[194:197], v[202:205], v[112:115]
	v_mfma_f32_16x16x32_bf16 v[100:103], v[170:173], v[210:213], v[100:103]
	v_mfma_f32_16x16x32_bf16 v[96:99], v[194:197], v[210:213], v[96:99]
	v_mfma_f32_16x16x32_bf16 v[84:87], v[170:173], v[218:221], v[84:87]
	v_mfma_f32_16x16x32_bf16 v[80:83], v[194:197], v[218:221], v[80:83]
	v_mfma_f32_16x16x32_bf16 v[68:71], v[170:173], v[226:229], v[68:71]
	v_mfma_f32_16x16x32_bf16 v[64:67], v[194:197], v[226:229], v[64:67]
	s_setprio 0
	s_barrier
	s_add_i32 s20, s20, s90
	v_lshl_add_u64 v[174:175], v[174:175], 0, s[26:27]
	s_mov_b32 m0, s20
	ds_read_b128 v[198:201], v181 offset:49152
	ds_read_b128 v[202:205], v181 offset:50176
	ds_read_b128 v[206:209], v181 offset:51200
	ds_read_b128 v[210:213], v181 offset:52224
	ds_read_b128 v[214:217], v181 offset:53248
	ds_read_b128 v[218:221], v181 offset:54272
	ds_read_b128 v[222:225], v181 offset:55296
	ds_read_b128 v[226:229], v181 offset:56320
	global_load_lds_dwordx4 v[174:175], off
	s_add_i32 m0, s20, 0x2000
	s_add_u32 s36, s82, 0x40080
	v_lshl_add_u64 v[174:175], v[186:187], 0, s[26:27]
	s_addc_u32 s37, s83, 0
	s_add_i32 s20, s21, s90
	global_load_lds_dwordx4 v[174:175], off
	s_mov_b32 m0, s20
	s_nop 0
	global_load_lds_dwordx4 v148, s[36:37]
	s_add_i32 m0, s20, 0x2000
	s_nop 0
	global_load_lds_dwordx4 v144, s[36:37]
	v_lshl_add_u64 v[174:175], v[230:231], 0, s[26:27]
	s_mov_b32 m0, s42
	s_nop 0
	global_load_lds_dwordx4 v[174:175], off
	v_lshl_add_u64 v[174:175], v[232:233], 0, s[26:27]
	s_mov_b32 m0, s43
	s_nop 0
	global_load_lds_dwordx4 v[174:175], off
	s_waitcnt vmcnt(8)
	s_waitcnt lgkmcnt(0)
	s_barrier
	s_setprio 1
	v_mfma_f32_16x16x32_bf16 v[60:63], v[128:131], v[198:201], v[60:63]
	v_mfma_f32_16x16x32_bf16 v[56:59], v[136:139], v[198:201], v[56:59]
	v_mfma_f32_16x16x32_bf16 v[44:47], v[128:131], v[206:209], v[44:47]
	v_mfma_f32_16x16x32_bf16 v[40:43], v[136:139], v[206:209], v[40:43]
	v_mfma_f32_16x16x32_bf16 v[28:31], v[128:131], v[214:217], v[28:31]
	v_mfma_f32_16x16x32_bf16 v[24:27], v[136:139], v[214:217], v[24:27]
	v_mfma_f32_16x16x32_bf16 v[12:15], v[128:131], v[222:225], v[12:15]
	v_mfma_f32_16x16x32_bf16 v[8:11], v[136:139], v[222:225], v[8:11]
	v_mfma_f32_16x16x32_bf16 v[60:63], v[132:135], v[202:205], v[60:63]
	v_mfma_f32_16x16x32_bf16 v[56:59], v[140:143], v[202:205], v[56:59]
	v_mfma_f32_16x16x32_bf16 v[44:47], v[132:135], v[210:213], v[44:47]
	v_mfma_f32_16x16x32_bf16 v[40:43], v[140:143], v[210:213], v[40:43]
	v_mfma_f32_16x16x32_bf16 v[28:31], v[132:135], v[218:221], v[28:31]
	v_mfma_f32_16x16x32_bf16 v[24:27], v[140:143], v[218:221], v[24:27]
	v_mfma_f32_16x16x32_bf16 v[12:15], v[132:135], v[226:229], v[12:15]
	v_mfma_f32_16x16x32_bf16 v[8:11], v[140:143], v[226:229], v[8:11]
	v_mfma_f32_16x16x32_bf16 v[52:55], v[166:169], v[198:201], v[52:55]
	v_mfma_f32_16x16x32_bf16 v[48:51], v[190:193], v[198:201], v[48:51]
	v_mfma_f32_16x16x32_bf16 v[36:39], v[166:169], v[206:209], v[36:39]
	v_mfma_f32_16x16x32_bf16 v[32:35], v[190:193], v[206:209], v[32:35]
	v_mfma_f32_16x16x32_bf16 v[20:23], v[166:169], v[214:217], v[20:23]
	v_mfma_f32_16x16x32_bf16 v[16:19], v[190:193], v[214:217], v[16:19]
	v_mfma_f32_16x16x32_bf16 v[4:7], v[166:169], v[222:225], v[4:7]
	v_mfma_f32_16x16x32_bf16 v[0:3], v[190:193], v[222:225], v[0:3]
	v_mfma_f32_16x16x32_bf16 v[52:55], v[170:173], v[202:205], v[52:55]
	v_mfma_f32_16x16x32_bf16 v[48:51], v[194:197], v[202:205], v[48:51]
	v_mfma_f32_16x16x32_bf16 v[36:39], v[170:173], v[210:213], v[36:39]
	v_mfma_f32_16x16x32_bf16 v[32:35], v[194:197], v[210:213], v[32:35]
	v_mfma_f32_16x16x32_bf16 v[20:23], v[170:173], v[218:221], v[20:23]
	v_mfma_f32_16x16x32_bf16 v[16:19], v[194:197], v[218:221], v[16:19]
	v_mfma_f32_16x16x32_bf16 v[4:7], v[170:173], v[226:229], v[4:7]
	v_mfma_f32_16x16x32_bf16 v[0:3], v[194:197], v[226:229], v[0:3]
	s_setprio 0
	s_barrier
	s_add_i32 s35, s35, 2
	s_add_u32 s80, s80, 0x100
	s_addc_u32 s81, s81, 0
	s_add_u32 vcc_hi, vcc_hi, 0x100
	s_addc_u32 s34, s34, 0
	s_cmp_gt_u32 s35, 13
	s_cbranch_scc0 .LBB0_96
	s_and_b64 vcc, exec, s[28:29]
	s_cbranch_vccz .LBB0_99
	s_barrier

;     __host__ __device__ bool next(int i, Unit& u) const { const long L = (long)i * G + c; if (L >= nwg) return false; return unit_of((int)L, u); }
;     __host__ __device__ bool next(int i, Unit& u) const { const int L = i == 0 ? l0 : (i == 1 ? l1 : (i == 2 ? l2 : -1)); if (L < 0 || L >= s.nwg) return false; return s.unit_of(L, u); }
;     __host__ __device__ bool next(int i, Unit& u) const { const bool ok = s.next(i >> 1, u); u.kh = i & 1; return ok; }
; #define PG8_STAGE(bufoff, gbase, voff) do { _Pragma("unroll") for (int _i = 0; _i < 2; ++_i) \
;         __builtin_amdgcn_global_load_lds((const unsigned*)((const char*)(gbase) + (voff)[_i]), (PG8_LAS unsigned*)(lds + (bufoff) + ldsw + _i * 8192), 16, 0, 0); } while (0)
; #define PG8_WAIT_V(n) asm volatile("s_waitcnt vmcnt(" #n ")" ::: "memory")
; template <class Epi, class Sched, bool ALIGN_EPI = false, bool SP2 = false>
; __device__ __forceinline__ void gemm_phase(PG8_LAS unsigned char* lds, const Gemm g, const Sched& S, const Epi& E) {
;     ...
;         const bool has_next = S.next(ui + 1, nxt);
;         const char* nA = has_next ? (const char*)g.A + (size_t)nxt.pm * tstep + nxt.kh * khb : cA; const char* nB = has_next ? (const char*)g.Bt + (size_t)nxt.pn * tstep + nxt.kh * khb : cB;
;         for (int t = 0; t < nt; t += 2) {
;             const bool last = (t == nt - 2);
;             const char* a1 = cA + (size_t)(t + 1) * kstep;
;             const char* a2 = last ? nA : cA + (size_t)(t + 2) * kstep; const char* b2 = last ? nB : cB + (size_t)(t + 2) * kstep;
;             const char* a3 = a2 + kstep; const char* b3 = b2 + kstep;
;             if (last && has_next) S.a_ready(nxt);
;             if constexpr (SP2) {
;             PG8_LDB(B0, 0, 0); PG8_LDB(B1, 0, 1); PG8_SCHED; PG8_LDA(At, 0, 0); PG8_STAGE(PG8_SA(1, 1), a1 + hstep, voffA);
;             PG8_WAIT_V(8); PG8_WAIT_L(0); PG8_BAR; PG8_MMA(0, 0, At, B0); PG8_MMA(0, 1, At, B1); PG8_BAR; PG8_SCHED;
;             PG8_LDA(At, 0, 1); PG8_STAGE(PG8_SB(0, 0), b2, voffB); PG8_STAGE(PG8_SB(0, 1), b2 + hstep, voffB); PG8_STAGE(PG8_SA(0, 0), a2, voffA);
;     ...
;         for (int a = 0; a < 2; ++a)
; #pragma unroll
;             for (int b = 0; b < 2; ++b)
; #pragma unroll
;                 for (int m = 0; m < 4; ++m)
; #pragma unroll
;                     for (int n = 0; n < 2; ++n) acc[a][b][m][n] = (f32x4){0.f, 0.f, 0.f, 0.f};
.LBB0_149:
	s_ashr_i32 s17, s16, 31
	s_lshl_b64 s[18:19], s[16:17], 19
	s_add_u32 s18, s29, s18
	s_addc_u32 s19, s30, s19
	s_and_b64 s[20:21], s[2:3], exec
	s_cselect_b32 s17, s19, s23
	s_cselect_b32 s45, s18, s22
	s_ashr_i32 s15, s14, 31
	s_lshl_b64 s[20:21], s[14:15], 19
	s_add_u32 s20, s50, s20
	s_addc_u32 s21, s51, s21
	s_and_b64 s[26:27], s[2:3], exec
	s_cselect_b32 s15, s21, s25
	s_cselect_b32 s46, s20, s24
	s_add_u32 s22, s22, 0x40080
	s_addc_u32 s23, s23, 0
	s_add_u32 s47, s24, 0x100
	s_addc_u32 s48, s25, 0
	s_mov_b32 s49, -2
	s_add_u32 s24, s22, 0xfffc0080
	s_addc_u32 s25, s23, -1
	s_waitcnt lgkmcnt(0)
	s_add_i32 s54, 0, 0x10000
	v_add_u32_e32 v147, s54, v152
	ds_read_b128 v[156:159], v147
	ds_read_b128 v[160:163], v147 offset:1024
	ds_read_b128 v[164:167], v147 offset:2048
	ds_read_b128 v[168:171], v147 offset:3072
	ds_read_b128 v[172:175], v154
	ds_read_b128 v[176:179], v154 offset:1024
	ds_read_b128 v[182:185], v154 offset:2048
	ds_read_b128 v[190:193], v154 offset:3072
	s_cmp_eq_u32 s49, 12
	s_cselect_b32 s27, s17, s25
	s_cselect_b32 s26, s45, s24
	s_cselect_b32 s25, s15, s48
	s_cselect_b32 s24, s46, s47
	s_add_i32 m0, s13, 0xc000
	ds_read_b128 v[194:197], v155
	ds_read_b128 v[198:201], v155 offset:1024
	ds_read_b128 v[202:205], v155 offset:2048
	ds_read_b128 v[206:209], v155 offset:3072
	ds_read_b128 v[210:213], v155 offset:4096
	ds_read_b128 v[214:217], v155 offset:5120
	ds_read_b128 v[218:221], v155 offset:6144
	ds_read_b128 v[222:225], v155 offset:7168
	global_load_lds_dwordx4 v138, s[22:23]
	s_add_i32 m0, s13, 0xe000
	s_nop 0
	global_load_lds_dwordx4 v140, s[22:23]
	s_waitcnt vmcnt(8)
	s_waitcnt lgkmcnt(0)
	s_barrier
	s_setprio 1
	v_mfma_f32_16x16x32_bf16 v[124:127], v[156:159], v[194:197], 0
	v_mfma_f32_16x16x32_bf16 v[120:123], v[164:167], v[194:197], 0
	v_mfma_f32_16x16x32_bf16 v[116:119], v[156:159], v[202:205], 0
	v_mfma_f32_16x16x32_bf16 v[112:115], v[164:167], v[202:205], 0
	v_mfma_f32_16x16x32_bf16 v[100:103], v[156:159], v[210:213], 0
	v_mfma_f32_16x16x32_bf16 v[96:99], v[164:167], v[210:213], 0
	v_mfma_f32_16x16x32_bf16 v[84:87], v[156:159], v[218:221], 0
	v_mfma_f32_16x16x32_bf16 v[80:83], v[164:167], v[218:221], 0
	v_mfma_f32_16x16x32_bf16 v[124:127], v[160:163], v[198:201], v[124:127]
	v_mfma_f32_16x16x32_bf16 v[120:123], v[168:171], v[198:201], v[120:123]
	v_mfma_f32_16x16x32_bf16 v[116:119], v[160:163], v[206:209], v[116:119]
	v_mfma_f32_16x16x32_bf16 v[112:115], v[168:171], v[206:209], v[112:115]
	v_mfma_f32_16x16x32_bf16 v[100:103], v[160:163], v[214:217], v[100:103]
	v_mfma_f32_16x16x32_bf16 v[96:99], v[168:171], v[214:217], v[96:99]
	v_mfma_f32_16x16x32_bf16 v[84:87], v[160:163], v[222:225], v[84:87]
	v_mfma_f32_16x16x32_bf16 v[80:83], v[168:171], v[222:225], v[80:83]
	v_mfma_f32_16x16x32_bf16 v[108:111], v[172:175], v[194:197], 0
	v_mfma_f32_16x16x32_bf16 v[104:107], v[182:185], v[194:197], 0
	v_mfma_f32_16x16x32_bf16 v[92:95], v[172:175], v[202:205], 0
	v_mfma_f32_16x16x32_bf16 v[88:91], v[182:185], v[202:205], 0
	v_mfma_f32_16x16x32_bf16 v[76:79], v[172:175], v[210:213], 0
	v_mfma_f32_16x16x32_bf16 v[72:75], v[182:185], v[210:213], 0
	v_mfma_f32_16x16x32_bf16 v[68:71], v[172:175], v[218:221], 0
	v_mfma_f32_16x16x32_bf16 v[64:67], v[182:185], v[218:221], 0
	v_mfma_f32_16x16x32_bf16 v[108:111], v[176:179], v[198:201], v[108:111]
	v_mfma_f32_16x16x32_bf16 v[104:107], v[190:193], v[198:201], v[104:107]
	v_mfma_f32_16x16x32_bf16 v[92:95], v[176:179], v[206:209], v[92:95]
	v_mfma_f32_16x16x32_bf16 v[88:91], v[190:193], v[206:209], v[88:91]
	v_mfma_f32_16x16x32_bf16 v[76:79], v[176:179], v[214:217], v[76:79]
	v_mfma_f32_16x16x32_bf16 v[72:75], v[190:193], v[214:217], v[72:75]
	v_mfma_f32_16x16x32_bf16 v[68:71], v[176:179], v[222:225], v[68:71]
	v_mfma_f32_16x16x32_bf16 v[64:67], v[190:193], v[222:225], v[64:67]
	s_setprio 0
	s_barrier
	s_add_i32 s54, s54, s31
	v_lshl_add_u64 v[186:187], s[24:25], 0, v[130:131]
	s_mov_b32 m0, s54
	ds_read_b128 v[194:197], v155 offset:16384
	ds_read_b128 v[198:201], v155 offset:17408
	ds_read_b128 v[202:205], v155 offset:18432
	ds_read_b128 v[206:209], v155 offset:19456
	ds_read_b128 v[210:213], v155 offset:20480
	ds_read_b128 v[214:217], v155 offset:21504
	ds_read_b128 v[218:221], v155 offset:22528
	ds_read_b128 v[222:225], v155 offset:23552
	global_load_lds_dwordx4 v[186:187], off
	s_add_i32 m0, s54, 0x2000
	s_add_u32 s54, s24, 0x40000
	v_lshl_add_u64 v[226:227], s[24:25], 0, v[134:135]
	s_addc_u32 s55, s25, 0
	s_add_i32 s76, s43, s31
	global_load_lds_dwordx4 v[226:227], off
	s_mov_b32 m0, s76
	v_lshl_add_u64 v[230:231], s[26:27], 0, v[132:133]
	global_load_lds_dwordx4 v130, s[54:55]
	s_add_i32 m0, s76, 0x2000
	s_nop 0
	global_load_lds_dwordx4 v134, s[54:55]
	v_lshl_add_u64 v[228:229], s[26:27], 0, v[128:129]
	s_mov_b32 m0, s13
	s_nop 0
	global_load_lds_dwordx4 v[228:229], off
	s_mov_b32 m0, s34
	s_nop 0
	global_load_lds_dwordx4 v[230:231], off
	s_waitcnt vmcnt(8)
	s_waitcnt lgkmcnt(0)
	s_barrier
; #define PG8_STAGE(bufoff, gbase, voff) do { _Pragma("unroll") for (int _i = 0; _i < 2; ++_i) \
;         __builtin_amdgcn_global_load_lds((const unsigned*)((const char*)(gbase) + (voff)[_i]), (PG8_LAS unsigned*)(lds + (bufoff) + ldsw + _i * 8192), 16, 0, 0); } while (0)
; #define PG8_LDA(dst, b, h) do { _Pragma("unroll") for (int m = 0; m < 4; ++m) _Pragma("unroll") for (int k = 0; k < 2; ++k) dst[m][k] = *(const PG8_LAS bf16x8*)(lds + PG8_SA(b, h) + aoff + m * 2048 + k * 1024); } while (0)
; #define PG8_LDB(dst, b, h) do { _Pragma("unroll") for (int n = 0; n < 2; ++n) _Pragma("unroll") for (int k = 0; k < 2; ++k) dst[n][k] = *(const PG8_LAS bf16x8*)(lds + PG8_SB(b, h) + boff + n * 2048 + k * 1024); } while (0)
; #define PG8_MMA(ai, bj, At, Bt) do { __builtin_amdgcn_s_setprio(1); _Pragma("unroll") for (int m = 0; m < 4; ++m) _Pragma("unroll") for (int n = 0; n < 2; ++n) _Pragma("unroll") for (int k = 0; k < 2; ++k) \
;         acc[ai][bj][m][n] = __builtin_amdgcn_mfma_f32_16x16x32_bf16(Bt[n][k], At[m][k], acc[ai][bj][m][n], 0, 0, 0); __builtin_amdgcn_s_setprio(0); } while (0)
; #define PG8_WAIT_V(n) asm volatile("s_waitcnt vmcnt(" #n ")" ::: "memory")
; #define PG8_WAIT_L(n) asm volatile("s_waitcnt lgkmcnt(" #n ")" ::: "memory")
; #define PG8_BAR __builtin_amdgcn_s_barrier()
; #define PG8_SCHED __builtin_amdgcn_sched_barrier(0)
; template <class Epi, class Sched, bool ALIGN_EPI = false, bool SP2 = false>
; __device__ __forceinline__ void gemm_phase(PG8_LAS unsigned char* lds, const Gemm g, const Sched& S, const Epi& E) {
;     ...
;             PG8_LDB(B0, 0, 0); PG8_LDB(B1, 0, 1); PG8_SCHED; PG8_LDA(At, 0, 0); PG8_STAGE(PG8_SA(1, 1), a1 + hstep, voffA);
;             PG8_WAIT_V(8); PG8_WAIT_L(0); PG8_BAR; PG8_MMA(0, 0, At, B0); PG8_MMA(0, 1, At, B1); PG8_BAR; PG8_SCHED;
;             PG8_LDA(At, 0, 1); PG8_STAGE(PG8_SB(0, 0), b2, voffB); PG8_STAGE(PG8_SB(0, 1), b2 + hstep, voffB); PG8_STAGE(PG8_SA(0, 0), a2, voffA);
;             PG8_WAIT_V(8); PG8_WAIT_L(0); PG8_BAR; PG8_MMA(1, 0, At, B0); PG8_MMA(1, 1, At, B1); PG8_BAR; PG8_SCHED;
	s_setprio 1
	v_mfma_f32_16x16x32_bf16 v[60:63], v[156:159], v[194:197], 0
	v_mfma_f32_16x16x32_bf16 v[56:59], v[164:167], v[194:197], 0
	v_mfma_f32_16x16x32_bf16 v[52:55], v[156:159], v[202:205], 0
	v_mfma_f32_16x16x32_bf16 v[48:51], v[164:167], v[202:205], 0
	v_mfma_f32_16x16x32_bf16 v[36:39], v[156:159], v[210:213], 0
	v_mfma_f32_16x16x32_bf16 v[32:35], v[164:167], v[210:213], 0
	v_mfma_f32_16x16x32_bf16 v[20:23], v[156:159], v[218:221], 0
	v_mfma_f32_16x16x32_bf16 v[16:19], v[164:167], v[218:221], 0
	v_mfma_f32_16x16x32_bf16 v[60:63], v[160:163], v[198:201], v[60:63]
	v_mfma_f32_16x16x32_bf16 v[56:59], v[168:171], v[198:201], v[56:59]
	v_mfma_f32_16x16x32_bf16 v[52:55], v[160:163], v[206:209], v[52:55]
	v_mfma_f32_16x16x32_bf16 v[48:51], v[168:171], v[206:209], v[48:51]
	v_mfma_f32_16x16x32_bf16 v[36:39], v[160:163], v[214:217], v[36:39]
	v_mfma_f32_16x16x32_bf16 v[32:35], v[168:171], v[214:217], v[32:35]
	v_mfma_f32_16x16x32_bf16 v[20:23], v[160:163], v[222:225], v[20:23]
	v_mfma_f32_16x16x32_bf16 v[16:19], v[168:171], v[222:225], v[16:19]
	v_mfma_f32_16x16x32_bf16 v[44:47], v[172:175], v[194:197], 0
	v_mfma_f32_16x16x32_bf16 v[40:43], v[182:185], v[194:197], 0
	v_mfma_f32_16x16x32_bf16 v[28:31], v[172:175], v[202:205], 0
	v_mfma_f32_16x16x32_bf16 v[24:27], v[182:185], v[202:205], 0
	v_mfma_f32_16x16x32_bf16 v[12:15], v[172:175], v[210:213], 0
	v_mfma_f32_16x16x32_bf16 v[8:11], v[182:185], v[210:213], 0
	v_mfma_f32_16x16x32_bf16 v[4:7], v[172:175], v[218:221], 0
	v_mfma_f32_16x16x32_bf16 v[0:3], v[182:185], v[218:221], 0
	v_mfma_f32_16x16x32_bf16 v[44:47], v[176:179], v[198:201], v[44:47]
	v_mfma_f32_16x16x32_bf16 v[40:43], v[190:193], v[198:201], v[40:43]
	v_mfma_f32_16x16x32_bf16 v[28:31], v[176:179], v[206:209], v[28:31]
	v_mfma_f32_16x16x32_bf16 v[24:27], v[190:193], v[206:209], v[24:27]
	v_mfma_f32_16x16x32_bf16 v[12:15], v[176:179], v[214:217], v[12:15]
	v_mfma_f32_16x16x32_bf16 v[8:11], v[190:193], v[214:217], v[8:11]
	v_mfma_f32_16x16x32_bf16 v[4:7], v[176:179], v[222:225], v[4:7]
	v_mfma_f32_16x16x32_bf16 v[0:3], v[190:193], v[222:225], v[0:3]
	s_setprio 0
	s_barrier
	s_branch .Lmy_peel_150_mid
.LBB0_150:
	s_add_u32 s24, s22, 0xfffc0080
	s_addc_u32 s25, s23, -1
	s_waitcnt lgkmcnt(0)
	s_add_i32 s54, 0, 0x10000
	v_add_u32_e32 v147, s54, v152
	ds_read_b128 v[156:159], v147
	ds_read_b128 v[160:163], v147 offset:1024
	ds_read_b128 v[164:167], v147 offset:2048
	ds_read_b128 v[168:171], v147 offset:3072
	ds_read_b128 v[172:175], v154
	ds_read_b128 v[176:179], v154 offset:1024
	ds_read_b128 v[182:185], v154 offset:2048
	ds_read_b128 v[190:193], v154 offset:3072
	s_cmp_eq_u32 s49, 12
	s_cselect_b32 s27, s17, s25
	s_cselect_b32 s26, s45, s24
	s_cselect_b32 s25, s15, s48
	s_cselect_b32 s24, s46, s47
	s_add_i32 m0, s13, 0xc000
	ds_read_b128 v[194:197], v155
	ds_read_b128 v[198:201], v155 offset:1024
	ds_read_b128 v[202:205], v155 offset:2048
	ds_read_b128 v[206:209], v155 offset:3072
	ds_read_b128 v[210:213], v155 offset:4096
	ds_read_b128 v[214:217], v155 offset:5120
	ds_read_b128 v[218:221], v155 offset:6144
	ds_read_b128 v[222:225], v155 offset:7168
	global_load_lds_dwordx4 v138, s[22:23]
	s_add_i32 m0, s13, 0xe000
	s_nop 0
	global_load_lds_dwordx4 v140, s[22:23]
	s_waitcnt vmcnt(8)
	s_waitcnt lgkmcnt(0)
	s_barrier
	s_setprio 1
	v_mfma_f32_16x16x32_bf16 v[124:127], v[156:159], v[194:197], v[124:127]
	v_mfma_f32_16x16x32_bf16 v[120:123], v[164:167], v[194:197], v[120:123]
	v_mfma_f32_16x16x32_bf16 v[116:119], v[156:159], v[202:205], v[116:119]
	v_mfma_f32_16x16x32_bf16 v[112:115], v[164:167], v[202:205], v[112:115]
	v_mfma_f32_16x16x32_bf16 v[100:103], v[156:159], v[210:213], v[100:103]
	v_mfma_f32_16x16x32_bf16 v[96:99], v[164:167], v[210:213], v[96:99]
	v_mfma_f32_16x16x32_bf16 v[84:87], v[156:159], v[218:221], v[84:87]
	v_mfma_f32_16x16x32_bf16 v[80:83], v[164:167], v[218:221], v[80:83]
	v_mfma_f32_16x16x32_bf16 v[124:127], v[160:163], v[198:201], v[124:127]
	v_mfma_f32_16x16x32_bf16 v[120:123], v[168:171], v[198:201], v[120:123]
	v_mfma_f32_16x16x32_bf16 v[116:119], v[160:163], v[206:209], v[116:119]
	v_mfma_f32_16x16x32_bf16 v[112:115], v[168:171], v[206:209], v[112:115]
	v_mfma_f32_16x16x32_bf16 v[100:103], v[160:163], v[214:217], v[100:103]
	v_mfma_f32_16x16x32_bf16 v[96:99], v[168:171], v[214:217], v[96:99]
	v_mfma_f32_16x16x32_bf16 v[84:87], v[160:163], v[222:225], v[84:87]
	v_mfma_f32_16x16x32_bf16 v[80:83], v[168:171], v[222:225], v[80:83]
	v_mfma_f32_16x16x32_bf16 v[108:111], v[172:175], v[194:197], v[108:111]
	v_mfma_f32_16x16x32_bf16 v[104:107], v[182:185], v[194:197], v[104:107]
	v_mfma_f32_16x16x32_bf16 v[92:95], v[172:175], v[202:205], v[92:95]
	v_mfma_f32_16x16x32_bf16 v[88:91], v[182:185], v[202:205], v[88:91]
	v_mfma_f32_16x16x32_bf16 v[76:79], v[172:175], v[210:213], v[76:79]
	v_mfma_f32_16x16x32_bf16 v[72:75], v[182:185], v[210:213], v[72:75]
	v_mfma_f32_16x16x32_bf16 v[68:71], v[172:175], v[218:221], v[68:71]
	v_mfma_f32_16x16x32_bf16 v[64:67], v[182:185], v[218:221], v[64:67]
	v_mfma_f32_16x16x32_bf16 v[108:111], v[176:179], v[198:201], v[108:111]
	v_mfma_f32_16x16x32_bf16 v[104:107], v[190:193], v[198:201], v[104:107]
	v_mfma_f32_16x16x32_bf16 v[92:95], v[176:179], v[206:209], v[92:95]
	v_mfma_f32_16x16x32_bf16 v[88:91], v[190:193], v[206:209], v[88:91]
	v_mfma_f32_16x16x32_bf16 v[76:79], v[176:179], v[214:217], v[76:79]
	v_mfma_f32_16x16x32_bf16 v[72:75], v[190:193], v[214:217], v[72:75]
	v_mfma_f32_16x16x32_bf16 v[68:71], v[176:179], v[222:225], v[68:71]
	v_mfma_f32_16x16x32_bf16 v[64:67], v[190:193], v[222:225], v[64:67]
	s_setprio 0
	s_barrier
; #define PG8_STAGE(bufoff, gbase, voff) do { _Pragma("unroll") for (int _i = 0; _i < 2; ++_i) \
;         __builtin_amdgcn_global_load_lds((const unsigned*)((const char*)(gbase) + (voff)[_i]), (PG8_LAS unsigned*)(lds + (bufoff) + ldsw + _i * 8192), 16, 0, 0); } while (0)
; #define PG8_LDA(dst, b, h) do { _Pragma("unroll") for (int m = 0; m < 4; ++m) _Pragma("unroll") for (int k = 0; k < 2; ++k) dst[m][k] = *(const PG8_LAS bf16x8*)(lds + PG8_SA(b, h) + aoff + m * 2048 + k * 1024); } while (0)
; #define PG8_MMA(ai, bj, At, Bt) do { __builtin_amdgcn_s_setprio(1); _Pragma("unroll") for (int m = 0; m < 4; ++m) _Pragma("unroll") for (int n = 0; n < 2; ++n) _Pragma("unroll") for (int k = 0; k < 2; ++k) \
;         acc[ai][bj][m][n] = __builtin_amdgcn_mfma_f32_16x16x32_bf16(Bt[n][k], At[m][k], acc[ai][bj][m][n], 0, 0, 0); __builtin_amdgcn_s_setprio(0); } while (0)
; #define PG8_WAIT_V(n) asm volatile("s_waitcnt vmcnt(" #n ")" ::: "memory")
; #define PG8_WAIT_L(n) asm volatile("s_waitcnt lgkmcnt(" #n ")" ::: "memory")
; #define PG8_BAR __builtin_amdgcn_s_barrier()
; #define PG8_SCHED __builtin_amdgcn_sched_barrier(0)
; template <class Epi, class Sched, bool ALIGN_EPI = false, bool SP2 = false>
; __device__ __forceinline__ void gemm_phase(PG8_LAS unsigned char* lds, const Gemm g, const Sched& S, const Epi& E) {
;     ...
;             PG8_LDA(At, 0, 1); PG8_STAGE(PG8_SB(0, 0), b2, voffB); PG8_STAGE(PG8_SB(0, 1), b2 + hstep, voffB); PG8_STAGE(PG8_SA(0, 0), a2, voffA);
;             PG8_WAIT_V(8); PG8_WAIT_L(0); PG8_BAR; PG8_MMA(1, 0, At, B0); PG8_MMA(1, 1, At, B1); PG8_BAR; PG8_SCHED;
	s_add_i32 s54, s54, s31
	v_lshl_add_u64 v[186:187], s[24:25], 0, v[130:131]
	s_mov_b32 m0, s54
	ds_read_b128 v[194:197], v155 offset:16384
	ds_read_b128 v[198:201], v155 offset:17408
	ds_read_b128 v[202:205], v155 offset:18432
	ds_read_b128 v[206:209], v155 offset:19456
	ds_read_b128 v[210:213], v155 offset:20480
	ds_read_b128 v[214:217], v155 offset:21504
	ds_read_b128 v[218:221], v155 offset:22528
	ds_read_b128 v[222:225], v155 offset:23552
	global_load_lds_dwordx4 v[186:187], off
	s_add_i32 m0, s54, 0x2000
	s_add_u32 s54, s24, 0x40000
	v_lshl_add_u64 v[226:227], s[24:25], 0, v[134:135]
	s_addc_u32 s55, s25, 0
	s_add_i32 s76, s43, s31
	global_load_lds_dwordx4 v[226:227], off
	s_mov_b32 m0, s76
	v_lshl_add_u64 v[230:231], s[26:27], 0, v[132:133]
	global_load_lds_dwordx4 v130, s[54:55]
	s_add_i32 m0, s76, 0x2000
	s_nop 0
	global_load_lds_dwordx4 v134, s[54:55]
	v_lshl_add_u64 v[228:229], s[26:27], 0, v[128:129]
	s_mov_b32 m0, s13
	s_nop 0
	global_load_lds_dwordx4 v[228:229], off
	s_mov_b32 m0, s34
	s_nop 0
	global_load_lds_dwordx4 v[230:231], off
	s_waitcnt vmcnt(8)
	s_waitcnt lgkmcnt(0)
	s_barrier
	s_setprio 1
	v_mfma_f32_16x16x32_bf16 v[60:63], v[156:159], v[194:197], v[60:63]
	v_mfma_f32_16x16x32_bf16 v[56:59], v[164:167], v[194:197], v[56:59]
	v_mfma_f32_16x16x32_bf16 v[52:55], v[156:159], v[202:205], v[52:55]
	v_mfma_f32_16x16x32_bf16 v[48:51], v[164:167], v[202:205], v[48:51]
	v_mfma_f32_16x16x32_bf16 v[36:39], v[156:159], v[210:213], v[36:39]
	v_mfma_f32_16x16x32_bf16 v[32:35], v[164:167], v[210:213], v[32:35]
	v_mfma_f32_16x16x32_bf16 v[20:23], v[156:159], v[218:221], v[20:23]
	v_mfma_f32_16x16x32_bf16 v[16:19], v[164:167], v[218:221], v[16:19]
	v_mfma_f32_16x16x32_bf16 v[60:63], v[160:163], v[198:201], v[60:63]
	v_mfma_f32_16x16x32_bf16 v[56:59], v[168:171], v[198:201], v[56:59]
	v_mfma_f32_16x16x32_bf16 v[52:55], v[160:163], v[206:209], v[52:55]
	v_mfma_f32_16x16x32_bf16 v[48:51], v[168:171], v[206:209], v[48:51]
	v_mfma_f32_16x16x32_bf16 v[36:39], v[160:163], v[214:217], v[36:39]
	v_mfma_f32_16x16x32_bf16 v[32:35], v[168:171], v[214:217], v[32:35]
	v_mfma_f32_16x16x32_bf16 v[20:23], v[160:163], v[222:225], v[20:23]
	v_mfma_f32_16x16x32_bf16 v[16:19], v[168:171], v[222:225], v[16:19]
	v_mfma_f32_16x16x32_bf16 v[44:47], v[172:175], v[194:197], v[44:47]
	v_mfma_f32_16x16x32_bf16 v[40:43], v[182:185], v[194:197], v[40:43]
	v_mfma_f32_16x16x32_bf16 v[28:31], v[172:175], v[202:205], v[28:31]
	v_mfma_f32_16x16x32_bf16 v[24:27], v[182:185], v[202:205], v[24:27]
	v_mfma_f32_16x16x32_bf16 v[12:15], v[172:175], v[210:213], v[12:15]
	v_mfma_f32_16x16x32_bf16 v[8:11], v[182:185], v[210:213], v[8:11]
	v_mfma_f32_16x16x32_bf16 v[4:7], v[172:175], v[218:221], v[4:7]
	v_mfma_f32_16x16x32_bf16 v[0:3], v[182:185], v[218:221], v[0:3]
	v_mfma_f32_16x16x32_bf16 v[44:47], v[176:179], v[198:201], v[44:47]
	v_mfma_f32_16x16x32_bf16 v[40:43], v[190:193], v[198:201], v[40:43]
	v_mfma_f32_16x16x32_bf16 v[28:31], v[176:179], v[206:209], v[28:31]
	v_mfma_f32_16x16x32_bf16 v[24:27], v[190:193], v[206:209], v[24:27]
	v_mfma_f32_16x16x32_bf16 v[12:15], v[176:179], v[214:217], v[12:15]
	v_mfma_f32_16x16x32_bf16 v[8:11], v[190:193], v[214:217], v[8:11]
	v_mfma_f32_16x16x32_bf16 v[4:7], v[176:179], v[222:225], v[4:7]
	v_mfma_f32_16x16x32_bf16 v[0:3], v[190:193], v[222:225], v[0:3]
	s_setprio 0
	s_barrier
; #define PG8_STAGE(bufoff, gbase, voff) do { _Pragma("unroll") for (int _i = 0; _i < 2; ++_i) \
;         __builtin_amdgcn_global_load_lds((const unsigned*)((const char*)(gbase) + (voff)[_i]), (PG8_LAS unsigned*)(lds + (bufoff) + ldsw + _i * 8192), 16, 0, 0); } while (0)
; #define PG8_LDA(dst, b, h) do { _Pragma("unroll") for (int m = 0; m < 4; ++m) _Pragma("unroll") for (int k = 0; k < 2; ++k) dst[m][k] = *(const PG8_LAS bf16x8*)(lds + PG8_SA(b, h) + aoff + m * 2048 + k * 1024); } while (0)
; #define PG8_LDB(dst, b, h) do { _Pragma("unroll") for (int n = 0; n < 2; ++n) _Pragma("unroll") for (int k = 0; k < 2; ++k) dst[n][k] = *(const PG8_LAS bf16x8*)(lds + PG8_SB(b, h) + boff + n * 2048 + k * 1024); } while (0)
; #define PG8_MMA(ai, bj, At, Bt) do { __builtin_amdgcn_s_setprio(1); _Pragma("unroll") for (int m = 0; m < 4; ++m) _Pragma("unroll") for (int n = 0; n < 2; ++n) _Pragma("unroll") for (int k = 0; k < 2; ++k) \
;         acc[ai][bj][m][n] = __builtin_amdgcn_mfma_f32_16x16x32_bf16(Bt[n][k], At[m][k], acc[ai][bj][m][n], 0, 0, 0); __builtin_amdgcn_s_setprio(0); } while (0)
; #define PG8_WAIT_V(n) asm volatile("s_waitcnt vmcnt(" #n ")" ::: "memory")
; #define PG8_WAIT_L(n) asm volatile("s_waitcnt lgkmcnt(" #n ")" ::: "memory")
; #define PG8_BAR __builtin_amdgcn_s_barrier()
; #define PG8_SCHED __builtin_amdgcn_sched_barrier(0)
; template <class Epi, class Sched, bool ALIGN_EPI = false, bool SP2 = false>
; __device__ __forceinline__ void gemm_phase(PG8_LAS unsigned char* lds, const Gemm g, const Sched& S, const Epi& E) {
;     ...
;         for (int t = 0; t < nt; t += 2) {
;     ...
;             PG8_LDB(B0, 1, 0); PG8_LDB(B1, 1, 1); PG8_SCHED; PG8_LDA(At, 1, 0); PG8_STAGE(PG8_SA(0, 1), a2 + hstep, voffA);
;             PG8_WAIT_V(8); PG8_WAIT_L(0); PG8_BAR; PG8_MMA(0, 0, At, B0); PG8_MMA(0, 1, At, B1); PG8_BAR; PG8_SCHED;
;             PG8_LDA(At, 1, 1); PG8_STAGE(PG8_SB(1, 0), b3, voffB); PG8_STAGE(PG8_SB(1, 1), b3 + hstep, voffB); PG8_STAGE(PG8_SA(1, 0), a3, voffA);
;             PG8_WAIT_V(8); PG8_WAIT_L(0); PG8_BAR; PG8_MMA(1, 0, At, B0); PG8_MMA(1, 1, At, B1); PG8_BAR; PG8_SCHED;
.Lmy_peel_150_mid:
	s_add_i32 s54, 0, 0x18000
	v_add_u32_e32 v147, s54, v152
	s_add_i32 s55, 0, 0x1c000
	ds_read_b128 v[156:159], v147
	ds_read_b128 v[160:163], v147 offset:1024
	ds_read_b128 v[164:167], v147 offset:2048
	ds_read_b128 v[168:171], v147 offset:3072
	v_add_u32_e32 v147, s55, v152
	ds_read_b128 v[172:175], v147
	ds_read_b128 v[176:179], v147 offset:1024
	ds_read_b128 v[182:185], v147 offset:2048
	ds_read_b128 v[190:193], v147 offset:3072
	s_add_u32 s26, s26, 0x40000
	s_addc_u32 s27, s27, 0
	s_mov_b32 m0, s35
	ds_read_b128 v[194:197], v155 offset:32768
	ds_read_b128 v[198:201], v155 offset:33792
	ds_read_b128 v[202:205], v155 offset:34816
	ds_read_b128 v[206:209], v155 offset:35840
	ds_read_b128 v[210:213], v155 offset:36864
	ds_read_b128 v[214:217], v155 offset:37888
	ds_read_b128 v[218:221], v155 offset:38912
	ds_read_b128 v[222:225], v155 offset:39936
	global_load_lds_dwordx4 v128, s[26:27]
	s_mov_b32 m0, s36
	s_nop 0
	global_load_lds_dwordx4 v132, s[26:27]
	s_waitcnt vmcnt(8)
	s_waitcnt lgkmcnt(0)
	s_barrier
	s_setprio 1
	v_mfma_f32_16x16x32_bf16 v[124:127], v[156:159], v[194:197], v[124:127]
	v_mfma_f32_16x16x32_bf16 v[120:123], v[164:167], v[194:197], v[120:123]
	v_mfma_f32_16x16x32_bf16 v[116:119], v[156:159], v[202:205], v[116:119]
	v_mfma_f32_16x16x32_bf16 v[112:115], v[164:167], v[202:205], v[112:115]
	v_mfma_f32_16x16x32_bf16 v[100:103], v[156:159], v[210:213], v[100:103]
	v_mfma_f32_16x16x32_bf16 v[96:99], v[164:167], v[210:213], v[96:99]
	v_mfma_f32_16x16x32_bf16 v[84:87], v[156:159], v[218:221], v[84:87]
	v_mfma_f32_16x16x32_bf16 v[80:83], v[164:167], v[218:221], v[80:83]
	v_mfma_f32_16x16x32_bf16 v[124:127], v[160:163], v[198:201], v[124:127]
	v_mfma_f32_16x16x32_bf16 v[120:123], v[168:171], v[198:201], v[120:123]
	v_mfma_f32_16x16x32_bf16 v[116:119], v[160:163], v[206:209], v[116:119]
	v_mfma_f32_16x16x32_bf16 v[112:115], v[168:171], v[206:209], v[112:115]
	v_mfma_f32_16x16x32_bf16 v[100:103], v[160:163], v[214:217], v[100:103]
	v_mfma_f32_16x16x32_bf16 v[96:99], v[168:171], v[214:217], v[96:99]
	v_mfma_f32_16x16x32_bf16 v[84:87], v[160:163], v[222:225], v[84:87]
	v_mfma_f32_16x16x32_bf16 v[80:83], v[168:171], v[222:225], v[80:83]
	v_mfma_f32_16x16x32_bf16 v[108:111], v[172:175], v[194:197], v[108:111]
	v_mfma_f32_16x16x32_bf16 v[104:107], v[182:185], v[194:197], v[104:107]
	v_mfma_f32_16x16x32_bf16 v[92:95], v[172:175], v[202:205], v[92:95]
	v_mfma_f32_16x16x32_bf16 v[88:91], v[182:185], v[202:205], v[88:91]
	v_mfma_f32_16x16x32_bf16 v[76:79], v[172:175], v[210:213], v[76:79]
	v_mfma_f32_16x16x32_bf16 v[72:75], v[182:185], v[210:213], v[72:75]
	v_mfma_f32_16x16x32_bf16 v[68:71], v[172:175], v[218:221], v[68:71]
	v_mfma_f32_16x16x32_bf16 v[64:67], v[182:185], v[218:221], v[64:67]
	v_mfma_f32_16x16x32_bf16 v[108:111], v[176:179], v[198:201], v[108:111]
	v_mfma_f32_16x16x32_bf16 v[104:107], v[190:193], v[198:201], v[104:107]
	v_mfma_f32_16x16x32_bf16 v[92:95], v[176:179], v[206:209], v[92:95]
	v_mfma_f32_16x16x32_bf16 v[88:91], v[190:193], v[206:209], v[88:91]
	v_mfma_f32_16x16x32_bf16 v[76:79], v[176:179], v[214:217], v[76:79]
	v_mfma_f32_16x16x32_bf16 v[72:75], v[190:193], v[214:217], v[72:75]
	v_mfma_f32_16x16x32_bf16 v[68:71], v[176:179], v[222:225], v[68:71]
	v_mfma_f32_16x16x32_bf16 v[64:67], v[190:193], v[222:225], v[64:67]
	s_setprio 0
	s_barrier
	s_add_i32 s26, s54, s31
	v_lshl_add_u64 v[186:187], v[186:187], 0, s[8:9]
	s_mov_b32 m0, s26
	ds_read_b128 v[194:197], v155 offset:49152
	ds_read_b128 v[198:201], v155 offset:50176
	ds_read_b128 v[202:205], v155 offset:51200
	ds_read_b128 v[206:209], v155 offset:52224
	ds_read_b128 v[210:213], v155 offset:53248
	ds_read_b128 v[214:217], v155 offset:54272
	ds_read_b128 v[218:221], v155 offset:55296
	ds_read_b128 v[222:225], v155 offset:56320
	global_load_lds_dwordx4 v[186:187], off
	s_add_i32 m0, s26, 0x2000
	s_add_u32 s24, s24, 0x40080
	v_lshl_add_u64 v[186:187], v[226:227], 0, s[8:9]
	s_addc_u32 s25, s25, 0
	s_add_i32 s26, s55, s31
	global_load_lds_dwordx4 v[186:187], off
	s_mov_b32 m0, s26
	s_nop 0
	global_load_lds_dwordx4 v130, s[24:25]
	s_add_i32 m0, s26, 0x2000
	s_nop 0
	global_load_lds_dwordx4 v134, s[24:25]
	v_lshl_add_u64 v[186:187], v[228:229], 0, s[8:9]
	s_mov_b32 m0, s39
	s_nop 0
	global_load_lds_dwordx4 v[186:187], off
	v_lshl_add_u64 v[186:187], v[230:231], 0, s[8:9]
	s_mov_b32 m0, s40
	s_nop 0
	global_load_lds_dwordx4 v[186:187], off
	s_waitcnt vmcnt(8)
	s_waitcnt lgkmcnt(0)
	s_barrier
	s_setprio 1
	v_mfma_f32_16x16x32_bf16 v[60:63], v[156:159], v[194:197], v[60:63]
	v_mfma_f32_16x16x32_bf16 v[56:59], v[164:167], v[194:197], v[56:59]
	v_mfma_f32_16x16x32_bf16 v[52:55], v[156:159], v[202:205], v[52:55]
	v_mfma_f32_16x16x32_bf16 v[48:51], v[164:167], v[202:205], v[48:51]
	v_mfma_f32_16x16x32_bf16 v[36:39], v[156:159], v[210:213], v[36:39]
	v_mfma_f32_16x16x32_bf16 v[32:35], v[164:167], v[210:213], v[32:35]
	v_mfma_f32_16x16x32_bf16 v[20:23], v[156:159], v[218:221], v[20:23]
	v_mfma_f32_16x16x32_bf16 v[16:19], v[164:167], v[218:221], v[16:19]
	v_mfma_f32_16x16x32_bf16 v[60:63], v[160:163], v[198:201], v[60:63]
	v_mfma_f32_16x16x32_bf16 v[56:59], v[168:171], v[198:201], v[56:59]
	v_mfma_f32_16x16x32_bf16 v[52:55], v[160:163], v[206:209], v[52:55]
	v_mfma_f32_16x16x32_bf16 v[48:51], v[168:171], v[206:209], v[48:51]
	v_mfma_f32_16x16x32_bf16 v[36:39], v[160:163], v[214:217], v[36:39]
	v_mfma_f32_16x16x32_bf16 v[32:35], v[168:171], v[214:217], v[32:35]
	v_mfma_f32_16x16x32_bf16 v[20:23], v[160:163], v[222:225], v[20:23]
	v_mfma_f32_16x16x32_bf16 v[16:19], v[168:171], v[222:225], v[16:19]
	v_mfma_f32_16x16x32_bf16 v[44:47], v[172:175], v[194:197], v[44:47]
	v_mfma_f32_16x16x32_bf16 v[40:43], v[182:185], v[194:197], v[40:43]
	v_mfma_f32_16x16x32_bf16 v[28:31], v[172:175], v[202:205], v[28:31]
	v_mfma_f32_16x16x32_bf16 v[24:27], v[182:185], v[202:205], v[24:27]
	v_mfma_f32_16x16x32_bf16 v[12:15], v[172:175], v[210:213], v[12:15]
	v_mfma_f32_16x16x32_bf16 v[8:11], v[182:185], v[210:213], v[8:11]
	v_mfma_f32_16x16x32_bf16 v[4:7], v[172:175], v[218:221], v[4:7]
	v_mfma_f32_16x16x32_bf16 v[0:3], v[182:185], v[218:221], v[0:3]
	v_mfma_f32_16x16x32_bf16 v[44:47], v[176:179], v[198:201], v[44:47]
	v_mfma_f32_16x16x32_bf16 v[40:43], v[190:193], v[198:201], v[40:43]
	v_mfma_f32_16x16x32_bf16 v[28:31], v[176:179], v[206:209], v[28:31]
	v_mfma_f32_16x16x32_bf16 v[24:27], v[190:193], v[206:209], v[24:27]
	v_mfma_f32_16x16x32_bf16 v[12:15], v[176:179], v[214:217], v[12:15]
	v_mfma_f32_16x16x32_bf16 v[8:11], v[190:193], v[214:217], v[8:11]
	v_mfma_f32_16x16x32_bf16 v[4:7], v[176:179], v[222:225], v[4:7]
	v_mfma_f32_16x16x32_bf16 v[0:3], v[190:193], v[222:225], v[0:3]
	s_setprio 0
	s_barrier
	s_add_i32 s49, s49, 2
	s_add_u32 s22, s22, 0x100
	s_addc_u32 s23, s23, 0
	s_add_u32 s47, s47, 0x100
	s_addc_u32 s48, s48, 0
	s_cmp_gt_u32 s49, 13
	s_cbranch_scc0 .LBB0_150
	s_and_b64 vcc, exec, s[10:11]
	s_cbranch_vccz .LBB0_153
	s_barrier

;     __host__ __device__ bool next(int i, Unit& u) const { const long L = (long)i * G + c; if (L >= nwg) return false; return unit_of((int)L, u); }
;     __host__ __device__ bool next(int i, Unit& u) const { const int L = i == 0 ? l0 : (i == 1 ? l1 : (i == 2 ? l2 : -1)); if (L < 0 || L >= s.nwg) return false; return s.unit_of(L, u); }
;     __host__ __device__ bool next(int i, Unit& u) const { const bool ok = s.next(i >> 1, u); u.kh = i & 1; return ok; }
; #define PG8_STAGE(bufoff, gbase, voff) do { _Pragma("unroll") for (int _i = 0; _i < 2; ++_i) \
;         __builtin_amdgcn_global_load_lds((const unsigned*)((const char*)(gbase) + (voff)[_i]), (PG8_LAS unsigned*)(lds + (bufoff) + ldsw + _i * 8192), 16, 0, 0); } while (0)
; #define PG8_WAIT_V(n) asm volatile("s_waitcnt vmcnt(" #n ")" ::: "memory")
; template <class Epi, class Sched, bool ALIGN_EPI = false, bool SP2 = false>
; __device__ __forceinline__ void gemm_phase(PG8_LAS unsigned char* lds, const Gemm g, const Sched& S, const Epi& E) {
;     ...
;         const bool has_next = S.next(ui + 1, nxt);
;         const char* nA = has_next ? (const char*)g.A + (size_t)nxt.pm * tstep + nxt.kh * khb : cA; const char* nB = has_next ? (const char*)g.Bt + (size_t)nxt.pn * tstep + nxt.kh * khb : cB;
;         for (int t = 0; t < nt; t += 2) {
;             const bool last = (t == nt - 2);
;             const char* a1 = cA + (size_t)(t + 1) * kstep;
;             const char* a2 = last ? nA : cA + (size_t)(t + 2) * kstep; const char* b2 = last ? nB : cB + (size_t)(t + 2) * kstep;
;             const char* a3 = a2 + kstep; const char* b3 = b2 + kstep;
;             if (last && has_next) S.a_ready(nxt);
;             if constexpr (SP2) {
;             PG8_LDB(B0, 0, 0); PG8_LDB(B1, 0, 1); PG8_SCHED; PG8_LDA(At, 0, 0); PG8_STAGE(PG8_SA(1, 1), a1 + hstep, voffA);
;             PG8_WAIT_V(8); PG8_WAIT_L(0); PG8_BAR; PG8_MMA(0, 0, At, B0); PG8_MMA(0, 1, At, B1); PG8_BAR; PG8_SCHED;
;             PG8_LDA(At, 0, 1); PG8_STAGE(PG8_SB(0, 0), b2, voffB); PG8_STAGE(PG8_SB(0, 1), b2 + hstep, voffB); PG8_STAGE(PG8_SA(0, 0), a2, voffA);
;     ...
;         for (int a = 0; a < 2; ++a)
; #pragma unroll
;             for (int b = 0; b < 2; ++b)
; #pragma unroll
;                 for (int m = 0; m < 4; ++m)
; #pragma unroll
;                     for (int n = 0; n < 2; ++n) acc[a][b][m][n] = (f32x4){0.f, 0.f, 0.f, 0.f};
.LBB0_683:
	s_ashr_i32 s3, s2, 31
	s_lshl_b64 s[12:13], s[2:3], 19
	v_readlane_b32 s3, v254, 13
	s_add_u32 s16, s3, s12
	v_readlane_b32 s3, v254, 17
	s_addc_u32 s17, s3, s13
	s_and_b64 s[12:13], s[38:39], exec
	s_cselect_b32 s3, s17, s1
	s_cselect_b32 s94, s16, s0
	s_ashr_i32 s5, s4, 31
	s_lshl_b64 s[12:13], s[4:5], 19
	v_readlane_b32 s5, v254, 15
	s_add_u32 s12, s5, s12
	s_addc_u32 s13, s50, s13
	s_and_b64 s[42:43], s[38:39], exec
	s_cselect_b32 s5, s13, s41
	s_cselect_b32 s95, s12, s40
	s_add_u32 s0, s0, 0x40080
	s_addc_u32 s1, s1, 0
	s_add_u32 s96, s40, 0x100
	s_addc_u32 s97, s41, 0
	s_mov_b32 vcc_lo, -2
	ds_read_b128 v[128:131], v174
	ds_read_b128 v[132:135], v174 offset:1024
	ds_read_b128 v[136:139], v174 offset:2048
	ds_read_b128 v[140:143], v174 offset:3072
	ds_read_b128 v[162:165], v175
	ds_read_b128 v[166:169], v175 offset:1024
	ds_read_b128 v[180:183], v175 offset:2048
	ds_read_b128 v[184:187], v175 offset:3072
	s_add_u32 s8, s0, 0xfffc0080
	s_addc_u32 s9, s1, -1
	s_cmp_eq_u32 vcc_lo, 12
	s_cselect_b32 s43, s3, s9
	s_cselect_b32 s42, s94, s8
	s_cselect_b32 s41, s5, s97
	s_cselect_b32 s40, s95, s96
	s_add_i32 m0, s47, 0xc000
	ds_read_b128 v[190:193], v176
	ds_read_b128 v[194:197], v176 offset:1024
	ds_read_b128 v[198:201], v176 offset:2048
	ds_read_b128 v[202:205], v176 offset:3072
	ds_read_b128 v[206:209], v176 offset:4096
	ds_read_b128 v[210:213], v176 offset:5120
	ds_read_b128 v[214:217], v176 offset:6144
	ds_read_b128 v[218:221], v176 offset:7168
	global_load_lds_dwordx4 v158, s[0:1]
	s_add_i32 m0, s47, 0xe000
	s_nop 0
	global_load_lds_dwordx4 v160, s[0:1]
	s_waitcnt vmcnt(8)
	s_waitcnt lgkmcnt(0)
	s_barrier
	s_setprio 1
	v_mfma_f32_16x16x32_bf16 v[124:127], v[128:131], v[190:193], 0
	v_mfma_f32_16x16x32_bf16 v[120:123], v[136:139], v[190:193], 0
	v_mfma_f32_16x16x32_bf16 v[108:111], v[128:131], v[198:201], 0
	v_mfma_f32_16x16x32_bf16 v[104:107], v[136:139], v[198:201], 0
	v_mfma_f32_16x16x32_bf16 v[92:95], v[128:131], v[206:209], 0
	v_mfma_f32_16x16x32_bf16 v[88:91], v[136:139], v[206:209], 0
	v_mfma_f32_16x16x32_bf16 v[76:79], v[128:131], v[214:217], 0
	v_mfma_f32_16x16x32_bf16 v[72:75], v[136:139], v[214:217], 0
	v_mfma_f32_16x16x32_bf16 v[124:127], v[132:135], v[194:197], v[124:127]
	v_mfma_f32_16x16x32_bf16 v[120:123], v[140:143], v[194:197], v[120:123]
	v_mfma_f32_16x16x32_bf16 v[108:111], v[132:135], v[202:205], v[108:111]
	v_mfma_f32_16x16x32_bf16 v[104:107], v[140:143], v[202:205], v[104:107]
	v_mfma_f32_16x16x32_bf16 v[92:95], v[132:135], v[210:213], v[92:95]
	v_mfma_f32_16x16x32_bf16 v[88:91], v[140:143], v[210:213], v[88:91]
	v_mfma_f32_16x16x32_bf16 v[76:79], v[132:135], v[218:221], v[76:79]
	v_mfma_f32_16x16x32_bf16 v[72:75], v[140:143], v[218:221], v[72:75]
	v_mfma_f32_16x16x32_bf16 v[116:119], v[162:165], v[190:193], 0
	v_mfma_f32_16x16x32_bf16 v[112:115], v[180:183], v[190:193], 0
	v_mfma_f32_16x16x32_bf16 v[100:103], v[162:165], v[198:201], 0
	v_mfma_f32_16x16x32_bf16 v[96:99], v[180:183], v[198:201], 0
	v_mfma_f32_16x16x32_bf16 v[84:87], v[162:165], v[206:209], 0
	v_mfma_f32_16x16x32_bf16 v[80:83], v[180:183], v[206:209], 0
	v_mfma_f32_16x16x32_bf16 v[68:71], v[162:165], v[214:217], 0
	v_mfma_f32_16x16x32_bf16 v[64:67], v[180:183], v[214:217], 0
	v_mfma_f32_16x16x32_bf16 v[116:119], v[166:169], v[194:197], v[116:119]
	v_mfma_f32_16x16x32_bf16 v[112:115], v[184:187], v[194:197], v[112:115]
	v_mfma_f32_16x16x32_bf16 v[100:103], v[166:169], v[202:205], v[100:103]
	v_mfma_f32_16x16x32_bf16 v[96:99], v[184:187], v[202:205], v[96:99]
	v_mfma_f32_16x16x32_bf16 v[84:87], v[166:169], v[210:213], v[84:87]
	v_mfma_f32_16x16x32_bf16 v[80:83], v[184:187], v[210:213], v[80:83]
	v_mfma_f32_16x16x32_bf16 v[68:71], v[166:169], v[218:221], v[68:71]
	v_mfma_f32_16x16x32_bf16 v[64:67], v[184:187], v[218:221], v[64:67]
	s_setprio 0
	s_barrier
	s_add_i32 s8, s76, s46
	v_lshl_add_u64 v[170:171], s[40:41], 0, v[146:147]
	s_mov_b32 m0, s8
	ds_read_b128 v[190:193], v176 offset:16384
	ds_read_b128 v[194:197], v176 offset:17408
	ds_read_b128 v[198:201], v176 offset:18432
	ds_read_b128 v[202:205], v176 offset:19456
	ds_read_b128 v[206:209], v176 offset:20480
	ds_read_b128 v[210:213], v176 offset:21504
	ds_read_b128 v[214:217], v176 offset:22528
	ds_read_b128 v[218:221], v176 offset:23552
	global_load_lds_dwordx4 v[170:171], off
	s_add_i32 m0, s8, 0x2000
	s_add_u32 s8, s40, 0x40000
	v_lshl_add_u64 v[222:223], s[40:41], 0, v[150:151]
	s_addc_u32 s9, s41, 0
	s_add_i32 s54, s77, s46
	global_load_lds_dwordx4 v[222:223], off
	s_mov_b32 m0, s54
	v_lshl_add_u64 v[226:227], s[42:43], 0, v[148:149]
	global_load_lds_dwordx4 v146, s[8:9]
	s_add_i32 m0, s54, 0x2000
	s_nop 0
	global_load_lds_dwordx4 v150, s[8:9]
	v_lshl_add_u64 v[224:225], s[42:43], 0, v[144:145]
	s_mov_b32 m0, s47
	s_nop 0
	global_load_lds_dwordx4 v[224:225], off
	s_mov_b32 m0, s48
	s_nop 0
	global_load_lds_dwordx4 v[226:227], off
	s_waitcnt vmcnt(8)
	s_waitcnt lgkmcnt(0)
	s_barrier
; #define PG8_STAGE(bufoff, gbase, voff) do { _Pragma("unroll") for (int _i = 0; _i < 2; ++_i) \
;         __builtin_amdgcn_global_load_lds((const unsigned*)((const char*)(gbase) + (voff)[_i]), (PG8_LAS unsigned*)(lds + (bufoff) + ldsw + _i * 8192), 16, 0, 0); } while (0)
; #define PG8_LDA(dst, b, h) do { _Pragma("unroll") for (int m = 0; m < 4; ++m) _Pragma("unroll") for (int k = 0; k < 2; ++k) dst[m][k] = *(const PG8_LAS bf16x8*)(lds + PG8_SA(b, h) + aoff + m * 2048 + k * 1024); } while (0)
; #define PG8_LDB(dst, b, h) do { _Pragma("unroll") for (int n = 0; n < 2; ++n) _Pragma("unroll") for (int k = 0; k < 2; ++k) dst[n][k] = *(const PG8_LAS bf16x8*)(lds + PG8_SB(b, h) + boff + n * 2048 + k * 1024); } while (0)
; #define PG8_MMA(ai, bj, At, Bt) do { __builtin_amdgcn_s_setprio(1); _Pragma("unroll") for (int m = 0; m < 4; ++m) _Pragma("unroll") for (int n = 0; n < 2; ++n) _Pragma("unroll") for (int k = 0; k < 2; ++k) \
;         acc[ai][bj][m][n] = __builtin_amdgcn_mfma_f32_16x16x32_bf16(Bt[n][k], At[m][k], acc[ai][bj][m][n], 0, 0, 0); __builtin_amdgcn_s_setprio(0); } while (0)
; #define PG8_WAIT_V(n) asm volatile("s_waitcnt vmcnt(" #n ")" ::: "memory")
; #define PG8_WAIT_L(n) asm volatile("s_waitcnt lgkmcnt(" #n ")" ::: "memory")
; #define PG8_BAR __builtin_amdgcn_s_barrier()
; #define PG8_SCHED __builtin_amdgcn_sched_barrier(0)
; template <class Epi, class Sched, bool ALIGN_EPI = false, bool SP2 = false>
; __device__ __forceinline__ void gemm_phase(PG8_LAS unsigned char* lds, const Gemm g, const Sched& S, const Epi& E) {
;     ...
;             PG8_LDB(B0, 0, 0); PG8_LDB(B1, 0, 1); PG8_SCHED; PG8_LDA(At, 0, 0); PG8_STAGE(PG8_SA(1, 1), a1 + hstep, voffA);
;             PG8_WAIT_V(8); PG8_WAIT_L(0); PG8_BAR; PG8_MMA(0, 0, At, B0); PG8_MMA(0, 1, At, B1); PG8_BAR; PG8_SCHED;
;             PG8_LDA(At, 0, 1); PG8_STAGE(PG8_SB(0, 0), b2, voffB); PG8_STAGE(PG8_SB(0, 1), b2 + hstep, voffB); PG8_STAGE(PG8_SA(0, 0), a2, voffA);
;             PG8_WAIT_V(8); PG8_WAIT_L(0); PG8_BAR; PG8_MMA(1, 0, At, B0); PG8_MMA(1, 1, At, B1); PG8_BAR; PG8_SCHED;
	s_setprio 1
	v_mfma_f32_16x16x32_bf16 v[60:63], v[128:131], v[190:193], 0
	v_mfma_f32_16x16x32_bf16 v[56:59], v[136:139], v[190:193], 0
	v_mfma_f32_16x16x32_bf16 v[44:47], v[128:131], v[198:201], 0
	v_mfma_f32_16x16x32_bf16 v[40:43], v[136:139], v[198:201], 0
	v_mfma_f32_16x16x32_bf16 v[28:31], v[128:131], v[206:209], 0
	v_mfma_f32_16x16x32_bf16 v[24:27], v[136:139], v[206:209], 0
	v_mfma_f32_16x16x32_bf16 v[12:15], v[128:131], v[214:217], 0
	v_mfma_f32_16x16x32_bf16 v[8:11], v[136:139], v[214:217], 0
	v_mfma_f32_16x16x32_bf16 v[60:63], v[132:135], v[194:197], v[60:63]
	v_mfma_f32_16x16x32_bf16 v[56:59], v[140:143], v[194:197], v[56:59]
	v_mfma_f32_16x16x32_bf16 v[44:47], v[132:135], v[202:205], v[44:47]
	v_mfma_f32_16x16x32_bf16 v[40:43], v[140:143], v[202:205], v[40:43]
	v_mfma_f32_16x16x32_bf16 v[28:31], v[132:135], v[210:213], v[28:31]
	v_mfma_f32_16x16x32_bf16 v[24:27], v[140:143], v[210:213], v[24:27]
	v_mfma_f32_16x16x32_bf16 v[12:15], v[132:135], v[218:221], v[12:15]
	v_mfma_f32_16x16x32_bf16 v[8:11], v[140:143], v[218:221], v[8:11]
	v_mfma_f32_16x16x32_bf16 v[52:55], v[162:165], v[190:193], 0
	v_mfma_f32_16x16x32_bf16 v[48:51], v[180:183], v[190:193], 0
	v_mfma_f32_16x16x32_bf16 v[36:39], v[162:165], v[198:201], 0
	v_mfma_f32_16x16x32_bf16 v[32:35], v[180:183], v[198:201], 0
	v_mfma_f32_16x16x32_bf16 v[20:23], v[162:165], v[206:209], 0
	v_mfma_f32_16x16x32_bf16 v[16:19], v[180:183], v[206:209], 0
	v_mfma_f32_16x16x32_bf16 v[4:7], v[162:165], v[214:217], 0
	v_mfma_f32_16x16x32_bf16 v[0:3], v[180:183], v[214:217], 0
	v_mfma_f32_16x16x32_bf16 v[52:55], v[166:169], v[194:197], v[52:55]
	v_mfma_f32_16x16x32_bf16 v[48:51], v[184:187], v[194:197], v[48:51]
	v_mfma_f32_16x16x32_bf16 v[36:39], v[166:169], v[202:205], v[36:39]
	v_mfma_f32_16x16x32_bf16 v[32:35], v[184:187], v[202:205], v[32:35]
	v_mfma_f32_16x16x32_bf16 v[20:23], v[166:169], v[210:213], v[20:23]
	v_mfma_f32_16x16x32_bf16 v[16:19], v[184:187], v[210:213], v[16:19]
	v_mfma_f32_16x16x32_bf16 v[4:7], v[166:169], v[218:221], v[4:7]
	v_mfma_f32_16x16x32_bf16 v[0:3], v[184:187], v[218:221], v[0:3]
	s_setprio 0
	s_barrier
	s_branch .Lmy_peel_684_mid
.LBB0_684:
	ds_read_b128 v[128:131], v174
	ds_read_b128 v[132:135], v174 offset:1024
	ds_read_b128 v[136:139], v174 offset:2048
	ds_read_b128 v[140:143], v174 offset:3072
	ds_read_b128 v[162:165], v175
	ds_read_b128 v[166:169], v175 offset:1024
	ds_read_b128 v[180:183], v175 offset:2048
	ds_read_b128 v[184:187], v175 offset:3072
	s_add_u32 s8, s0, 0xfffc0080
	s_addc_u32 s9, s1, -1
	s_cmp_eq_u32 vcc_lo, 12
	s_cselect_b32 s43, s3, s9
	s_cselect_b32 s42, s94, s8
	s_cselect_b32 s41, s5, s97
	s_cselect_b32 s40, s95, s96
	s_add_i32 m0, s47, 0xc000
	ds_read_b128 v[190:193], v176
	ds_read_b128 v[194:197], v176 offset:1024
	ds_read_b128 v[198:201], v176 offset:2048
	ds_read_b128 v[202:205], v176 offset:3072
	ds_read_b128 v[206:209], v176 offset:4096
	ds_read_b128 v[210:213], v176 offset:5120
	ds_read_b128 v[214:217], v176 offset:6144
	ds_read_b128 v[218:221], v176 offset:7168
	global_load_lds_dwordx4 v158, s[0:1]
	s_add_i32 m0, s47, 0xe000
	s_nop 0
	global_load_lds_dwordx4 v160, s[0:1]
	s_waitcnt vmcnt(8)
	s_waitcnt lgkmcnt(0)
	s_barrier
	s_setprio 1
	v_mfma_f32_16x16x32_bf16 v[124:127], v[128:131], v[190:193], v[124:127]
	v_mfma_f32_16x16x32_bf16 v[120:123], v[136:139], v[190:193], v[120:123]
	v_mfma_f32_16x16x32_bf16 v[108:111], v[128:131], v[198:201], v[108:111]
	v_mfma_f32_16x16x32_bf16 v[104:107], v[136:139], v[198:201], v[104:107]
	v_mfma_f32_16x16x32_bf16 v[92:95], v[128:131], v[206:209], v[92:95]
	v_mfma_f32_16x16x32_bf16 v[88:91], v[136:139], v[206:209], v[88:91]
	v_mfma_f32_16x16x32_bf16 v[76:79], v[128:131], v[214:217], v[76:79]
	v_mfma_f32_16x16x32_bf16 v[72:75], v[136:139], v[214:217], v[72:75]
	v_mfma_f32_16x16x32_bf16 v[124:127], v[132:135], v[194:197], v[124:127]
	v_mfma_f32_16x16x32_bf16 v[120:123], v[140:143], v[194:197], v[120:123]
	v_mfma_f32_16x16x32_bf16 v[108:111], v[132:135], v[202:205], v[108:111]
	v_mfma_f32_16x16x32_bf16 v[104:107], v[140:143], v[202:205], v[104:107]
	v_mfma_f32_16x16x32_bf16 v[92:95], v[132:135], v[210:213], v[92:95]
	v_mfma_f32_16x16x32_bf16 v[88:91], v[140:143], v[210:213], v[88:91]
	v_mfma_f32_16x16x32_bf16 v[76:79], v[132:135], v[218:221], v[76:79]
	v_mfma_f32_16x16x32_bf16 v[72:75], v[140:143], v[218:221], v[72:75]
	v_mfma_f32_16x16x32_bf16 v[116:119], v[162:165], v[190:193], v[116:119]
	v_mfma_f32_16x16x32_bf16 v[112:115], v[180:183], v[190:193], v[112:115]
	v_mfma_f32_16x16x32_bf16 v[100:103], v[162:165], v[198:201], v[100:103]
	v_mfma_f32_16x16x32_bf16 v[96:99], v[180:183], v[198:201], v[96:99]
	v_mfma_f32_16x16x32_bf16 v[84:87], v[162:165], v[206:209], v[84:87]
	v_mfma_f32_16x16x32_bf16 v[80:83], v[180:183], v[206:209], v[80:83]
	v_mfma_f32_16x16x32_bf16 v[68:71], v[162:165], v[214:217], v[68:71]
	v_mfma_f32_16x16x32_bf16 v[64:67], v[180:183], v[214:217], v[64:67]
	v_mfma_f32_16x16x32_bf16 v[116:119], v[166:169], v[194:197], v[116:119]
	v_mfma_f32_16x16x32_bf16 v[112:115], v[184:187], v[194:197], v[112:115]
	v_mfma_f32_16x16x32_bf16 v[100:103], v[166:169], v[202:205], v[100:103]
	v_mfma_f32_16x16x32_bf16 v[96:99], v[184:187], v[202:205], v[96:99]
	v_mfma_f32_16x16x32_bf16 v[84:87], v[166:169], v[210:213], v[84:87]
	v_mfma_f32_16x16x32_bf16 v[80:83], v[184:187], v[210:213], v[80:83]
	v_mfma_f32_16x16x32_bf16 v[68:71], v[166:169], v[218:221], v[68:71]
	v_mfma_f32_16x16x32_bf16 v[64:67], v[184:187], v[218:221], v[64:67]
	s_setprio 0
	s_barrier
; #define PG8_STAGE(bufoff, gbase, voff) do { _Pragma("unroll") for (int _i = 0; _i < 2; ++_i) \
;         __builtin_amdgcn_global_load_lds((const unsigned*)((const char*)(gbase) + (voff)[_i]), (PG8_LAS unsigned*)(lds + (bufoff) + ldsw + _i * 8192), 16, 0, 0); } while (0)
; #define PG8_LDA(dst, b, h) do { _Pragma("unroll") for (int m = 0; m < 4; ++m) _Pragma("unroll") for (int k = 0; k < 2; ++k) dst[m][k] = *(const PG8_LAS bf16x8*)(lds + PG8_SA(b, h) + aoff + m * 2048 + k * 1024); } while (0)
; #define PG8_MMA(ai, bj, At, Bt) do { __builtin_amdgcn_s_setprio(1); _Pragma("unroll") for (int m = 0; m < 4; ++m) _Pragma("unroll") for (int n = 0; n < 2; ++n) _Pragma("unroll") for (int k = 0; k < 2; ++k) \
;         acc[ai][bj][m][n] = __builtin_amdgcn_mfma_f32_16x16x32_bf16(Bt[n][k], At[m][k], acc[ai][bj][m][n], 0, 0, 0); __builtin_amdgcn_s_setprio(0); } while (0)
; #define PG8_WAIT_V(n) asm volatile("s_waitcnt vmcnt(" #n ")" ::: "memory")
; #define PG8_WAIT_L(n) asm volatile("s_waitcnt lgkmcnt(" #n ")" ::: "memory")
; #define PG8_BAR __builtin_amdgcn_s_barrier()
; #define PG8_SCHED __builtin_amdgcn_sched_barrier(0)
; template <class Epi, class Sched, bool ALIGN_EPI = false, bool SP2 = false>
; __device__ __forceinline__ void gemm_phase(PG8_LAS unsigned char* lds, const Gemm g, const Sched& S, const Epi& E) {
;     ...
;             PG8_LDA(At, 0, 1); PG8_STAGE(PG8_SB(0, 0), b2, voffB); PG8_STAGE(PG8_SB(0, 1), b2 + hstep, voffB); PG8_STAGE(PG8_SA(0, 0), a2, voffA);
;             PG8_WAIT_V(8); PG8_WAIT_L(0); PG8_BAR; PG8_MMA(1, 0, At, B0); PG8_MMA(1, 1, At, B1); PG8_BAR; PG8_SCHED;
	s_add_i32 s8, s76, s46
	v_lshl_add_u64 v[170:171], s[40:41], 0, v[146:147]
	s_mov_b32 m0, s8
	ds_read_b128 v[190:193], v176 offset:16384
	ds_read_b128 v[194:197], v176 offset:17408
	ds_read_b128 v[198:201], v176 offset:18432
	ds_read_b128 v[202:205], v176 offset:19456
	ds_read_b128 v[206:209], v176 offset:20480
	ds_read_b128 v[210:213], v176 offset:21504
	ds_read_b128 v[214:217], v176 offset:22528
	ds_read_b128 v[218:221], v176 offset:23552
	global_load_lds_dwordx4 v[170:171], off
	s_add_i32 m0, s8, 0x2000
	s_add_u32 s8, s40, 0x40000
	v_lshl_add_u64 v[222:223], s[40:41], 0, v[150:151]
	s_addc_u32 s9, s41, 0
	s_add_i32 s54, s77, s46
	global_load_lds_dwordx4 v[222:223], off
	s_mov_b32 m0, s54
	v_lshl_add_u64 v[226:227], s[42:43], 0, v[148:149]
	global_load_lds_dwordx4 v146, s[8:9]
	s_add_i32 m0, s54, 0x2000
	s_nop 0
	global_load_lds_dwordx4 v150, s[8:9]
	v_lshl_add_u64 v[224:225], s[42:43], 0, v[144:145]
	s_mov_b32 m0, s47
	s_nop 0
	global_load_lds_dwordx4 v[224:225], off
	s_mov_b32 m0, s48
	s_nop 0
	global_load_lds_dwordx4 v[226:227], off
	s_waitcnt vmcnt(8)
	s_waitcnt lgkmcnt(0)
	s_barrier
	s_setprio 1
	v_mfma_f32_16x16x32_bf16 v[60:63], v[128:131], v[190:193], v[60:63]
	v_mfma_f32_16x16x32_bf16 v[56:59], v[136:139], v[190:193], v[56:59]
	v_mfma_f32_16x16x32_bf16 v[44:47], v[128:131], v[198:201], v[44:47]
	v_mfma_f32_16x16x32_bf16 v[40:43], v[136:139], v[198:201], v[40:43]
	v_mfma_f32_16x16x32_bf16 v[28:31], v[128:131], v[206:209], v[28:31]
	v_mfma_f32_16x16x32_bf16 v[24:27], v[136:139], v[206:209], v[24:27]
	v_mfma_f32_16x16x32_bf16 v[12:15], v[128:131], v[214:217], v[12:15]
	v_mfma_f32_16x16x32_bf16 v[8:11], v[136:139], v[214:217], v[8:11]
	v_mfma_f32_16x16x32_bf16 v[60:63], v[132:135], v[194:197], v[60:63]
	v_mfma_f32_16x16x32_bf16 v[56:59], v[140:143], v[194:197], v[56:59]
	v_mfma_f32_16x16x32_bf16 v[44:47], v[132:135], v[202:205], v[44:47]
	v_mfma_f32_16x16x32_bf16 v[40:43], v[140:143], v[202:205], v[40:43]
	v_mfma_f32_16x16x32_bf16 v[28:31], v[132:135], v[210:213], v[28:31]
	v_mfma_f32_16x16x32_bf16 v[24:27], v[140:143], v[210:213], v[24:27]
	v_mfma_f32_16x16x32_bf16 v[12:15], v[132:135], v[218:221], v[12:15]
	v_mfma_f32_16x16x32_bf16 v[8:11], v[140:143], v[218:221], v[8:11]
	v_mfma_f32_16x16x32_bf16 v[52:55], v[162:165], v[190:193], v[52:55]
	v_mfma_f32_16x16x32_bf16 v[48:51], v[180:183], v[190:193], v[48:51]
	v_mfma_f32_16x16x32_bf16 v[36:39], v[162:165], v[198:201], v[36:39]
	v_mfma_f32_16x16x32_bf16 v[32:35], v[180:183], v[198:201], v[32:35]
	v_mfma_f32_16x16x32_bf16 v[20:23], v[162:165], v[206:209], v[20:23]
	v_mfma_f32_16x16x32_bf16 v[16:19], v[180:183], v[206:209], v[16:19]
	v_mfma_f32_16x16x32_bf16 v[4:7], v[162:165], v[214:217], v[4:7]
	v_mfma_f32_16x16x32_bf16 v[0:3], v[180:183], v[214:217], v[0:3]
	v_mfma_f32_16x16x32_bf16 v[52:55], v[166:169], v[194:197], v[52:55]
	v_mfma_f32_16x16x32_bf16 v[48:51], v[184:187], v[194:197], v[48:51]
	v_mfma_f32_16x16x32_bf16 v[36:39], v[166:169], v[202:205], v[36:39]
	v_mfma_f32_16x16x32_bf16 v[32:35], v[184:187], v[202:205], v[32:35]
	v_mfma_f32_16x16x32_bf16 v[20:23], v[166:169], v[210:213], v[20:23]
	v_mfma_f32_16x16x32_bf16 v[16:19], v[184:187], v[210:213], v[16:19]
	v_mfma_f32_16x16x32_bf16 v[4:7], v[166:169], v[218:221], v[4:7]
	v_mfma_f32_16x16x32_bf16 v[0:3], v[184:187], v[218:221], v[0:3]
	s_setprio 0
	s_barrier
; #define PG8_STAGE(bufoff, gbase, voff) do { _Pragma("unroll") for (int _i = 0; _i < 2; ++_i) \
;         __builtin_amdgcn_global_load_lds((const unsigned*)((const char*)(gbase) + (voff)[_i]), (PG8_LAS unsigned*)(lds + (bufoff) + ldsw + _i * 8192), 16, 0, 0); } while (0)
; #define PG8_LDA(dst, b, h) do { _Pragma("unroll") for (int m = 0; m < 4; ++m) _Pragma("unroll") for (int k = 0; k < 2; ++k) dst[m][k] = *(const PG8_LAS bf16x8*)(lds + PG8_SA(b, h) + aoff + m * 2048 + k * 1024); } while (0)
; #define PG8_LDB(dst, b, h) do { _Pragma("unroll") for (int n = 0; n < 2; ++n) _Pragma("unroll") for (int k = 0; k < 2; ++k) dst[n][k] = *(const PG8_LAS bf16x8*)(lds + PG8_SB(b, h) + boff + n * 2048 + k * 1024); } while (0)
; #define PG8_MMA(ai, bj, At, Bt) do { __builtin_amdgcn_s_setprio(1); _Pragma("unroll") for (int m = 0; m < 4; ++m) _Pragma("unroll") for (int n = 0; n < 2; ++n) _Pragma("unroll") for (int k = 0; k < 2; ++k) \
;         acc[ai][bj][m][n] = __builtin_amdgcn_mfma_f32_16x16x32_bf16(Bt[n][k], At[m][k], acc[ai][bj][m][n], 0, 0, 0); __builtin_amdgcn_s_setprio(0); } while (0)
; #define PG8_WAIT_V(n) asm volatile("s_waitcnt vmcnt(" #n ")" ::: "memory")
; #define PG8_WAIT_L(n) asm volatile("s_waitcnt lgkmcnt(" #n ")" ::: "memory")
; #define PG8_BAR __builtin_amdgcn_s_barrier()
; #define PG8_SCHED __builtin_amdgcn_sched_barrier(0)
; template <class Epi, class Sched, bool ALIGN_EPI = false, bool SP2 = false>
; __device__ __forceinline__ void gemm_phase(PG8_LAS unsigned char* lds, const Gemm g, const Sched& S, const Epi& E) {
;     ...
;         for (int t = 0; t < nt; t += 2) {
;     ...
;             PG8_LDB(B0, 1, 0); PG8_LDB(B1, 1, 1); PG8_SCHED; PG8_LDA(At, 1, 0); PG8_STAGE(PG8_SA(0, 1), a2 + hstep, voffA);
;             PG8_WAIT_V(8); PG8_WAIT_L(0); PG8_BAR; PG8_MMA(0, 0, At, B0); PG8_MMA(0, 1, At, B1); PG8_BAR; PG8_SCHED;
;             PG8_LDA(At, 1, 1); PG8_STAGE(PG8_SB(1, 0), b3, voffB); PG8_STAGE(PG8_SB(1, 1), b3 + hstep, voffB); PG8_STAGE(PG8_SA(1, 0), a3, voffA);
;             PG8_WAIT_V(8); PG8_WAIT_L(0); PG8_BAR; PG8_MMA(1, 0, At, B0); PG8_MMA(1, 1, At, B1); PG8_BAR; PG8_SCHED;
.Lmy_peel_684_mid:
	s_add_i32 s54, 0, 0x18000
	s_add_i32 s55, 0, 0x1c000
	v_add_u32_e32 v140, s54, v172
	v_add_u32_e32 v152, s55, v172
	ds_read_b128 v[128:131], v140
	ds_read_b128 v[132:135], v140 offset:1024
	ds_read_b128 v[136:139], v140 offset:2048
	ds_read_b128 v[140:143], v140 offset:3072
	ds_read_b128 v[162:165], v152
	ds_read_b128 v[166:169], v152 offset:1024
	ds_read_b128 v[180:183], v152 offset:2048
	ds_read_b128 v[184:187], v152 offset:3072
	s_add_u32 s8, s42, 0x40000
	s_addc_u32 s9, s43, 0
	s_mov_b32 m0, s49
	ds_read_b128 v[190:193], v176 offset:32768
	ds_read_b128 v[194:197], v176 offset:33792
	ds_read_b128 v[198:201], v176 offset:34816
	ds_read_b128 v[202:205], v176 offset:35840
	ds_read_b128 v[206:209], v176 offset:36864
	ds_read_b128 v[210:213], v176 offset:37888
	ds_read_b128 v[214:217], v176 offset:38912
	ds_read_b128 v[218:221], v176 offset:39936
	global_load_lds_dwordx4 v144, s[8:9]
	s_mov_b32 m0, s51
	s_nop 0
	global_load_lds_dwordx4 v148, s[8:9]
	s_waitcnt vmcnt(8)
	s_waitcnt lgkmcnt(0)
	s_barrier
	s_setprio 1
	v_mfma_f32_16x16x32_bf16 v[124:127], v[128:131], v[190:193], v[124:127]
	v_mfma_f32_16x16x32_bf16 v[120:123], v[136:139], v[190:193], v[120:123]
	v_mfma_f32_16x16x32_bf16 v[108:111], v[128:131], v[198:201], v[108:111]
	v_mfma_f32_16x16x32_bf16 v[104:107], v[136:139], v[198:201], v[104:107]
	v_mfma_f32_16x16x32_bf16 v[92:95], v[128:131], v[206:209], v[92:95]
	v_mfma_f32_16x16x32_bf16 v[88:91], v[136:139], v[206:209], v[88:91]
	v_mfma_f32_16x16x32_bf16 v[76:79], v[128:131], v[214:217], v[76:79]
	v_mfma_f32_16x16x32_bf16 v[72:75], v[136:139], v[214:217], v[72:75]
	v_mfma_f32_16x16x32_bf16 v[124:127], v[132:135], v[194:197], v[124:127]
	v_mfma_f32_16x16x32_bf16 v[120:123], v[140:143], v[194:197], v[120:123]
	v_mfma_f32_16x16x32_bf16 v[108:111], v[132:135], v[202:205], v[108:111]
	v_mfma_f32_16x16x32_bf16 v[104:107], v[140:143], v[202:205], v[104:107]
	v_mfma_f32_16x16x32_bf16 v[92:95], v[132:135], v[210:213], v[92:95]
	v_mfma_f32_16x16x32_bf16 v[88:91], v[140:143], v[210:213], v[88:91]
	v_mfma_f32_16x16x32_bf16 v[76:79], v[132:135], v[218:221], v[76:79]
	v_mfma_f32_16x16x32_bf16 v[72:75], v[140:143], v[218:221], v[72:75]
	v_mfma_f32_16x16x32_bf16 v[116:119], v[162:165], v[190:193], v[116:119]
	v_mfma_f32_16x16x32_bf16 v[112:115], v[180:183], v[190:193], v[112:115]
	v_mfma_f32_16x16x32_bf16 v[100:103], v[162:165], v[198:201], v[100:103]
	v_mfma_f32_16x16x32_bf16 v[96:99], v[180:183], v[198:201], v[96:99]
	v_mfma_f32_16x16x32_bf16 v[84:87], v[162:165], v[206:209], v[84:87]
	v_mfma_f32_16x16x32_bf16 v[80:83], v[180:183], v[206:209], v[80:83]
	v_mfma_f32_16x16x32_bf16 v[68:71], v[162:165], v[214:217], v[68:71]
	v_mfma_f32_16x16x32_bf16 v[64:67], v[180:183], v[214:217], v[64:67]
	v_mfma_f32_16x16x32_bf16 v[116:119], v[166:169], v[194:197], v[116:119]
	v_mfma_f32_16x16x32_bf16 v[112:115], v[184:187], v[194:197], v[112:115]
	v_mfma_f32_16x16x32_bf16 v[100:103], v[166:169], v[202:205], v[100:103]
	v_mfma_f32_16x16x32_bf16 v[96:99], v[184:187], v[202:205], v[96:99]
	v_mfma_f32_16x16x32_bf16 v[84:87], v[166:169], v[210:213], v[84:87]
	v_mfma_f32_16x16x32_bf16 v[80:83], v[184:187], v[210:213], v[80:83]
	v_mfma_f32_16x16x32_bf16 v[68:71], v[166:169], v[218:221], v[68:71]
	v_mfma_f32_16x16x32_bf16 v[64:67], v[184:187], v[218:221], v[64:67]
	s_setprio 0
	s_barrier
	s_add_i32 s8, s54, s46
	v_lshl_add_u64 v[170:171], v[170:171], 0, s[14:15]
	s_mov_b32 m0, s8
	ds_read_b128 v[190:193], v176 offset:49152
	ds_read_b128 v[194:197], v176 offset:50176
	ds_read_b128 v[198:201], v176 offset:51200
	ds_read_b128 v[202:205], v176 offset:52224
	ds_read_b128 v[206:209], v176 offset:53248
	ds_read_b128 v[210:213], v176 offset:54272
	ds_read_b128 v[214:217], v176 offset:55296
	ds_read_b128 v[218:221], v176 offset:56320
	global_load_lds_dwordx4 v[170:171], off
	s_add_i32 m0, s8, 0x2000
	s_add_u32 s8, s40, 0x40080
	v_lshl_add_u64 v[170:171], v[222:223], 0, s[14:15]
	s_addc_u32 s9, s41, 0
	s_add_i32 s40, s55, s46
	global_load_lds_dwordx4 v[170:171], off
	s_mov_b32 m0, s40
	s_nop 0
	global_load_lds_dwordx4 v146, s[8:9]
	s_add_i32 m0, s40, 0x2000
	s_nop 0
	global_load_lds_dwordx4 v150, s[8:9]
	v_lshl_add_u64 v[170:171], v[224:225], 0, s[14:15]
	s_mov_b32 m0, s66
	s_nop 0
	global_load_lds_dwordx4 v[170:171], off
	v_lshl_add_u64 v[170:171], v[226:227], 0, s[14:15]
	s_mov_b32 m0, s67
	s_nop 0
	global_load_lds_dwordx4 v[170:171], off
	s_waitcnt vmcnt(8)
	s_waitcnt lgkmcnt(0)
	s_barrier
	s_setprio 1
	v_mfma_f32_16x16x32_bf16 v[60:63], v[128:131], v[190:193], v[60:63]
	v_mfma_f32_16x16x32_bf16 v[56:59], v[136:139], v[190:193], v[56:59]
	v_mfma_f32_16x16x32_bf16 v[44:47], v[128:131], v[198:201], v[44:47]
	v_mfma_f32_16x16x32_bf16 v[40:43], v[136:139], v[198:201], v[40:43]
	v_mfma_f32_16x16x32_bf16 v[28:31], v[128:131], v[206:209], v[28:31]
	v_mfma_f32_16x16x32_bf16 v[24:27], v[136:139], v[206:209], v[24:27]
	v_mfma_f32_16x16x32_bf16 v[12:15], v[128:131], v[214:217], v[12:15]
	v_mfma_f32_16x16x32_bf16 v[8:11], v[136:139], v[214:217], v[8:11]
	v_mfma_f32_16x16x32_bf16 v[60:63], v[132:135], v[194:197], v[60:63]
	v_mfma_f32_16x16x32_bf16 v[56:59], v[140:143], v[194:197], v[56:59]
	v_mfma_f32_16x16x32_bf16 v[44:47], v[132:135], v[202:205], v[44:47]
	v_mfma_f32_16x16x32_bf16 v[40:43], v[140:143], v[202:205], v[40:43]
	v_mfma_f32_16x16x32_bf16 v[28:31], v[132:135], v[210:213], v[28:31]
	v_mfma_f32_16x16x32_bf16 v[24:27], v[140:143], v[210:213], v[24:27]
	v_mfma_f32_16x16x32_bf16 v[12:15], v[132:135], v[218:221], v[12:15]
	v_mfma_f32_16x16x32_bf16 v[8:11], v[140:143], v[218:221], v[8:11]
	v_mfma_f32_16x16x32_bf16 v[52:55], v[162:165], v[190:193], v[52:55]
	v_mfma_f32_16x16x32_bf16 v[48:51], v[180:183], v[190:193], v[48:51]
	v_mfma_f32_16x16x32_bf16 v[36:39], v[162:165], v[198:201], v[36:39]
	v_mfma_f32_16x16x32_bf16 v[32:35], v[180:183], v[198:201], v[32:35]
	v_mfma_f32_16x16x32_bf16 v[20:23], v[162:165], v[206:209], v[20:23]
	v_mfma_f32_16x16x32_bf16 v[16:19], v[180:183], v[206:209], v[16:19]
	v_mfma_f32_16x16x32_bf16 v[4:7], v[162:165], v[214:217], v[4:7]
	v_mfma_f32_16x16x32_bf16 v[0:3], v[180:183], v[214:217], v[0:3]
	v_mfma_f32_16x16x32_bf16 v[52:55], v[166:169], v[194:197], v[52:55]
	v_mfma_f32_16x16x32_bf16 v[48:51], v[184:187], v[194:197], v[48:51]
	v_mfma_f32_16x16x32_bf16 v[36:39], v[166:169], v[202:205], v[36:39]
	v_mfma_f32_16x16x32_bf16 v[32:35], v[184:187], v[202:205], v[32:35]
	v_mfma_f32_16x16x32_bf16 v[20:23], v[166:169], v[210:213], v[20:23]
	v_mfma_f32_16x16x32_bf16 v[16:19], v[184:187], v[210:213], v[16:19]
	v_mfma_f32_16x16x32_bf16 v[4:7], v[166:169], v[218:221], v[4:7]
	v_mfma_f32_16x16x32_bf16 v[0:3], v[184:187], v[218:221], v[0:3]
	s_setprio 0
	s_barrier
	s_add_i32 vcc_lo, vcc_lo, 2
	s_add_u32 s0, s0, 0x100
	s_addc_u32 s1, s1, 0
	s_add_u32 s96, s96, 0x100
	s_addc_u32 s97, s97, 0
	s_cmp_gt_u32 vcc_lo, 13
	s_cbranch_scc0 .LBB0_684
	s_and_b64 vcc, exec, s[18:19]
	s_cbranch_vccz .LBB0_687
	s_barrier

;     __host__ __device__ bool next(int i, Unit& u) const { const long L = (long)i * G + c; if (L >= nwg) return false; return unit_of((int)L, u); }
;     __host__ __device__ bool next(int i, Unit& u) const { const int L = i == 0 ? l0 : (i == 1 ? l1 : (i == 2 ? l2 : -1)); if (L < 0 || L >= s.nwg) return false; return s.unit_of(L, u); }
;     __host__ __device__ bool next(int i, Unit& u) const { const bool ok = s.next(i >> 1, u); u.kh = i & 1; return ok; }
; #define PG8_STAGE(bufoff, gbase, voff) do { _Pragma("unroll") for (int _i = 0; _i < 2; ++_i) \
;         __builtin_amdgcn_global_load_lds((const unsigned*)((const char*)(gbase) + (voff)[_i]), (PG8_LAS unsigned*)(lds + (bufoff) + ldsw + _i * 8192), 16, 0, 0); } while (0)
; #define PG8_WAIT_V(n) asm volatile("s_waitcnt vmcnt(" #n ")" ::: "memory")
; template <class Epi, class Sched, bool ALIGN_EPI = false, bool SP2 = false>
; __device__ __forceinline__ void gemm_phase(PG8_LAS unsigned char* lds, const Gemm g, const Sched& S, const Epi& E) {
;     ...
;         const bool has_next = S.next(ui + 1, nxt);
;         const char* nA = has_next ? (const char*)g.A + (size_t)nxt.pm * tstep + nxt.kh * khb : cA; const char* nB = has_next ? (const char*)g.Bt + (size_t)nxt.pn * tstep + nxt.kh * khb : cB;
;         for (int t = 0; t < nt; t += 2) {
;             const bool last = (t == nt - 2);
;             const char* a1 = cA + (size_t)(t + 1) * kstep;
;             const char* a2 = last ? nA : cA + (size_t)(t + 2) * kstep; const char* b2 = last ? nB : cB + (size_t)(t + 2) * kstep;
;             const char* a3 = a2 + kstep; const char* b3 = b2 + kstep;
;             if (last && has_next) S.a_ready(nxt);
;             if constexpr (SP2) {
;             PG8_LDB(B0, 0, 0); PG8_LDB(B1, 0, 1); PG8_SCHED; PG8_LDA(At, 0, 0); PG8_STAGE(PG8_SA(1, 1), a1 + hstep, voffA);
;             PG8_WAIT_V(8); PG8_WAIT_L(0); PG8_BAR; PG8_MMA(0, 0, At, B0); PG8_MMA(0, 1, At, B1); PG8_BAR; PG8_SCHED;
;             PG8_LDA(At, 0, 1); PG8_STAGE(PG8_SB(0, 0), b2, voffB); PG8_STAGE(PG8_SB(0, 1), b2 + hstep, voffB); PG8_STAGE(PG8_SA(0, 0), a2, voffA);
;     ...
;         for (int a = 0; a < 2; ++a)
; #pragma unroll
;             for (int b = 0; b < 2; ++b)
; #pragma unroll
;                 for (int m = 0; m < 4; ++m)
; #pragma unroll
;                     for (int n = 0; n < 2; ++n) acc[a][b][m][n] = (f32x4){0.f, 0.f, 0.f, 0.f};
.LBB0_881:
	s_ashr_i32 s23, s22, 31
	s_lshl_b64 s[24:25], s[22:23], 19
	s_add_u32 s24, s38, s24
	s_addc_u32 s25, s39, s25
	s_and_b64 s[26:27], s[4:5], exec
	s_cselect_b32 s23, s25, s31
	s_cselect_b32 s29, s24, s30
	s_ashr_i32 s21, s20, 31
	s_lshl_b64 s[26:27], s[20:21], 19
	s_add_u32 s26, s40, s26
	s_addc_u32 s27, s41, s27
	s_and_b64 s[36:37], s[4:5], exec
	s_cselect_b32 s21, s27, s35
	s_cselect_b32 s58, s26, s34
	s_add_u32 s30, s30, 0x40080
	s_addc_u32 s31, s31, 0
	s_add_u32 s59, s34, 0x100
	s_addc_u32 s60, s35, 0
	s_mov_b32 s61, -2
	s_waitcnt lgkmcnt(0)
	ds_read_b128 v[128:131], v173
	ds_read_b128 v[132:135], v173 offset:1024
	ds_read_b128 v[136:139], v173 offset:2048
	ds_read_b128 v[140:143], v173 offset:3072
	ds_read_b128 v[164:167], v174
	ds_read_b128 v[168:171], v174 offset:1024
	ds_read_b128 v[178:181], v174 offset:2048
	ds_read_b128 v[182:185], v174 offset:3072
	s_add_u32 s34, s30, 0xfffc0080
	s_addc_u32 s35, s31, -1
	s_cmp_eq_u32 s61, 12
	s_cselect_b32 s37, s23, s35
	s_cselect_b32 s36, s29, s34
	s_cselect_b32 s35, s21, s60
	s_cselect_b32 s34, s58, s59
	s_add_i32 m0, s43, 0xc000
	ds_read_b128 v[190:193], v175
	ds_read_b128 v[194:197], v175 offset:1024
	ds_read_b128 v[198:201], v175 offset:2048
	ds_read_b128 v[202:205], v175 offset:3072
	ds_read_b128 v[206:209], v175 offset:4096
	ds_read_b128 v[210:213], v175 offset:5120
	ds_read_b128 v[214:217], v175 offset:6144
	ds_read_b128 v[218:221], v175 offset:7168
	global_load_lds_dwordx4 v156, s[30:31]
	s_add_i32 m0, s43, 0xe000
	s_nop 0
	global_load_lds_dwordx4 v158, s[30:31]
	s_waitcnt vmcnt(8)
	s_waitcnt lgkmcnt(0)
	s_barrier
	s_setprio 1
	v_mfma_f32_16x16x32_bf16 v[124:127], v[128:131], v[190:193], 0
	v_mfma_f32_16x16x32_bf16 v[120:123], v[136:139], v[190:193], 0
	v_mfma_f32_16x16x32_bf16 v[108:111], v[128:131], v[198:201], 0
	v_mfma_f32_16x16x32_bf16 v[104:107], v[136:139], v[198:201], 0
	v_mfma_f32_16x16x32_bf16 v[92:95], v[128:131], v[206:209], 0
	v_mfma_f32_16x16x32_bf16 v[88:91], v[136:139], v[206:209], 0
	v_mfma_f32_16x16x32_bf16 v[76:79], v[128:131], v[214:217], 0
	v_mfma_f32_16x16x32_bf16 v[72:75], v[136:139], v[214:217], 0
	v_mfma_f32_16x16x32_bf16 v[124:127], v[132:135], v[194:197], v[124:127]
	v_mfma_f32_16x16x32_bf16 v[120:123], v[140:143], v[194:197], v[120:123]
	v_mfma_f32_16x16x32_bf16 v[108:111], v[132:135], v[202:205], v[108:111]
	v_mfma_f32_16x16x32_bf16 v[104:107], v[140:143], v[202:205], v[104:107]
	v_mfma_f32_16x16x32_bf16 v[92:95], v[132:135], v[210:213], v[92:95]
	v_mfma_f32_16x16x32_bf16 v[88:91], v[140:143], v[210:213], v[88:91]
	v_mfma_f32_16x16x32_bf16 v[76:79], v[132:135], v[218:221], v[76:79]
	v_mfma_f32_16x16x32_bf16 v[72:75], v[140:143], v[218:221], v[72:75]
	v_mfma_f32_16x16x32_bf16 v[116:119], v[164:167], v[190:193], 0
	v_mfma_f32_16x16x32_bf16 v[112:115], v[178:181], v[190:193], 0
	v_mfma_f32_16x16x32_bf16 v[100:103], v[164:167], v[198:201], 0
	v_mfma_f32_16x16x32_bf16 v[96:99], v[178:181], v[198:201], 0
	v_mfma_f32_16x16x32_bf16 v[84:87], v[164:167], v[206:209], 0
	v_mfma_f32_16x16x32_bf16 v[80:83], v[178:181], v[206:209], 0
	v_mfma_f32_16x16x32_bf16 v[68:71], v[164:167], v[214:217], 0
	v_mfma_f32_16x16x32_bf16 v[64:67], v[178:181], v[214:217], 0
	v_mfma_f32_16x16x32_bf16 v[116:119], v[168:171], v[194:197], v[116:119]
	v_mfma_f32_16x16x32_bf16 v[112:115], v[182:185], v[194:197], v[112:115]
	v_mfma_f32_16x16x32_bf16 v[100:103], v[168:171], v[202:205], v[100:103]
	v_mfma_f32_16x16x32_bf16 v[96:99], v[182:185], v[202:205], v[96:99]
	v_mfma_f32_16x16x32_bf16 v[84:87], v[168:171], v[210:213], v[84:87]
	v_mfma_f32_16x16x32_bf16 v[80:83], v[182:185], v[210:213], v[80:83]
	v_mfma_f32_16x16x32_bf16 v[68:71], v[168:171], v[218:221], v[68:71]
	v_mfma_f32_16x16x32_bf16 v[64:67], v[182:185], v[218:221], v[64:67]
	s_setprio 0
	s_barrier
	s_add_i32 s62, s55, s42
	v_lshl_add_u64 v[186:187], s[34:35], 0, v[146:147]
	s_mov_b32 m0, s62
	ds_read_b128 v[190:193], v175 offset:16384
	ds_read_b128 v[194:197], v175 offset:17408
	ds_read_b128 v[198:201], v175 offset:18432
	ds_read_b128 v[202:205], v175 offset:19456
	ds_read_b128 v[206:209], v175 offset:20480
	ds_read_b128 v[210:213], v175 offset:21504
	ds_read_b128 v[214:217], v175 offset:22528
	ds_read_b128 v[218:221], v175 offset:23552
	global_load_lds_dwordx4 v[186:187], off
	s_add_i32 m0, s62, 0x2000
	s_add_u32 s62, s34, 0x40000
	v_lshl_add_u64 v[222:223], s[34:35], 0, v[150:151]
	s_addc_u32 s63, s35, 0
	s_add_i32 s64, s56, s42
	global_load_lds_dwordx4 v[222:223], off
	s_mov_b32 m0, s64
	v_lshl_add_u64 v[226:227], s[36:37], 0, v[148:149]
	global_load_lds_dwordx4 v146, s[62:63]
	s_add_i32 m0, s64, 0x2000
	s_nop 0
	global_load_lds_dwordx4 v150, s[62:63]
	v_lshl_add_u64 v[224:225], s[36:37], 0, v[144:145]
	s_mov_b32 m0, s43
	s_nop 0
	global_load_lds_dwordx4 v[224:225], off
	s_mov_b32 m0, s44
	s_nop 0
	global_load_lds_dwordx4 v[226:227], off
	s_waitcnt vmcnt(8)
	s_waitcnt lgkmcnt(0)
	s_barrier
	s_setprio 1
	v_mfma_f32_16x16x32_bf16 v[60:63], v[128:131], v[190:193], 0
	v_mfma_f32_16x16x32_bf16 v[56:59], v[136:139], v[190:193], 0
	v_mfma_f32_16x16x32_bf16 v[44:47], v[128:131], v[198:201], 0
	v_mfma_f32_16x16x32_bf16 v[40:43], v[136:139], v[198:201], 0
	v_mfma_f32_16x16x32_bf16 v[28:31], v[128:131], v[206:209], 0
	v_mfma_f32_16x16x32_bf16 v[24:27], v[136:139], v[206:209], 0
	v_mfma_f32_16x16x32_bf16 v[12:15], v[128:131], v[214:217], 0
	v_mfma_f32_16x16x32_bf16 v[8:11], v[136:139], v[214:217], 0
	v_mfma_f32_16x16x32_bf16 v[60:63], v[132:135], v[194:197], v[60:63]
	v_mfma_f32_16x16x32_bf16 v[56:59], v[140:143], v[194:197], v[56:59]
	v_mfma_f32_16x16x32_bf16 v[44:47], v[132:135], v[202:205], v[44:47]
	v_mfma_f32_16x16x32_bf16 v[40:43], v[140:143], v[202:205], v[40:43]
	v_mfma_f32_16x16x32_bf16 v[28:31], v[132:135], v[210:213], v[28:31]
	v_mfma_f32_16x16x32_bf16 v[24:27], v[140:143], v[210:213], v[24:27]
	v_mfma_f32_16x16x32_bf16 v[12:15], v[132:135], v[218:221], v[12:15]
	v_mfma_f32_16x16x32_bf16 v[8:11], v[140:143], v[218:221], v[8:11]
	v_mfma_f32_16x16x32_bf16 v[52:55], v[164:167], v[190:193], 0
	v_mfma_f32_16x16x32_bf16 v[48:51], v[178:181], v[190:193], 0
	v_mfma_f32_16x16x32_bf16 v[36:39], v[164:167], v[198:201], 0
	v_mfma_f32_16x16x32_bf16 v[32:35], v[178:181], v[198:201], 0
	v_mfma_f32_16x16x32_bf16 v[20:23], v[164:167], v[206:209], 0
	v_mfma_f32_16x16x32_bf16 v[16:19], v[178:181], v[206:209], 0
	v_mfma_f32_16x16x32_bf16 v[4:7], v[164:167], v[214:217], 0
	v_mfma_f32_16x16x32_bf16 v[0:3], v[178:181], v[214:217], 0
	v_mfma_f32_16x16x32_bf16 v[52:55], v[168:171], v[194:197], v[52:55]
	v_mfma_f32_16x16x32_bf16 v[48:51], v[182:185], v[194:197], v[48:51]
	v_mfma_f32_16x16x32_bf16 v[36:39], v[168:171], v[202:205], v[36:39]
	v_mfma_f32_16x16x32_bf16 v[32:35], v[182:185], v[202:205], v[32:35]
	v_mfma_f32_16x16x32_bf16 v[20:23], v[168:171], v[210:213], v[20:23]
	v_mfma_f32_16x16x32_bf16 v[16:19], v[182:185], v[210:213], v[16:19]
	v_mfma_f32_16x16x32_bf16 v[4:7], v[168:171], v[218:221], v[4:7]
	v_mfma_f32_16x16x32_bf16 v[0:3], v[182:185], v[218:221], v[0:3]
	s_setprio 0
	s_barrier
	s_branch .Lmy_peel_882_mid
; #define PG8_STAGE(bufoff, gbase, voff) do { _Pragma("unroll") for (int _i = 0; _i < 2; ++_i) \
;         __builtin_amdgcn_global_load_lds((const unsigned*)((const char*)(gbase) + (voff)[_i]), (PG8_LAS unsigned*)(lds + (bufoff) + ldsw + _i * 8192), 16, 0, 0); } while (0)
; #define PG8_LDA(dst, b, h) do { _Pragma("unroll") for (int m = 0; m < 4; ++m) _Pragma("unroll") for (int k = 0; k < 2; ++k) dst[m][k] = *(const PG8_LAS bf16x8*)(lds + PG8_SA(b, h) + aoff + m * 2048 + k * 1024); } while (0)
; #define PG8_LDB(dst, b, h) do { _Pragma("unroll") for (int n = 0; n < 2; ++n) _Pragma("unroll") for (int k = 0; k < 2; ++k) dst[n][k] = *(const PG8_LAS bf16x8*)(lds + PG8_SB(b, h) + boff + n * 2048 + k * 1024); } while (0)
; #define PG8_MMA(ai, bj, At, Bt) do { __builtin_amdgcn_s_setprio(1); _Pragma("unroll") for (int m = 0; m < 4; ++m) _Pragma("unroll") for (int n = 0; n < 2; ++n) _Pragma("unroll") for (int k = 0; k < 2; ++k) \
;         acc[ai][bj][m][n] = __builtin_amdgcn_mfma_f32_16x16x32_bf16(Bt[n][k], At[m][k], acc[ai][bj][m][n], 0, 0, 0); __builtin_amdgcn_s_setprio(0); } while (0)
; #define PG8_WAIT_V(n) asm volatile("s_waitcnt vmcnt(" #n ")" ::: "memory")
; #define PG8_WAIT_L(n) asm volatile("s_waitcnt lgkmcnt(" #n ")" ::: "memory")
; #define PG8_BAR __builtin_amdgcn_s_barrier()
; #define PG8_SCHED __builtin_amdgcn_sched_barrier(0)
; template <class Epi, class Sched, bool ALIGN_EPI = false, bool SP2 = false>
; __device__ __forceinline__ void gemm_phase(PG8_LAS unsigned char* lds, const Gemm g, const Sched& S, const Epi& E) {
;     ...
;             PG8_LDB(B0, 0, 0); PG8_LDB(B1, 0, 1); PG8_SCHED; PG8_LDA(At, 0, 0); PG8_STAGE(PG8_SA(1, 1), a1 + hstep, voffA);
;             PG8_WAIT_V(8); PG8_WAIT_L(0); PG8_BAR; PG8_MMA(0, 0, At, B0); PG8_MMA(0, 1, At, B1); PG8_BAR; PG8_SCHED;
;             PG8_LDA(At, 0, 1); PG8_STAGE(PG8_SB(0, 0), b2, voffB); PG8_STAGE(PG8_SB(0, 1), b2 + hstep, voffB); PG8_STAGE(PG8_SA(0, 0), a2, voffA);
;             PG8_WAIT_V(8); PG8_WAIT_L(0); PG8_BAR; PG8_MMA(1, 0, At, B0); PG8_MMA(1, 1, At, B1); PG8_BAR; PG8_SCHED;
.LBB0_882:
	ds_read_b128 v[128:131], v173
	ds_read_b128 v[132:135], v173 offset:1024
	ds_read_b128 v[136:139], v173 offset:2048
	ds_read_b128 v[140:143], v173 offset:3072
	ds_read_b128 v[164:167], v174
	ds_read_b128 v[168:171], v174 offset:1024
	ds_read_b128 v[178:181], v174 offset:2048
	ds_read_b128 v[182:185], v174 offset:3072
	s_add_u32 s34, s30, 0xfffc0080
	s_addc_u32 s35, s31, -1
	s_cmp_eq_u32 s61, 12
	s_cselect_b32 s37, s23, s35
	s_cselect_b32 s36, s29, s34
	s_cselect_b32 s35, s21, s60
	s_cselect_b32 s34, s58, s59
	s_add_i32 m0, s43, 0xc000
	ds_read_b128 v[190:193], v175
	ds_read_b128 v[194:197], v175 offset:1024
	ds_read_b128 v[198:201], v175 offset:2048
	ds_read_b128 v[202:205], v175 offset:3072
	ds_read_b128 v[206:209], v175 offset:4096
	ds_read_b128 v[210:213], v175 offset:5120
	ds_read_b128 v[214:217], v175 offset:6144
	ds_read_b128 v[218:221], v175 offset:7168
	global_load_lds_dwordx4 v156, s[30:31]
	s_add_i32 m0, s43, 0xe000
	s_nop 0
	global_load_lds_dwordx4 v158, s[30:31]
	s_waitcnt vmcnt(8)
	s_waitcnt lgkmcnt(0)
	s_barrier
	s_setprio 1
	v_mfma_f32_16x16x32_bf16 v[124:127], v[128:131], v[190:193], v[124:127]
	v_mfma_f32_16x16x32_bf16 v[120:123], v[136:139], v[190:193], v[120:123]
	v_mfma_f32_16x16x32_bf16 v[108:111], v[128:131], v[198:201], v[108:111]
	v_mfma_f32_16x16x32_bf16 v[104:107], v[136:139], v[198:201], v[104:107]
	v_mfma_f32_16x16x32_bf16 v[92:95], v[128:131], v[206:209], v[92:95]
	v_mfma_f32_16x16x32_bf16 v[88:91], v[136:139], v[206:209], v[88:91]
	v_mfma_f32_16x16x32_bf16 v[76:79], v[128:131], v[214:217], v[76:79]
	v_mfma_f32_16x16x32_bf16 v[72:75], v[136:139], v[214:217], v[72:75]
	v_mfma_f32_16x16x32_bf16 v[124:127], v[132:135], v[194:197], v[124:127]
	v_mfma_f32_16x16x32_bf16 v[120:123], v[140:143], v[194:197], v[120:123]
	v_mfma_f32_16x16x32_bf16 v[108:111], v[132:135], v[202:205], v[108:111]
	v_mfma_f32_16x16x32_bf16 v[104:107], v[140:143], v[202:205], v[104:107]
	v_mfma_f32_16x16x32_bf16 v[92:95], v[132:135], v[210:213], v[92:95]
	v_mfma_f32_16x16x32_bf16 v[88:91], v[140:143], v[210:213], v[88:91]
	v_mfma_f32_16x16x32_bf16 v[76:79], v[132:135], v[218:221], v[76:79]
	v_mfma_f32_16x16x32_bf16 v[72:75], v[140:143], v[218:221], v[72:75]
	v_mfma_f32_16x16x32_bf16 v[116:119], v[164:167], v[190:193], v[116:119]
	v_mfma_f32_16x16x32_bf16 v[112:115], v[178:181], v[190:193], v[112:115]
	v_mfma_f32_16x16x32_bf16 v[100:103], v[164:167], v[198:201], v[100:103]
	v_mfma_f32_16x16x32_bf16 v[96:99], v[178:181], v[198:201], v[96:99]
	v_mfma_f32_16x16x32_bf16 v[84:87], v[164:167], v[206:209], v[84:87]
	v_mfma_f32_16x16x32_bf16 v[80:83], v[178:181], v[206:209], v[80:83]
	v_mfma_f32_16x16x32_bf16 v[68:71], v[164:167], v[214:217], v[68:71]
	v_mfma_f32_16x16x32_bf16 v[64:67], v[178:181], v[214:217], v[64:67]
	v_mfma_f32_16x16x32_bf16 v[116:119], v[168:171], v[194:197], v[116:119]
	v_mfma_f32_16x16x32_bf16 v[112:115], v[182:185], v[194:197], v[112:115]
	v_mfma_f32_16x16x32_bf16 v[100:103], v[168:171], v[202:205], v[100:103]
	v_mfma_f32_16x16x32_bf16 v[96:99], v[182:185], v[202:205], v[96:99]
	v_mfma_f32_16x16x32_bf16 v[84:87], v[168:171], v[210:213], v[84:87]
	v_mfma_f32_16x16x32_bf16 v[80:83], v[182:185], v[210:213], v[80:83]
	v_mfma_f32_16x16x32_bf16 v[68:71], v[168:171], v[218:221], v[68:71]
	v_mfma_f32_16x16x32_bf16 v[64:67], v[182:185], v[218:221], v[64:67]
	s_setprio 0
	s_barrier
	s_add_i32 s62, s55, s42
	v_lshl_add_u64 v[186:187], s[34:35], 0, v[146:147]
	s_mov_b32 m0, s62
	ds_read_b128 v[190:193], v175 offset:16384
	ds_read_b128 v[194:197], v175 offset:17408
	ds_read_b128 v[198:201], v175 offset:18432
	ds_read_b128 v[202:205], v175 offset:19456
	ds_read_b128 v[206:209], v175 offset:20480
	ds_read_b128 v[210:213], v175 offset:21504
	ds_read_b128 v[214:217], v175 offset:22528
	ds_read_b128 v[218:221], v175 offset:23552
	global_load_lds_dwordx4 v[186:187], off
	s_add_i32 m0, s62, 0x2000
	s_add_u32 s62, s34, 0x40000
	v_lshl_add_u64 v[222:223], s[34:35], 0, v[150:151]
	s_addc_u32 s63, s35, 0
	s_add_i32 s64, s56, s42
	global_load_lds_dwordx4 v[222:223], off
	s_mov_b32 m0, s64
	v_lshl_add_u64 v[226:227], s[36:37], 0, v[148:149]
	global_load_lds_dwordx4 v146, s[62:63]
	s_add_i32 m0, s64, 0x2000
	s_nop 0
	global_load_lds_dwordx4 v150, s[62:63]
	v_lshl_add_u64 v[224:225], s[36:37], 0, v[144:145]
	s_mov_b32 m0, s43
	s_nop 0
	global_load_lds_dwordx4 v[224:225], off
	s_mov_b32 m0, s44
	s_nop 0
	global_load_lds_dwordx4 v[226:227], off
	s_waitcnt vmcnt(8)
	s_waitcnt lgkmcnt(0)
	s_barrier
	s_setprio 1
	v_mfma_f32_16x16x32_bf16 v[60:63], v[128:131], v[190:193], v[60:63]
	v_mfma_f32_16x16x32_bf16 v[56:59], v[136:139], v[190:193], v[56:59]
	v_mfma_f32_16x16x32_bf16 v[44:47], v[128:131], v[198:201], v[44:47]
	v_mfma_f32_16x16x32_bf16 v[40:43], v[136:139], v[198:201], v[40:43]
	v_mfma_f32_16x16x32_bf16 v[28:31], v[128:131], v[206:209], v[28:31]
	v_mfma_f32_16x16x32_bf16 v[24:27], v[136:139], v[206:209], v[24:27]
	v_mfma_f32_16x16x32_bf16 v[12:15], v[128:131], v[214:217], v[12:15]
	v_mfma_f32_16x16x32_bf16 v[8:11], v[136:139], v[214:217], v[8:11]
	v_mfma_f32_16x16x32_bf16 v[60:63], v[132:135], v[194:197], v[60:63]
	v_mfma_f32_16x16x32_bf16 v[56:59], v[140:143], v[194:197], v[56:59]
	v_mfma_f32_16x16x32_bf16 v[44:47], v[132:135], v[202:205], v[44:47]
	v_mfma_f32_16x16x32_bf16 v[40:43], v[140:143], v[202:205], v[40:43]
	v_mfma_f32_16x16x32_bf16 v[28:31], v[132:135], v[210:213], v[28:31]
	v_mfma_f32_16x16x32_bf16 v[24:27], v[140:143], v[210:213], v[24:27]
	v_mfma_f32_16x16x32_bf16 v[12:15], v[132:135], v[218:221], v[12:15]
	v_mfma_f32_16x16x32_bf16 v[8:11], v[140:143], v[218:221], v[8:11]
	v_mfma_f32_16x16x32_bf16 v[52:55], v[164:167], v[190:193], v[52:55]
	v_mfma_f32_16x16x32_bf16 v[48:51], v[178:181], v[190:193], v[48:51]
	v_mfma_f32_16x16x32_bf16 v[36:39], v[164:167], v[198:201], v[36:39]
	v_mfma_f32_16x16x32_bf16 v[32:35], v[178:181], v[198:201], v[32:35]
	v_mfma_f32_16x16x32_bf16 v[20:23], v[164:167], v[206:209], v[20:23]
	v_mfma_f32_16x16x32_bf16 v[16:19], v[178:181], v[206:209], v[16:19]
	v_mfma_f32_16x16x32_bf16 v[4:7], v[164:167], v[214:217], v[4:7]
	v_mfma_f32_16x16x32_bf16 v[0:3], v[178:181], v[214:217], v[0:3]
	v_mfma_f32_16x16x32_bf16 v[52:55], v[168:171], v[194:197], v[52:55]
	v_mfma_f32_16x16x32_bf16 v[48:51], v[182:185], v[194:197], v[48:51]
	v_mfma_f32_16x16x32_bf16 v[36:39], v[168:171], v[202:205], v[36:39]
	v_mfma_f32_16x16x32_bf16 v[32:35], v[182:185], v[202:205], v[32:35]
	v_mfma_f32_16x16x32_bf16 v[20:23], v[168:171], v[210:213], v[20:23]
	v_mfma_f32_16x16x32_bf16 v[16:19], v[182:185], v[210:213], v[16:19]
	v_mfma_f32_16x16x32_bf16 v[4:7], v[168:171], v[218:221], v[4:7]
	v_mfma_f32_16x16x32_bf16 v[0:3], v[182:185], v[218:221], v[0:3]
	s_setprio 0
	s_barrier
; #define PG8_STAGE(bufoff, gbase, voff) do { _Pragma("unroll") for (int _i = 0; _i < 2; ++_i) \
;         __builtin_amdgcn_global_load_lds((const unsigned*)((const char*)(gbase) + (voff)[_i]), (PG8_LAS unsigned*)(lds + (bufoff) + ldsw + _i * 8192), 16, 0, 0); } while (0)
; #define PG8_LDA(dst, b, h) do { _Pragma("unroll") for (int m = 0; m < 4; ++m) _Pragma("unroll") for (int k = 0; k < 2; ++k) dst[m][k] = *(const PG8_LAS bf16x8*)(lds + PG8_SA(b, h) + aoff + m * 2048 + k * 1024); } while (0)
; #define PG8_LDB(dst, b, h) do { _Pragma("unroll") for (int n = 0; n < 2; ++n) _Pragma("unroll") for (int k = 0; k < 2; ++k) dst[n][k] = *(const PG8_LAS bf16x8*)(lds + PG8_SB(b, h) + boff + n * 2048 + k * 1024); } while (0)
; #define PG8_MMA(ai, bj, At, Bt) do { __builtin_amdgcn_s_setprio(1); _Pragma("unroll") for (int m = 0; m < 4; ++m) _Pragma("unroll") for (int n = 0; n < 2; ++n) _Pragma("unroll") for (int k = 0; k < 2; ++k) \
;         acc[ai][bj][m][n] = __builtin_amdgcn_mfma_f32_16x16x32_bf16(Bt[n][k], At[m][k], acc[ai][bj][m][n], 0, 0, 0); __builtin_amdgcn_s_setprio(0); } while (0)
; #define PG8_WAIT_V(n) asm volatile("s_waitcnt vmcnt(" #n ")" ::: "memory")
; #define PG8_WAIT_L(n) asm volatile("s_waitcnt lgkmcnt(" #n ")" ::: "memory")
; #define PG8_BAR __builtin_amdgcn_s_barrier()
; #define PG8_SCHED __builtin_amdgcn_sched_barrier(0)
; template <class Epi, class Sched, bool ALIGN_EPI = false, bool SP2 = false>
; __device__ __forceinline__ void gemm_phase(PG8_LAS unsigned char* lds, const Gemm g, const Sched& S, const Epi& E) {
;     ...
;         for (int t = 0; t < nt; t += 2) {
;     ...
;             PG8_LDB(B0, 1, 0); PG8_LDB(B1, 1, 1); PG8_SCHED; PG8_LDA(At, 1, 0); PG8_STAGE(PG8_SA(0, 1), a2 + hstep, voffA);
;             PG8_WAIT_V(8); PG8_WAIT_L(0); PG8_BAR; PG8_MMA(0, 0, At, B0); PG8_MMA(0, 1, At, B1); PG8_BAR; PG8_SCHED;
;             PG8_LDA(At, 1, 1); PG8_STAGE(PG8_SB(1, 0), b3, voffB); PG8_STAGE(PG8_SB(1, 1), b3 + hstep, voffB); PG8_STAGE(PG8_SA(1, 0), a3, voffA);
;             PG8_WAIT_V(8); PG8_WAIT_L(0); PG8_BAR; PG8_MMA(1, 0, At, B0); PG8_MMA(1, 1, At, B1); PG8_BAR; PG8_SCHED;
.Lmy_peel_882_mid:
	s_add_i32 s62, 0, 0x18000
	s_add_i32 s63, 0, 0x1c000
	v_add_u32_e32 v140, s62, v172
	v_add_u32_e32 v177, s63, v172
	ds_read_b128 v[128:131], v140
	ds_read_b128 v[132:135], v140 offset:1024
	ds_read_b128 v[136:139], v140 offset:2048
	ds_read_b128 v[140:143], v140 offset:3072
	ds_read_b128 v[164:167], v177
	ds_read_b128 v[168:171], v177 offset:1024
	ds_read_b128 v[178:181], v177 offset:2048
	ds_read_b128 v[182:185], v177 offset:3072
	s_add_u32 s36, s36, 0x40000
	s_addc_u32 s37, s37, 0
	s_mov_b32 m0, s45
	ds_read_b128 v[190:193], v175 offset:32768
	ds_read_b128 v[194:197], v175 offset:33792
	ds_read_b128 v[198:201], v175 offset:34816
	ds_read_b128 v[202:205], v175 offset:35840
	ds_read_b128 v[206:209], v175 offset:36864
	ds_read_b128 v[210:213], v175 offset:37888
	ds_read_b128 v[214:217], v175 offset:38912
	ds_read_b128 v[218:221], v175 offset:39936
	global_load_lds_dwordx4 v144, s[36:37]
	s_mov_b32 m0, s46
	s_nop 0
	global_load_lds_dwordx4 v148, s[36:37]
	s_waitcnt vmcnt(8)
	s_waitcnt lgkmcnt(0)
	s_barrier
	s_setprio 1
	v_mfma_f32_16x16x32_bf16 v[124:127], v[128:131], v[190:193], v[124:127]
	v_mfma_f32_16x16x32_bf16 v[120:123], v[136:139], v[190:193], v[120:123]
	v_mfma_f32_16x16x32_bf16 v[108:111], v[128:131], v[198:201], v[108:111]
	v_mfma_f32_16x16x32_bf16 v[104:107], v[136:139], v[198:201], v[104:107]
	v_mfma_f32_16x16x32_bf16 v[92:95], v[128:131], v[206:209], v[92:95]
	v_mfma_f32_16x16x32_bf16 v[88:91], v[136:139], v[206:209], v[88:91]
	v_mfma_f32_16x16x32_bf16 v[76:79], v[128:131], v[214:217], v[76:79]
	v_mfma_f32_16x16x32_bf16 v[72:75], v[136:139], v[214:217], v[72:75]
	v_mfma_f32_16x16x32_bf16 v[124:127], v[132:135], v[194:197], v[124:127]
	v_mfma_f32_16x16x32_bf16 v[120:123], v[140:143], v[194:197], v[120:123]
	v_mfma_f32_16x16x32_bf16 v[108:111], v[132:135], v[202:205], v[108:111]
	v_mfma_f32_16x16x32_bf16 v[104:107], v[140:143], v[202:205], v[104:107]
	v_mfma_f32_16x16x32_bf16 v[92:95], v[132:135], v[210:213], v[92:95]
	v_mfma_f32_16x16x32_bf16 v[88:91], v[140:143], v[210:213], v[88:91]
	v_mfma_f32_16x16x32_bf16 v[76:79], v[132:135], v[218:221], v[76:79]
	v_mfma_f32_16x16x32_bf16 v[72:75], v[140:143], v[218:221], v[72:75]
	v_mfma_f32_16x16x32_bf16 v[116:119], v[164:167], v[190:193], v[116:119]
	v_mfma_f32_16x16x32_bf16 v[112:115], v[178:181], v[190:193], v[112:115]
	v_mfma_f32_16x16x32_bf16 v[100:103], v[164:167], v[198:201], v[100:103]
	v_mfma_f32_16x16x32_bf16 v[96:99], v[178:181], v[198:201], v[96:99]
	v_mfma_f32_16x16x32_bf16 v[84:87], v[164:167], v[206:209], v[84:87]
	v_mfma_f32_16x16x32_bf16 v[80:83], v[178:181], v[206:209], v[80:83]
	v_mfma_f32_16x16x32_bf16 v[68:71], v[164:167], v[214:217], v[68:71]
	v_mfma_f32_16x16x32_bf16 v[64:67], v[178:181], v[214:217], v[64:67]
	v_mfma_f32_16x16x32_bf16 v[116:119], v[168:171], v[194:197], v[116:119]
	v_mfma_f32_16x16x32_bf16 v[112:115], v[182:185], v[194:197], v[112:115]
	v_mfma_f32_16x16x32_bf16 v[100:103], v[168:171], v[202:205], v[100:103]
	v_mfma_f32_16x16x32_bf16 v[96:99], v[182:185], v[202:205], v[96:99]
	v_mfma_f32_16x16x32_bf16 v[84:87], v[168:171], v[210:213], v[84:87]
	v_mfma_f32_16x16x32_bf16 v[80:83], v[182:185], v[210:213], v[80:83]
	v_mfma_f32_16x16x32_bf16 v[68:71], v[168:171], v[218:221], v[68:71]
	v_mfma_f32_16x16x32_bf16 v[64:67], v[182:185], v[218:221], v[64:67]
	s_setprio 0
	s_barrier
	s_add_i32 s36, s62, s42
	v_lshl_add_u64 v[186:187], v[186:187], 0, s[16:17]
	s_mov_b32 m0, s36
	ds_read_b128 v[190:193], v175 offset:49152
	ds_read_b128 v[194:197], v175 offset:50176
	ds_read_b128 v[198:201], v175 offset:51200
	ds_read_b128 v[202:205], v175 offset:52224
	ds_read_b128 v[206:209], v175 offset:53248
	ds_read_b128 v[210:213], v175 offset:54272
	ds_read_b128 v[214:217], v175 offset:55296
	ds_read_b128 v[218:221], v175 offset:56320
	global_load_lds_dwordx4 v[186:187], off
	s_add_i32 m0, s36, 0x2000
	s_add_u32 s34, s34, 0x40080
	v_lshl_add_u64 v[186:187], v[222:223], 0, s[16:17]
	s_addc_u32 s35, s35, 0
	s_add_i32 s36, s63, s42
	global_load_lds_dwordx4 v[186:187], off
	s_mov_b32 m0, s36
	s_nop 0
	global_load_lds_dwordx4 v146, s[34:35]
	s_add_i32 m0, s36, 0x2000
	s_nop 0
	global_load_lds_dwordx4 v150, s[34:35]
	v_lshl_add_u64 v[186:187], v[224:225], 0, s[16:17]
	s_mov_b32 m0, s48
	s_nop 0
	global_load_lds_dwordx4 v[186:187], off
	v_lshl_add_u64 v[186:187], v[226:227], 0, s[16:17]
	s_mov_b32 m0, s49
	s_nop 0
	global_load_lds_dwordx4 v[186:187], off
	s_waitcnt vmcnt(8)
	s_waitcnt lgkmcnt(0)
	s_barrier
	s_setprio 1
	v_mfma_f32_16x16x32_bf16 v[60:63], v[128:131], v[190:193], v[60:63]
	v_mfma_f32_16x16x32_bf16 v[56:59], v[136:139], v[190:193], v[56:59]
	v_mfma_f32_16x16x32_bf16 v[44:47], v[128:131], v[198:201], v[44:47]
	v_mfma_f32_16x16x32_bf16 v[40:43], v[136:139], v[198:201], v[40:43]
	v_mfma_f32_16x16x32_bf16 v[28:31], v[128:131], v[206:209], v[28:31]
	v_mfma_f32_16x16x32_bf16 v[24:27], v[136:139], v[206:209], v[24:27]
	v_mfma_f32_16x16x32_bf16 v[12:15], v[128:131], v[214:217], v[12:15]
	v_mfma_f32_16x16x32_bf16 v[8:11], v[136:139], v[214:217], v[8:11]
	v_mfma_f32_16x16x32_bf16 v[60:63], v[132:135], v[194:197], v[60:63]
	v_mfma_f32_16x16x32_bf16 v[56:59], v[140:143], v[194:197], v[56:59]
	v_mfma_f32_16x16x32_bf16 v[44:47], v[132:135], v[202:205], v[44:47]
	v_mfma_f32_16x16x32_bf16 v[40:43], v[140:143], v[202:205], v[40:43]
	v_mfma_f32_16x16x32_bf16 v[28:31], v[132:135], v[210:213], v[28:31]
	v_mfma_f32_16x16x32_bf16 v[24:27], v[140:143], v[210:213], v[24:27]
	v_mfma_f32_16x16x32_bf16 v[12:15], v[132:135], v[218:221], v[12:15]
	v_mfma_f32_16x16x32_bf16 v[8:11], v[140:143], v[218:221], v[8:11]
	v_mfma_f32_16x16x32_bf16 v[52:55], v[164:167], v[190:193], v[52:55]
	v_mfma_f32_16x16x32_bf16 v[48:51], v[178:181], v[190:193], v[48:51]
	v_mfma_f32_16x16x32_bf16 v[36:39], v[164:167], v[198:201], v[36:39]
	v_mfma_f32_16x16x32_bf16 v[32:35], v[178:181], v[198:201], v[32:35]
	v_mfma_f32_16x16x32_bf16 v[20:23], v[164:167], v[206:209], v[20:23]
	v_mfma_f32_16x16x32_bf16 v[16:19], v[178:181], v[206:209], v[16:19]
	v_mfma_f32_16x16x32_bf16 v[4:7], v[164:167], v[214:217], v[4:7]
	v_mfma_f32_16x16x32_bf16 v[0:3], v[178:181], v[214:217], v[0:3]
	v_mfma_f32_16x16x32_bf16 v[52:55], v[168:171], v[194:197], v[52:55]
	v_mfma_f32_16x16x32_bf16 v[48:51], v[182:185], v[194:197], v[48:51]
	v_mfma_f32_16x16x32_bf16 v[36:39], v[168:171], v[202:205], v[36:39]
	v_mfma_f32_16x16x32_bf16 v[32:35], v[182:185], v[202:205], v[32:35]
	v_mfma_f32_16x16x32_bf16 v[20:23], v[168:171], v[210:213], v[20:23]
	v_mfma_f32_16x16x32_bf16 v[16:19], v[182:185], v[210:213], v[16:19]
	v_mfma_f32_16x16x32_bf16 v[4:7], v[168:171], v[218:221], v[4:7]
	v_mfma_f32_16x16x32_bf16 v[0:3], v[182:185], v[218:221], v[0:3]
	s_setprio 0
	s_barrier
	s_add_i32 s61, s61, 2
	s_add_u32 s30, s30, 0x100
	s_addc_u32 s31, s31, 0
	s_add_u32 s59, s59, 0x100
	s_addc_u32 s60, s60, 0
	s_cmp_gt_u32 s61, 13
	s_cbranch_scc0 .LBB0_882
	s_and_b64 vcc, exec, s[18:19]
	s_cbranch_vccz .LBB0_885
	s_barrier

;     __host__ __device__ bool next(int i, Unit& u) const { const long L = (long)i * G + c; if (L >= nwg) return false; return unit_of((int)L, u); }
;     __host__ __device__ bool next(int i, Unit& u) const { const int L = i == 0 ? l0 : (i == 1 ? l1 : (i == 2 ? l2 : -1)); if (L < 0 || L >= s.nwg) return false; return s.unit_of(L, u); }
;     __host__ __device__ bool next(int i, Unit& u) const { const bool ok = s.next(i >> 1, u); u.kh = i & 1; return ok; }
; #define PG8_STAGE(bufoff, gbase, voff) do { _Pragma("unroll") for (int _i = 0; _i < 2; ++_i) \
;         __builtin_amdgcn_global_load_lds((const unsigned*)((const char*)(gbase) + (voff)[_i]), (PG8_LAS unsigned*)(lds + (bufoff) + ldsw + _i * 8192), 16, 0, 0); } while (0)
; #define PG8_WAIT_V(n) asm volatile("s_waitcnt vmcnt(" #n ")" ::: "memory")
; template <class Epi, class Sched, bool ALIGN_EPI = false, bool SP2 = false>
; __device__ __forceinline__ void gemm_phase(PG8_LAS unsigned char* lds, const Gemm g, const Sched& S, const Epi& E) {
;     ...
;         const bool has_next = S.next(ui + 1, nxt);
;         const char* nA = has_next ? (const char*)g.A + (size_t)nxt.pm * tstep + nxt.kh * khb : cA; const char* nB = has_next ? (const char*)g.Bt + (size_t)nxt.pn * tstep + nxt.kh * khb : cB;
;         for (int t = 0; t < nt; t += 2) {
;             const bool last = (t == nt - 2);
;             const char* a1 = cA + (size_t)(t + 1) * kstep;
;             const char* a2 = last ? nA : cA + (size_t)(t + 2) * kstep; const char* b2 = last ? nB : cB + (size_t)(t + 2) * kstep;
;             const char* a3 = a2 + kstep; const char* b3 = b2 + kstep;
;             if (last && has_next) S.a_ready(nxt);
;             if constexpr (SP2) {
;             PG8_LDB(B0, 0, 0); PG8_LDB(B1, 0, 1); PG8_SCHED; PG8_LDA(At, 0, 0); PG8_STAGE(PG8_SA(1, 1), a1 + hstep, voffA);
;             PG8_WAIT_V(8); PG8_WAIT_L(0); PG8_BAR; PG8_MMA(0, 0, At, B0); PG8_MMA(0, 1, At, B1); PG8_BAR; PG8_SCHED;
;             PG8_LDA(At, 0, 1); PG8_STAGE(PG8_SB(0, 0), b2, voffB); PG8_STAGE(PG8_SB(0, 1), b2 + hstep, voffB); PG8_STAGE(PG8_SA(0, 0), a2, voffA);
;     ...
;         for (int a = 0; a < 2; ++a)
; #pragma unroll
;             for (int b = 0; b < 2; ++b)
; #pragma unroll
;                 for (int m = 0; m < 4; ++m)
; #pragma unroll
;                     for (int n = 0; n < 2; ++n) acc[a][b][m][n] = (f32x4){0.f, 0.f, 0.f, 0.f};
.LBB0_968:
	s_ashr_i32 s17, s16, 31
	s_lshl_b64 s[18:19], s[16:17], 19
	s_add_u32 s18, s30, s18
	s_addc_u32 s19, s31, s19
	s_and_b64 s[20:21], s[2:3], exec
	s_cselect_b32 s17, s19, s25
	s_cselect_b32 s51, s18, s24
	s_ashr_i32 s15, s14, 31
	s_lshl_b64 s[20:21], s[14:15], 19
	s_add_u32 s20, s34, s20
	s_addc_u32 s21, s35, s21
	s_and_b64 s[28:29], s[2:3], exec
	s_cselect_b32 s15, s21, s27
	s_cselect_b32 s54, s20, s26
	s_add_u32 s24, s24, 0x40080
	s_addc_u32 s25, s25, 0
	s_add_u32 s55, s26, 0x100
	s_addc_u32 s56, s27, 0
	s_mov_b32 s57, -2
	ds_read_b128 v[128:131], v191
	ds_read_b128 v[132:135], v191 offset:1024
	ds_read_b128 v[136:139], v191 offset:2048
	ds_read_b128 v[140:143], v191 offset:3072
	ds_read_b128 v[144:147], v192
	ds_read_b128 v[148:151], v192 offset:1024
	ds_read_b128 v[172:175], v192 offset:2048
	ds_read_b128 v[176:179], v192 offset:3072
	s_add_u32 s26, s24, 0xfffc0080
	s_addc_u32 s27, s25, -1
	s_cmp_eq_u32 s57, 12
	s_cselect_b32 s29, s17, s27
	s_cselect_b32 s28, s51, s26
	s_cselect_b32 s27, s15, s56
	s_cselect_b32 s26, s54, s55
	s_add_i32 m0, s39, 0xc000
	ds_read_b128 v[180:183], v193
	ds_read_b128 v[184:187], v193 offset:1024
	ds_read_b128 v[196:199], v193 offset:2048
	ds_read_b128 v[200:203], v193 offset:3072
	ds_read_b128 v[204:207], v193 offset:4096
	ds_read_b128 v[208:211], v193 offset:5120
	ds_read_b128 v[212:215], v193 offset:6144
	ds_read_b128 v[216:219], v193 offset:7168
	global_load_lds_dwordx4 v164, s[24:25]
	s_add_i32 m0, s39, 0xe000
	s_nop 0
	global_load_lds_dwordx4 v166, s[24:25]
	s_waitcnt vmcnt(8)
	s_waitcnt lgkmcnt(0)
	s_barrier
	s_setprio 1
	v_mfma_f32_16x16x32_bf16 v[124:127], v[128:131], v[180:183], 0
	v_mfma_f32_16x16x32_bf16 v[120:123], v[136:139], v[180:183], 0
	v_mfma_f32_16x16x32_bf16 v[108:111], v[128:131], v[196:199], 0
	v_mfma_f32_16x16x32_bf16 v[104:107], v[136:139], v[196:199], 0
	v_mfma_f32_16x16x32_bf16 v[92:95], v[128:131], v[204:207], 0
	v_mfma_f32_16x16x32_bf16 v[84:87], v[136:139], v[204:207], 0
	v_mfma_f32_16x16x32_bf16 v[76:79], v[128:131], v[212:215], 0
	v_mfma_f32_16x16x32_bf16 v[72:75], v[136:139], v[212:215], 0
	v_mfma_f32_16x16x32_bf16 v[124:127], v[132:135], v[184:187], v[124:127]
	v_mfma_f32_16x16x32_bf16 v[120:123], v[140:143], v[184:187], v[120:123]
	v_mfma_f32_16x16x32_bf16 v[108:111], v[132:135], v[200:203], v[108:111]
	v_mfma_f32_16x16x32_bf16 v[104:107], v[140:143], v[200:203], v[104:107]
	v_mfma_f32_16x16x32_bf16 v[92:95], v[132:135], v[208:211], v[92:95]
	v_mfma_f32_16x16x32_bf16 v[84:87], v[140:143], v[208:211], v[84:87]
	v_mfma_f32_16x16x32_bf16 v[76:79], v[132:135], v[216:219], v[76:79]
	v_mfma_f32_16x16x32_bf16 v[72:75], v[140:143], v[216:219], v[72:75]
	v_mfma_f32_16x16x32_bf16 v[116:119], v[144:147], v[180:183], 0
	v_mfma_f32_16x16x32_bf16 v[112:115], v[172:175], v[180:183], 0
	v_mfma_f32_16x16x32_bf16 v[100:103], v[144:147], v[196:199], 0
	v_mfma_f32_16x16x32_bf16 v[96:99], v[172:175], v[196:199], 0
	v_mfma_f32_16x16x32_bf16 v[88:91], v[144:147], v[204:207], 0
	v_mfma_f32_16x16x32_bf16 v[80:83], v[172:175], v[204:207], 0
	v_mfma_f32_16x16x32_bf16 v[68:71], v[144:147], v[212:215], 0
	v_mfma_f32_16x16x32_bf16 v[64:67], v[172:175], v[212:215], 0
	v_mfma_f32_16x16x32_bf16 v[116:119], v[148:151], v[184:187], v[116:119]
	v_mfma_f32_16x16x32_bf16 v[112:115], v[176:179], v[184:187], v[112:115]
	v_mfma_f32_16x16x32_bf16 v[100:103], v[148:151], v[200:203], v[100:103]
	v_mfma_f32_16x16x32_bf16 v[96:99], v[176:179], v[200:203], v[96:99]
	v_mfma_f32_16x16x32_bf16 v[88:91], v[148:151], v[208:211], v[88:91]
	v_mfma_f32_16x16x32_bf16 v[80:83], v[176:179], v[208:211], v[80:83]
	v_mfma_f32_16x16x32_bf16 v[68:71], v[148:151], v[216:219], v[68:71]
	v_mfma_f32_16x16x32_bf16 v[64:67], v[176:179], v[216:219], v[64:67]
	s_setprio 0
	s_barrier
	s_add_i32 s58, s47, s36
	v_lshl_add_u64 v[220:221], s[26:27], 0, v[156:157]
	s_mov_b32 m0, s58
	ds_read_b128 v[180:183], v193 offset:16384
	ds_read_b128 v[184:187], v193 offset:17408
	ds_read_b128 v[196:199], v193 offset:18432
	ds_read_b128 v[200:203], v193 offset:19456
	ds_read_b128 v[204:207], v193 offset:20480
	ds_read_b128 v[208:211], v193 offset:21504
	ds_read_b128 v[212:215], v193 offset:22528
	ds_read_b128 v[216:219], v193 offset:23552
	global_load_lds_dwordx4 v[220:221], off
	s_add_i32 m0, s58, 0x2000
	s_add_u32 s58, s26, 0x40000
	v_lshl_add_u64 v[222:223], s[26:27], 0, v[152:153]
	s_addc_u32 s59, s27, 0
	s_add_i32 s60, s48, s36
	global_load_lds_dwordx4 v[222:223], off
	s_mov_b32 m0, s60
	v_lshl_add_u64 v[226:227], s[28:29], 0, v[154:155]
	global_load_lds_dwordx4 v156, s[58:59]
	s_add_i32 m0, s60, 0x2000
	s_nop 0
	global_load_lds_dwordx4 v152, s[58:59]
	v_lshl_add_u64 v[224:225], s[28:29], 0, v[158:159]
	s_mov_b32 m0, s39
	s_nop 0
	global_load_lds_dwordx4 v[224:225], off
	s_mov_b32 m0, s40
	s_nop 0
	global_load_lds_dwordx4 v[226:227], off
	s_waitcnt vmcnt(8)
	s_waitcnt lgkmcnt(0)
	s_barrier
	s_setprio 1
	v_mfma_f32_16x16x32_bf16 v[60:63], v[128:131], v[180:183], 0
	v_mfma_f32_16x16x32_bf16 v[52:55], v[136:139], v[180:183], 0
	v_mfma_f32_16x16x32_bf16 v[44:47], v[128:131], v[196:199], 0
	v_mfma_f32_16x16x32_bf16 v[40:43], v[136:139], v[196:199], 0
	v_mfma_f32_16x16x32_bf16 v[28:31], v[128:131], v[204:207], 0
	v_mfma_f32_16x16x32_bf16 v[20:23], v[136:139], v[204:207], 0
	v_mfma_f32_16x16x32_bf16 v[12:15], v[128:131], v[212:215], 0
	v_mfma_f32_16x16x32_bf16 v[8:11], v[136:139], v[212:215], 0
	v_mfma_f32_16x16x32_bf16 v[60:63], v[132:135], v[184:187], v[60:63]
	v_mfma_f32_16x16x32_bf16 v[52:55], v[140:143], v[184:187], v[52:55]
	v_mfma_f32_16x16x32_bf16 v[44:47], v[132:135], v[200:203], v[44:47]
	v_mfma_f32_16x16x32_bf16 v[40:43], v[140:143], v[200:203], v[40:43]
	v_mfma_f32_16x16x32_bf16 v[28:31], v[132:135], v[208:211], v[28:31]
	v_mfma_f32_16x16x32_bf16 v[20:23], v[140:143], v[208:211], v[20:23]
	v_mfma_f32_16x16x32_bf16 v[12:15], v[132:135], v[216:219], v[12:15]
	v_mfma_f32_16x16x32_bf16 v[8:11], v[140:143], v[216:219], v[8:11]
	v_mfma_f32_16x16x32_bf16 v[56:59], v[144:147], v[180:183], 0
	v_mfma_f32_16x16x32_bf16 v[48:51], v[172:175], v[180:183], 0
	v_mfma_f32_16x16x32_bf16 v[36:39], v[144:147], v[196:199], 0
	v_mfma_f32_16x16x32_bf16 v[32:35], v[172:175], v[196:199], 0
	v_mfma_f32_16x16x32_bf16 v[24:27], v[144:147], v[204:207], 0
	v_mfma_f32_16x16x32_bf16 v[16:19], v[172:175], v[204:207], 0
	v_mfma_f32_16x16x32_bf16 v[4:7], v[144:147], v[212:215], 0
	v_mfma_f32_16x16x32_bf16 v[0:3], v[172:175], v[212:215], 0
	v_mfma_f32_16x16x32_bf16 v[56:59], v[148:151], v[184:187], v[56:59]
	v_mfma_f32_16x16x32_bf16 v[48:51], v[176:179], v[184:187], v[48:51]
	v_mfma_f32_16x16x32_bf16 v[36:39], v[148:151], v[200:203], v[36:39]
	v_mfma_f32_16x16x32_bf16 v[32:35], v[176:179], v[200:203], v[32:35]
	v_mfma_f32_16x16x32_bf16 v[24:27], v[148:151], v[208:211], v[24:27]
	v_mfma_f32_16x16x32_bf16 v[16:19], v[176:179], v[208:211], v[16:19]
	v_mfma_f32_16x16x32_bf16 v[4:7], v[148:151], v[216:219], v[4:7]
	v_mfma_f32_16x16x32_bf16 v[0:3], v[176:179], v[216:219], v[0:3]
	s_setprio 0
	s_barrier
	s_branch .Lmy_peel_969_mid
; #define PG8_STAGE(bufoff, gbase, voff) do { _Pragma("unroll") for (int _i = 0; _i < 2; ++_i) \
;         __builtin_amdgcn_global_load_lds((const unsigned*)((const char*)(gbase) + (voff)[_i]), (PG8_LAS unsigned*)(lds + (bufoff) + ldsw + _i * 8192), 16, 0, 0); } while (0)
; #define PG8_LDA(dst, b, h) do { _Pragma("unroll") for (int m = 0; m < 4; ++m) _Pragma("unroll") for (int k = 0; k < 2; ++k) dst[m][k] = *(const PG8_LAS bf16x8*)(lds + PG8_SA(b, h) + aoff + m * 2048 + k * 1024); } while (0)
; #define PG8_LDB(dst, b, h) do { _Pragma("unroll") for (int n = 0; n < 2; ++n) _Pragma("unroll") for (int k = 0; k < 2; ++k) dst[n][k] = *(const PG8_LAS bf16x8*)(lds + PG8_SB(b, h) + boff + n * 2048 + k * 1024); } while (0)
; #define PG8_MMA(ai, bj, At, Bt) do { __builtin_amdgcn_s_setprio(1); _Pragma("unroll") for (int m = 0; m < 4; ++m) _Pragma("unroll") for (int n = 0; n < 2; ++n) _Pragma("unroll") for (int k = 0; k < 2; ++k) \
;         acc[ai][bj][m][n] = __builtin_amdgcn_mfma_f32_16x16x32_bf16(Bt[n][k], At[m][k], acc[ai][bj][m][n], 0, 0, 0); __builtin_amdgcn_s_setprio(0); } while (0)
; #define PG8_WAIT_V(n) asm volatile("s_waitcnt vmcnt(" #n ")" ::: "memory")
; #define PG8_WAIT_L(n) asm volatile("s_waitcnt lgkmcnt(" #n ")" ::: "memory")
; #define PG8_BAR __builtin_amdgcn_s_barrier()
; #define PG8_SCHED __builtin_amdgcn_sched_barrier(0)
; template <class Epi, class Sched, bool ALIGN_EPI = false, bool SP2 = false>
; __device__ __forceinline__ void gemm_phase(PG8_LAS unsigned char* lds, const Gemm g, const Sched& S, const Epi& E) {
;     ...
;             PG8_LDB(B0, 0, 0); PG8_LDB(B1, 0, 1); PG8_SCHED; PG8_LDA(At, 0, 0); PG8_STAGE(PG8_SA(1, 1), a1 + hstep, voffA);
;             PG8_WAIT_V(8); PG8_WAIT_L(0); PG8_BAR; PG8_MMA(0, 0, At, B0); PG8_MMA(0, 1, At, B1); PG8_BAR; PG8_SCHED;
;             PG8_LDA(At, 0, 1); PG8_STAGE(PG8_SB(0, 0), b2, voffB); PG8_STAGE(PG8_SB(0, 1), b2 + hstep, voffB); PG8_STAGE(PG8_SA(0, 0), a2, voffA);
;             PG8_WAIT_V(8); PG8_WAIT_L(0); PG8_BAR; PG8_MMA(1, 0, At, B0); PG8_MMA(1, 1, At, B1); PG8_BAR; PG8_SCHED;
.LBB0_969:
	ds_read_b128 v[128:131], v191
	ds_read_b128 v[132:135], v191 offset:1024
	ds_read_b128 v[136:139], v191 offset:2048
	ds_read_b128 v[140:143], v191 offset:3072
	ds_read_b128 v[144:147], v192
	ds_read_b128 v[148:151], v192 offset:1024
	ds_read_b128 v[172:175], v192 offset:2048
	ds_read_b128 v[176:179], v192 offset:3072
	s_add_u32 s26, s24, 0xfffc0080
	s_addc_u32 s27, s25, -1
	s_cmp_eq_u32 s57, 12
	s_cselect_b32 s29, s17, s27
	s_cselect_b32 s28, s51, s26
	s_cselect_b32 s27, s15, s56
	s_cselect_b32 s26, s54, s55
	s_add_i32 m0, s39, 0xc000
	ds_read_b128 v[180:183], v193
	ds_read_b128 v[184:187], v193 offset:1024
	ds_read_b128 v[196:199], v193 offset:2048
	ds_read_b128 v[200:203], v193 offset:3072
	ds_read_b128 v[204:207], v193 offset:4096
	ds_read_b128 v[208:211], v193 offset:5120
	ds_read_b128 v[212:215], v193 offset:6144
	ds_read_b128 v[216:219], v193 offset:7168
	global_load_lds_dwordx4 v164, s[24:25]
	s_add_i32 m0, s39, 0xe000
	s_nop 0
	global_load_lds_dwordx4 v166, s[24:25]
	s_waitcnt vmcnt(8)
	s_waitcnt lgkmcnt(0)
	s_barrier
	s_setprio 1
	v_mfma_f32_16x16x32_bf16 v[124:127], v[128:131], v[180:183], v[124:127]
	v_mfma_f32_16x16x32_bf16 v[120:123], v[136:139], v[180:183], v[120:123]
	v_mfma_f32_16x16x32_bf16 v[108:111], v[128:131], v[196:199], v[108:111]
	v_mfma_f32_16x16x32_bf16 v[104:107], v[136:139], v[196:199], v[104:107]
	v_mfma_f32_16x16x32_bf16 v[92:95], v[128:131], v[204:207], v[92:95]
	v_mfma_f32_16x16x32_bf16 v[84:87], v[136:139], v[204:207], v[84:87]
	v_mfma_f32_16x16x32_bf16 v[76:79], v[128:131], v[212:215], v[76:79]
	v_mfma_f32_16x16x32_bf16 v[72:75], v[136:139], v[212:215], v[72:75]
	v_mfma_f32_16x16x32_bf16 v[124:127], v[132:135], v[184:187], v[124:127]
	v_mfma_f32_16x16x32_bf16 v[120:123], v[140:143], v[184:187], v[120:123]
	v_mfma_f32_16x16x32_bf16 v[108:111], v[132:135], v[200:203], v[108:111]
	v_mfma_f32_16x16x32_bf16 v[104:107], v[140:143], v[200:203], v[104:107]
	v_mfma_f32_16x16x32_bf16 v[92:95], v[132:135], v[208:211], v[92:95]
	v_mfma_f32_16x16x32_bf16 v[84:87], v[140:143], v[208:211], v[84:87]
	v_mfma_f32_16x16x32_bf16 v[76:79], v[132:135], v[216:219], v[76:79]
	v_mfma_f32_16x16x32_bf16 v[72:75], v[140:143], v[216:219], v[72:75]
	v_mfma_f32_16x16x32_bf16 v[116:119], v[144:147], v[180:183], v[116:119]
	v_mfma_f32_16x16x32_bf16 v[112:115], v[172:175], v[180:183], v[112:115]
	v_mfma_f32_16x16x32_bf16 v[100:103], v[144:147], v[196:199], v[100:103]
	v_mfma_f32_16x16x32_bf16 v[96:99], v[172:175], v[196:199], v[96:99]
	v_mfma_f32_16x16x32_bf16 v[88:91], v[144:147], v[204:207], v[88:91]
	v_mfma_f32_16x16x32_bf16 v[80:83], v[172:175], v[204:207], v[80:83]
	v_mfma_f32_16x16x32_bf16 v[68:71], v[144:147], v[212:215], v[68:71]
	v_mfma_f32_16x16x32_bf16 v[64:67], v[172:175], v[212:215], v[64:67]
	v_mfma_f32_16x16x32_bf16 v[116:119], v[148:151], v[184:187], v[116:119]
	v_mfma_f32_16x16x32_bf16 v[112:115], v[176:179], v[184:187], v[112:115]
	v_mfma_f32_16x16x32_bf16 v[100:103], v[148:151], v[200:203], v[100:103]
	v_mfma_f32_16x16x32_bf16 v[96:99], v[176:179], v[200:203], v[96:99]
	v_mfma_f32_16x16x32_bf16 v[88:91], v[148:151], v[208:211], v[88:91]
	v_mfma_f32_16x16x32_bf16 v[80:83], v[176:179], v[208:211], v[80:83]
	v_mfma_f32_16x16x32_bf16 v[68:71], v[148:151], v[216:219], v[68:71]
	v_mfma_f32_16x16x32_bf16 v[64:67], v[176:179], v[216:219], v[64:67]
	s_setprio 0
	s_barrier
	s_add_i32 s58, s47, s36
	v_lshl_add_u64 v[220:221], s[26:27], 0, v[156:157]
	s_mov_b32 m0, s58
	ds_read_b128 v[180:183], v193 offset:16384
	ds_read_b128 v[184:187], v193 offset:17408
	ds_read_b128 v[196:199], v193 offset:18432
	ds_read_b128 v[200:203], v193 offset:19456
	ds_read_b128 v[204:207], v193 offset:20480
	ds_read_b128 v[208:211], v193 offset:21504
	ds_read_b128 v[212:215], v193 offset:22528
	ds_read_b128 v[216:219], v193 offset:23552
	global_load_lds_dwordx4 v[220:221], off
	s_add_i32 m0, s58, 0x2000
	s_add_u32 s58, s26, 0x40000
	v_lshl_add_u64 v[222:223], s[26:27], 0, v[152:153]
	s_addc_u32 s59, s27, 0
	s_add_i32 s60, s48, s36
	global_load_lds_dwordx4 v[222:223], off
	s_mov_b32 m0, s60
	v_lshl_add_u64 v[226:227], s[28:29], 0, v[154:155]
	global_load_lds_dwordx4 v156, s[58:59]
	s_add_i32 m0, s60, 0x2000
	s_nop 0
	global_load_lds_dwordx4 v152, s[58:59]
	v_lshl_add_u64 v[224:225], s[28:29], 0, v[158:159]
	s_mov_b32 m0, s39
	s_nop 0
	global_load_lds_dwordx4 v[224:225], off
	s_mov_b32 m0, s40
	s_nop 0
	global_load_lds_dwordx4 v[226:227], off
	s_waitcnt vmcnt(8)
	s_waitcnt lgkmcnt(0)
	s_barrier
	s_setprio 1
	v_mfma_f32_16x16x32_bf16 v[60:63], v[128:131], v[180:183], v[60:63]
	v_mfma_f32_16x16x32_bf16 v[52:55], v[136:139], v[180:183], v[52:55]
	v_mfma_f32_16x16x32_bf16 v[44:47], v[128:131], v[196:199], v[44:47]
	v_mfma_f32_16x16x32_bf16 v[40:43], v[136:139], v[196:199], v[40:43]
	v_mfma_f32_16x16x32_bf16 v[28:31], v[128:131], v[204:207], v[28:31]
	v_mfma_f32_16x16x32_bf16 v[20:23], v[136:139], v[204:207], v[20:23]
	v_mfma_f32_16x16x32_bf16 v[12:15], v[128:131], v[212:215], v[12:15]
	v_mfma_f32_16x16x32_bf16 v[8:11], v[136:139], v[212:215], v[8:11]
	v_mfma_f32_16x16x32_bf16 v[60:63], v[132:135], v[184:187], v[60:63]
	v_mfma_f32_16x16x32_bf16 v[52:55], v[140:143], v[184:187], v[52:55]
	v_mfma_f32_16x16x32_bf16 v[44:47], v[132:135], v[200:203], v[44:47]
	v_mfma_f32_16x16x32_bf16 v[40:43], v[140:143], v[200:203], v[40:43]
	v_mfma_f32_16x16x32_bf16 v[28:31], v[132:135], v[208:211], v[28:31]
	v_mfma_f32_16x16x32_bf16 v[20:23], v[140:143], v[208:211], v[20:23]
	v_mfma_f32_16x16x32_bf16 v[12:15], v[132:135], v[216:219], v[12:15]
	v_mfma_f32_16x16x32_bf16 v[8:11], v[140:143], v[216:219], v[8:11]
	v_mfma_f32_16x16x32_bf16 v[56:59], v[144:147], v[180:183], v[56:59]
	v_mfma_f32_16x16x32_bf16 v[48:51], v[172:175], v[180:183], v[48:51]
	v_mfma_f32_16x16x32_bf16 v[36:39], v[144:147], v[196:199], v[36:39]
	v_mfma_f32_16x16x32_bf16 v[32:35], v[172:175], v[196:199], v[32:35]
	v_mfma_f32_16x16x32_bf16 v[24:27], v[144:147], v[204:207], v[24:27]
	v_mfma_f32_16x16x32_bf16 v[16:19], v[172:175], v[204:207], v[16:19]
	v_mfma_f32_16x16x32_bf16 v[4:7], v[144:147], v[212:215], v[4:7]
	v_mfma_f32_16x16x32_bf16 v[0:3], v[172:175], v[212:215], v[0:3]
	v_mfma_f32_16x16x32_bf16 v[56:59], v[148:151], v[184:187], v[56:59]
	v_mfma_f32_16x16x32_bf16 v[48:51], v[176:179], v[184:187], v[48:51]
	v_mfma_f32_16x16x32_bf16 v[36:39], v[148:151], v[200:203], v[36:39]
	v_mfma_f32_16x16x32_bf16 v[32:35], v[176:179], v[200:203], v[32:35]
	v_mfma_f32_16x16x32_bf16 v[24:27], v[148:151], v[208:211], v[24:27]
	v_mfma_f32_16x16x32_bf16 v[16:19], v[176:179], v[208:211], v[16:19]
	v_mfma_f32_16x16x32_bf16 v[4:7], v[148:151], v[216:219], v[4:7]
	v_mfma_f32_16x16x32_bf16 v[0:3], v[176:179], v[216:219], v[0:3]
	s_setprio 0
	s_barrier
; #define PG8_STAGE(bufoff, gbase, voff) do { _Pragma("unroll") for (int _i = 0; _i < 2; ++_i) \
;         __builtin_amdgcn_global_load_lds((const unsigned*)((const char*)(gbase) + (voff)[_i]), (PG8_LAS unsigned*)(lds + (bufoff) + ldsw + _i * 8192), 16, 0, 0); } while (0)
; #define PG8_LDA(dst, b, h) do { _Pragma("unroll") for (int m = 0; m < 4; ++m) _Pragma("unroll") for (int k = 0; k < 2; ++k) dst[m][k] = *(const PG8_LAS bf16x8*)(lds + PG8_SA(b, h) + aoff + m * 2048 + k * 1024); } while (0)
; #define PG8_LDB(dst, b, h) do { _Pragma("unroll") for (int n = 0; n < 2; ++n) _Pragma("unroll") for (int k = 0; k < 2; ++k) dst[n][k] = *(const PG8_LAS bf16x8*)(lds + PG8_SB(b, h) + boff + n * 2048 + k * 1024); } while (0)
; #define PG8_MMA(ai, bj, At, Bt) do { __builtin_amdgcn_s_setprio(1); _Pragma("unroll") for (int m = 0; m < 4; ++m) _Pragma("unroll") for (int n = 0; n < 2; ++n) _Pragma("unroll") for (int k = 0; k < 2; ++k) \
;         acc[ai][bj][m][n] = __builtin_amdgcn_mfma_f32_16x16x32_bf16(Bt[n][k], At[m][k], acc[ai][bj][m][n], 0, 0, 0); __builtin_amdgcn_s_setprio(0); } while (0)
; #define PG8_WAIT_V(n) asm volatile("s_waitcnt vmcnt(" #n ")" ::: "memory")
; #define PG8_WAIT_L(n) asm volatile("s_waitcnt lgkmcnt(" #n ")" ::: "memory")
; #define PG8_BAR __builtin_amdgcn_s_barrier()
; #define PG8_SCHED __builtin_amdgcn_sched_barrier(0)
; template <class Epi, class Sched, bool ALIGN_EPI = false, bool SP2 = false>
; __device__ __forceinline__ void gemm_phase(PG8_LAS unsigned char* lds, const Gemm g, const Sched& S, const Epi& E) {
;     ...
;         for (int t = 0; t < nt; t += 2) {
;     ...
;             PG8_LDB(B0, 1, 0); PG8_LDB(B1, 1, 1); PG8_SCHED; PG8_LDA(At, 1, 0); PG8_STAGE(PG8_SA(0, 1), a2 + hstep, voffA);
;             PG8_WAIT_V(8); PG8_WAIT_L(0); PG8_BAR; PG8_MMA(0, 0, At, B0); PG8_MMA(0, 1, At, B1); PG8_BAR; PG8_SCHED;
;             PG8_LDA(At, 1, 1); PG8_STAGE(PG8_SB(1, 0), b3, voffB); PG8_STAGE(PG8_SB(1, 1), b3 + hstep, voffB); PG8_STAGE(PG8_SA(1, 0), a3, voffA);
;             PG8_WAIT_V(8); PG8_WAIT_L(0); PG8_BAR; PG8_MMA(1, 0, At, B0); PG8_MMA(1, 1, At, B1); PG8_BAR; PG8_SCHED;
.Lmy_peel_969_mid:
	s_add_i32 s58, 0, 0x18000
	s_add_i32 s59, 0, 0x1c000
	v_add_u32_e32 v140, s58, v190
	v_add_u32_e32 v176, s59, v190
	ds_read_b128 v[128:131], v140
	ds_read_b128 v[132:135], v140 offset:1024
	ds_read_b128 v[136:139], v140 offset:2048
	ds_read_b128 v[140:143], v140 offset:3072
	ds_read_b128 v[144:147], v176
	ds_read_b128 v[148:151], v176 offset:1024
	ds_read_b128 v[172:175], v176 offset:2048
	ds_read_b128 v[176:179], v176 offset:3072
	s_add_u32 s28, s28, 0x40000
	s_addc_u32 s29, s29, 0
	s_mov_b32 m0, s41
	ds_read_b128 v[180:183], v193 offset:32768
	ds_read_b128 v[184:187], v193 offset:33792
	ds_read_b128 v[196:199], v193 offset:34816
	ds_read_b128 v[200:203], v193 offset:35840
	ds_read_b128 v[204:207], v193 offset:36864
	ds_read_b128 v[208:211], v193 offset:37888
	ds_read_b128 v[212:215], v193 offset:38912
	ds_read_b128 v[216:219], v193 offset:39936
	global_load_lds_dwordx4 v158, s[28:29]
	s_mov_b32 m0, s42
	s_nop 0
	global_load_lds_dwordx4 v154, s[28:29]
	s_waitcnt vmcnt(8)
	s_waitcnt lgkmcnt(0)
	s_barrier
	s_setprio 1
	v_mfma_f32_16x16x32_bf16 v[124:127], v[128:131], v[180:183], v[124:127]
	v_mfma_f32_16x16x32_bf16 v[120:123], v[136:139], v[180:183], v[120:123]
	v_mfma_f32_16x16x32_bf16 v[108:111], v[128:131], v[196:199], v[108:111]
	v_mfma_f32_16x16x32_bf16 v[104:107], v[136:139], v[196:199], v[104:107]
	v_mfma_f32_16x16x32_bf16 v[92:95], v[128:131], v[204:207], v[92:95]
	v_mfma_f32_16x16x32_bf16 v[84:87], v[136:139], v[204:207], v[84:87]
	v_mfma_f32_16x16x32_bf16 v[76:79], v[128:131], v[212:215], v[76:79]
	v_mfma_f32_16x16x32_bf16 v[72:75], v[136:139], v[212:215], v[72:75]
	v_mfma_f32_16x16x32_bf16 v[124:127], v[132:135], v[184:187], v[124:127]
	v_mfma_f32_16x16x32_bf16 v[120:123], v[140:143], v[184:187], v[120:123]
	v_mfma_f32_16x16x32_bf16 v[108:111], v[132:135], v[200:203], v[108:111]
	v_mfma_f32_16x16x32_bf16 v[104:107], v[140:143], v[200:203], v[104:107]
	v_mfma_f32_16x16x32_bf16 v[92:95], v[132:135], v[208:211], v[92:95]
	v_mfma_f32_16x16x32_bf16 v[84:87], v[140:143], v[208:211], v[84:87]
	v_mfma_f32_16x16x32_bf16 v[76:79], v[132:135], v[216:219], v[76:79]
	v_mfma_f32_16x16x32_bf16 v[72:75], v[140:143], v[216:219], v[72:75]
	v_mfma_f32_16x16x32_bf16 v[116:119], v[144:147], v[180:183], v[116:119]
	v_mfma_f32_16x16x32_bf16 v[112:115], v[172:175], v[180:183], v[112:115]
	v_mfma_f32_16x16x32_bf16 v[100:103], v[144:147], v[196:199], v[100:103]
	v_mfma_f32_16x16x32_bf16 v[96:99], v[172:175], v[196:199], v[96:99]
	v_mfma_f32_16x16x32_bf16 v[88:91], v[144:147], v[204:207], v[88:91]
	v_mfma_f32_16x16x32_bf16 v[80:83], v[172:175], v[204:207], v[80:83]
	v_mfma_f32_16x16x32_bf16 v[68:71], v[144:147], v[212:215], v[68:71]
	v_mfma_f32_16x16x32_bf16 v[64:67], v[172:175], v[212:215], v[64:67]
	v_mfma_f32_16x16x32_bf16 v[116:119], v[148:151], v[184:187], v[116:119]
	v_mfma_f32_16x16x32_bf16 v[112:115], v[176:179], v[184:187], v[112:115]
	v_mfma_f32_16x16x32_bf16 v[100:103], v[148:151], v[200:203], v[100:103]
	v_mfma_f32_16x16x32_bf16 v[96:99], v[176:179], v[200:203], v[96:99]
	v_mfma_f32_16x16x32_bf16 v[88:91], v[148:151], v[208:211], v[88:91]
	v_mfma_f32_16x16x32_bf16 v[80:83], v[176:179], v[208:211], v[80:83]
	v_mfma_f32_16x16x32_bf16 v[68:71], v[148:151], v[216:219], v[68:71]
	v_mfma_f32_16x16x32_bf16 v[64:67], v[176:179], v[216:219], v[64:67]
	s_setprio 0
	s_barrier
	s_add_i32 s28, s58, s36
	v_lshl_add_u64 v[220:221], v[220:221], 0, s[10:11]
	s_mov_b32 m0, s28
	ds_read_b128 v[180:183], v193 offset:49152
	ds_read_b128 v[184:187], v193 offset:50176
	ds_read_b128 v[196:199], v193 offset:51200
	ds_read_b128 v[200:203], v193 offset:52224
	ds_read_b128 v[204:207], v193 offset:53248
	ds_read_b128 v[208:211], v193 offset:54272
	ds_read_b128 v[212:215], v193 offset:55296
	ds_read_b128 v[216:219], v193 offset:56320
	global_load_lds_dwordx4 v[220:221], off
	s_add_i32 m0, s28, 0x2000
	s_add_u32 s26, s26, 0x40080
	v_lshl_add_u64 v[220:221], v[222:223], 0, s[10:11]
	s_addc_u32 s27, s27, 0
	s_add_i32 s28, s59, s36
	global_load_lds_dwordx4 v[220:221], off
	s_mov_b32 m0, s28
	s_nop 0
	global_load_lds_dwordx4 v156, s[26:27]
	s_add_i32 m0, s28, 0x2000
	s_nop 0
	global_load_lds_dwordx4 v152, s[26:27]
	v_lshl_add_u64 v[220:221], v[224:225], 0, s[10:11]
	s_mov_b32 m0, s43
	s_nop 0
	global_load_lds_dwordx4 v[220:221], off
	v_lshl_add_u64 v[220:221], v[226:227], 0, s[10:11]
	s_mov_b32 m0, s44
	s_nop 0
	global_load_lds_dwordx4 v[220:221], off
	s_waitcnt vmcnt(8)
	s_waitcnt lgkmcnt(0)
	s_barrier
	s_setprio 1
	v_mfma_f32_16x16x32_bf16 v[60:63], v[128:131], v[180:183], v[60:63]
	v_mfma_f32_16x16x32_bf16 v[52:55], v[136:139], v[180:183], v[52:55]
	v_mfma_f32_16x16x32_bf16 v[44:47], v[128:131], v[196:199], v[44:47]
	v_mfma_f32_16x16x32_bf16 v[40:43], v[136:139], v[196:199], v[40:43]
	v_mfma_f32_16x16x32_bf16 v[28:31], v[128:131], v[204:207], v[28:31]
	v_mfma_f32_16x16x32_bf16 v[20:23], v[136:139], v[204:207], v[20:23]
	v_mfma_f32_16x16x32_bf16 v[12:15], v[128:131], v[212:215], v[12:15]
	v_mfma_f32_16x16x32_bf16 v[8:11], v[136:139], v[212:215], v[8:11]
	v_mfma_f32_16x16x32_bf16 v[60:63], v[132:135], v[184:187], v[60:63]
	v_mfma_f32_16x16x32_bf16 v[52:55], v[140:143], v[184:187], v[52:55]
	v_mfma_f32_16x16x32_bf16 v[44:47], v[132:135], v[200:203], v[44:47]
	v_mfma_f32_16x16x32_bf16 v[40:43], v[140:143], v[200:203], v[40:43]
	v_mfma_f32_16x16x32_bf16 v[28:31], v[132:135], v[208:211], v[28:31]
	v_mfma_f32_16x16x32_bf16 v[20:23], v[140:143], v[208:211], v[20:23]
	v_mfma_f32_16x16x32_bf16 v[12:15], v[132:135], v[216:219], v[12:15]
	v_mfma_f32_16x16x32_bf16 v[8:11], v[140:143], v[216:219], v[8:11]
	v_mfma_f32_16x16x32_bf16 v[56:59], v[144:147], v[180:183], v[56:59]
	v_mfma_f32_16x16x32_bf16 v[48:51], v[172:175], v[180:183], v[48:51]
	v_mfma_f32_16x16x32_bf16 v[36:39], v[144:147], v[196:199], v[36:39]
	v_mfma_f32_16x16x32_bf16 v[32:35], v[172:175], v[196:199], v[32:35]
	v_mfma_f32_16x16x32_bf16 v[24:27], v[144:147], v[204:207], v[24:27]
	v_mfma_f32_16x16x32_bf16 v[16:19], v[172:175], v[204:207], v[16:19]
	v_mfma_f32_16x16x32_bf16 v[4:7], v[144:147], v[212:215], v[4:7]
	v_mfma_f32_16x16x32_bf16 v[0:3], v[172:175], v[212:215], v[0:3]
	v_mfma_f32_16x16x32_bf16 v[56:59], v[148:151], v[184:187], v[56:59]
	v_mfma_f32_16x16x32_bf16 v[48:51], v[176:179], v[184:187], v[48:51]
	v_mfma_f32_16x16x32_bf16 v[36:39], v[148:151], v[200:203], v[36:39]
	v_mfma_f32_16x16x32_bf16 v[32:35], v[176:179], v[200:203], v[32:35]
	v_mfma_f32_16x16x32_bf16 v[24:27], v[148:151], v[208:211], v[24:27]
	v_mfma_f32_16x16x32_bf16 v[16:19], v[176:179], v[208:211], v[16:19]
	v_mfma_f32_16x16x32_bf16 v[4:7], v[148:151], v[216:219], v[4:7]
	v_mfma_f32_16x16x32_bf16 v[0:3], v[176:179], v[216:219], v[0:3]
	s_setprio 0
	s_barrier
	s_add_i32 s57, s57, 2
	s_add_u32 s24, s24, 0x100
	s_addc_u32 s25, s25, 0
	s_add_u32 s55, s55, 0x100
	s_addc_u32 s56, s56, 0
	s_cmp_gt_u32 s57, 13
	s_cbranch_scc0 .LBB0_969
	s_and_b64 vcc, exec, s[12:13]
	s_cbranch_vccz .LBB0_972
	s_barrier

;     __host__ __device__ bool next(int i, Unit& u) const { const long L = (long)i * G + c; if (L >= nwg) return false; return unit_of((int)L, u); }
;     __host__ __device__ bool next(int i, Unit& u) const { const int L = i == 0 ? l0 : (i == 1 ? l1 : (i == 2 ? l2 : -1)); if (L < 0 || L >= s.nwg) return false; return s.unit_of(L, u); }
;     __host__ __device__ bool next(int i, Unit& u) const { const bool ok = s.next(i >> 1, u); u.kh = i & 1; return ok; }
; #define PG8_STAGE(bufoff, gbase, voff) do { _Pragma("unroll") for (int _i = 0; _i < 2; ++_i) \
;         __builtin_amdgcn_global_load_lds((const unsigned*)((const char*)(gbase) + (voff)[_i]), (PG8_LAS unsigned*)(lds + (bufoff) + ldsw + _i * 8192), 16, 0, 0); } while (0)
; #define PG8_WAIT_V(n) asm volatile("s_waitcnt vmcnt(" #n ")" ::: "memory")
; template <class Epi, class Sched, bool ALIGN_EPI = false, bool SP2 = false>
; __device__ __forceinline__ void gemm_phase(PG8_LAS unsigned char* lds, const Gemm g, const Sched& S, const Epi& E) {
;     ...
;         const bool has_next = S.next(ui + 1, nxt);
;         const char* nA = has_next ? (const char*)g.A + (size_t)nxt.pm * tstep + nxt.kh * khb : cA; const char* nB = has_next ? (const char*)g.Bt + (size_t)nxt.pn * tstep + nxt.kh * khb : cB;
;         for (int t = 0; t < nt; t += 2) {
;             const bool last = (t == nt - 2);
;             const char* a1 = cA + (size_t)(t + 1) * kstep;
;             const char* a2 = last ? nA : cA + (size_t)(t + 2) * kstep; const char* b2 = last ? nB : cB + (size_t)(t + 2) * kstep;
;             const char* a3 = a2 + kstep; const char* b3 = b2 + kstep;
;             if (last && has_next) S.a_ready(nxt);
;             if constexpr (SP2) {
;             PG8_LDB(B0, 0, 0); PG8_LDB(B1, 0, 1); PG8_SCHED; PG8_LDA(At, 0, 0); PG8_STAGE(PG8_SA(1, 1), a1 + hstep, voffA);
;             PG8_WAIT_V(8); PG8_WAIT_L(0); PG8_BAR; PG8_MMA(0, 0, At, B0); PG8_MMA(0, 1, At, B1); PG8_BAR; PG8_SCHED;
;             PG8_LDA(At, 0, 1); PG8_STAGE(PG8_SB(0, 0), b2, voffB); PG8_STAGE(PG8_SB(0, 1), b2 + hstep, voffB); PG8_STAGE(PG8_SA(0, 0), a2, voffA);
;     ...
;         for (int a = 0; a < 2; ++a)
; #pragma unroll
;             for (int b = 0; b < 2; ++b)
; #pragma unroll
;                 for (int m = 0; m < 4; ++m)
; #pragma unroll
;                     for (int n = 0; n < 2; ++n) acc[a][b][m][n] = (f32x4){0.f, 0.f, 0.f, 0.f};
.LBB0_1051:
	s_add_u32 s54, s24, 0x100
	s_addc_u32 s55, s25, 0
	s_mov_b32 s56, -2
	ds_read_b128 v[146:149], v153
	ds_read_b128 v[156:159], v153 offset:1024
	ds_read_b128 v[160:163], v153 offset:2048
	ds_read_b128 v[164:167], v153 offset:3072
	ds_read_b128 v[168:171], v154
	ds_read_b128 v[172:175], v154 offset:1024
	ds_read_b128 v[176:179], v154 offset:2048
	ds_read_b128 v[180:183], v154 offset:3072
	s_add_u32 s24, s22, 0x100
	s_addc_u32 s25, s23, 0
	s_cmp_eq_u32 s56, 40
	s_cselect_b32 s29, s3, s25
	s_cselect_b32 s28, s2, s24
	s_cselect_b32 s27, s21, s55
	s_cselect_b32 s26, s20, s54
	s_add_i32 m0, s38, 0xc000
	ds_read_b128 v[184:187], v155
	ds_read_b128 v[188:191], v155 offset:1024
	ds_read_b128 v[192:195], v155 offset:2048
	ds_read_b128 v[196:199], v155 offset:3072
	ds_read_b128 v[200:203], v155 offset:4096
	ds_read_b128 v[204:207], v155 offset:5120
	ds_read_b128 v[208:211], v155 offset:6144
	ds_read_b128 v[212:215], v155 offset:7168
	global_load_lds_dwordx4 v138, s[22:23]
	s_add_i32 m0, s38, 0xe000
	s_nop 0
	global_load_lds_dwordx4 v140, s[22:23]
	s_waitcnt vmcnt(8)
	s_waitcnt lgkmcnt(0)
	s_barrier
	s_setprio 1
	v_mfma_f32_16x16x32_bf16 v[124:127], v[146:149], v[184:187], 0
	v_mfma_f32_16x16x32_bf16 v[120:123], v[160:163], v[184:187], 0
	v_mfma_f32_16x16x32_bf16 v[116:119], v[146:149], v[192:195], 0
	v_mfma_f32_16x16x32_bf16 v[112:115], v[160:163], v[192:195], 0
	v_mfma_f32_16x16x32_bf16 v[92:95], v[146:149], v[200:203], 0
	v_mfma_f32_16x16x32_bf16 v[88:91], v[160:163], v[200:203], 0
	v_mfma_f32_16x16x32_bf16 v[76:79], v[146:149], v[208:211], 0
	v_mfma_f32_16x16x32_bf16 v[72:75], v[160:163], v[208:211], 0
	v_mfma_f32_16x16x32_bf16 v[124:127], v[156:159], v[188:191], v[124:127]
	v_mfma_f32_16x16x32_bf16 v[120:123], v[164:167], v[188:191], v[120:123]
	v_mfma_f32_16x16x32_bf16 v[116:119], v[156:159], v[196:199], v[116:119]
	v_mfma_f32_16x16x32_bf16 v[112:115], v[164:167], v[196:199], v[112:115]
	v_mfma_f32_16x16x32_bf16 v[92:95], v[156:159], v[204:207], v[92:95]
	v_mfma_f32_16x16x32_bf16 v[88:91], v[164:167], v[204:207], v[88:91]
	v_mfma_f32_16x16x32_bf16 v[76:79], v[156:159], v[212:215], v[76:79]
	v_mfma_f32_16x16x32_bf16 v[72:75], v[164:167], v[212:215], v[72:75]
	v_mfma_f32_16x16x32_bf16 v[108:111], v[168:171], v[184:187], 0
	v_mfma_f32_16x16x32_bf16 v[104:107], v[176:179], v[184:187], 0
	v_mfma_f32_16x16x32_bf16 v[100:103], v[168:171], v[192:195], 0
	v_mfma_f32_16x16x32_bf16 v[96:99], v[176:179], v[192:195], 0
	v_mfma_f32_16x16x32_bf16 v[84:87], v[168:171], v[200:203], 0
	v_mfma_f32_16x16x32_bf16 v[80:83], v[176:179], v[200:203], 0
	v_mfma_f32_16x16x32_bf16 v[68:71], v[168:171], v[208:211], 0
	v_mfma_f32_16x16x32_bf16 v[64:67], v[176:179], v[208:211], 0
	v_mfma_f32_16x16x32_bf16 v[108:111], v[172:175], v[188:191], v[108:111]
	v_mfma_f32_16x16x32_bf16 v[104:107], v[180:183], v[188:191], v[104:107]
	v_mfma_f32_16x16x32_bf16 v[100:103], v[172:175], v[196:199], v[100:103]
	v_mfma_f32_16x16x32_bf16 v[96:99], v[180:183], v[196:199], v[96:99]
	v_mfma_f32_16x16x32_bf16 v[84:87], v[172:175], v[204:207], v[84:87]
	v_mfma_f32_16x16x32_bf16 v[80:83], v[180:183], v[204:207], v[80:83]
	v_mfma_f32_16x16x32_bf16 v[68:71], v[172:175], v[212:215], v[68:71]
	v_mfma_f32_16x16x32_bf16 v[64:67], v[180:183], v[212:215], v[64:67]
	s_setprio 0
	s_barrier
	s_add_i32 s22, s46, s37
	v_lshl_add_u64 v[150:151], s[26:27], 0, v[130:131]
	s_mov_b32 m0, s22
	ds_read_b128 v[184:187], v155 offset:16384
	ds_read_b128 v[188:191], v155 offset:17408
	ds_read_b128 v[192:195], v155 offset:18432
	ds_read_b128 v[196:199], v155 offset:19456
	ds_read_b128 v[200:203], v155 offset:20480
	ds_read_b128 v[204:207], v155 offset:21504
	ds_read_b128 v[208:211], v155 offset:22528
	ds_read_b128 v[212:215], v155 offset:23552
	global_load_lds_dwordx4 v[150:151], off
	s_add_i32 m0, s22, 0x2000
	s_add_u32 s22, s26, 0xb0000
	v_lshl_add_u64 v[216:217], s[26:27], 0, v[134:135]
	s_addc_u32 s23, s27, 0
	s_add_i32 s57, s47, s37
	global_load_lds_dwordx4 v[216:217], off
	s_mov_b32 m0, s57
	v_lshl_add_u64 v[220:221], s[28:29], 0, v[132:133]
	global_load_lds_dwordx4 v130, s[22:23]
	s_add_i32 m0, s57, 0x2000
	s_nop 0
	global_load_lds_dwordx4 v134, s[22:23]
	v_lshl_add_u64 v[218:219], s[28:29], 0, v[128:129]
	s_mov_b32 m0, s38
	s_nop 0
	global_load_lds_dwordx4 v[218:219], off
	s_mov_b32 m0, s39
	s_nop 0
	global_load_lds_dwordx4 v[220:221], off
	s_waitcnt vmcnt(8)
	s_waitcnt lgkmcnt(0)
	s_barrier
	s_setprio 1
	v_mfma_f32_16x16x32_bf16 v[60:63], v[146:149], v[184:187], 0
	v_mfma_f32_16x16x32_bf16 v[56:59], v[160:163], v[184:187], 0
	v_mfma_f32_16x16x32_bf16 v[44:47], v[146:149], v[192:195], 0
	v_mfma_f32_16x16x32_bf16 v[40:43], v[160:163], v[192:195], 0
	v_mfma_f32_16x16x32_bf16 v[28:31], v[146:149], v[200:203], 0
	v_mfma_f32_16x16x32_bf16 v[24:27], v[160:163], v[200:203], 0
	v_mfma_f32_16x16x32_bf16 v[12:15], v[146:149], v[208:211], 0
	v_mfma_f32_16x16x32_bf16 v[8:11], v[160:163], v[208:211], 0
	v_mfma_f32_16x16x32_bf16 v[60:63], v[156:159], v[188:191], v[60:63]
	v_mfma_f32_16x16x32_bf16 v[56:59], v[164:167], v[188:191], v[56:59]
	v_mfma_f32_16x16x32_bf16 v[44:47], v[156:159], v[196:199], v[44:47]
	v_mfma_f32_16x16x32_bf16 v[40:43], v[164:167], v[196:199], v[40:43]
	v_mfma_f32_16x16x32_bf16 v[28:31], v[156:159], v[204:207], v[28:31]
	v_mfma_f32_16x16x32_bf16 v[24:27], v[164:167], v[204:207], v[24:27]
	v_mfma_f32_16x16x32_bf16 v[12:15], v[156:159], v[212:215], v[12:15]
	v_mfma_f32_16x16x32_bf16 v[8:11], v[164:167], v[212:215], v[8:11]
	v_mfma_f32_16x16x32_bf16 v[52:55], v[168:171], v[184:187], 0
	v_mfma_f32_16x16x32_bf16 v[48:51], v[176:179], v[184:187], 0
	v_mfma_f32_16x16x32_bf16 v[36:39], v[168:171], v[192:195], 0
	v_mfma_f32_16x16x32_bf16 v[32:35], v[176:179], v[192:195], 0
	v_mfma_f32_16x16x32_bf16 v[20:23], v[168:171], v[200:203], 0
	v_mfma_f32_16x16x32_bf16 v[16:19], v[176:179], v[200:203], 0
	v_mfma_f32_16x16x32_bf16 v[4:7], v[168:171], v[208:211], 0
	v_mfma_f32_16x16x32_bf16 v[0:3], v[176:179], v[208:211], 0
	v_mfma_f32_16x16x32_bf16 v[52:55], v[172:175], v[188:191], v[52:55]
	v_mfma_f32_16x16x32_bf16 v[48:51], v[180:183], v[188:191], v[48:51]
	v_mfma_f32_16x16x32_bf16 v[36:39], v[172:175], v[196:199], v[36:39]
	v_mfma_f32_16x16x32_bf16 v[32:35], v[180:183], v[196:199], v[32:35]
	v_mfma_f32_16x16x32_bf16 v[20:23], v[172:175], v[204:207], v[20:23]
	v_mfma_f32_16x16x32_bf16 v[16:19], v[180:183], v[204:207], v[16:19]
	v_mfma_f32_16x16x32_bf16 v[4:7], v[172:175], v[212:215], v[4:7]
	v_mfma_f32_16x16x32_bf16 v[0:3], v[180:183], v[212:215], v[0:3]
	s_setprio 0
	s_barrier
	s_branch .Lmy_peel_1052_mid
; #define PG8_STAGE(bufoff, gbase, voff) do { _Pragma("unroll") for (int _i = 0; _i < 2; ++_i) \
;         __builtin_amdgcn_global_load_lds((const unsigned*)((const char*)(gbase) + (voff)[_i]), (PG8_LAS unsigned*)(lds + (bufoff) + ldsw + _i * 8192), 16, 0, 0); } while (0)
; #define PG8_LDA(dst, b, h) do { _Pragma("unroll") for (int m = 0; m < 4; ++m) _Pragma("unroll") for (int k = 0; k < 2; ++k) dst[m][k] = *(const PG8_LAS bf16x8*)(lds + PG8_SA(b, h) + aoff + m * 2048 + k * 1024); } while (0)
; #define PG8_LDB(dst, b, h) do { _Pragma("unroll") for (int n = 0; n < 2; ++n) _Pragma("unroll") for (int k = 0; k < 2; ++k) dst[n][k] = *(const PG8_LAS bf16x8*)(lds + PG8_SB(b, h) + boff + n * 2048 + k * 1024); } while (0)
; #define PG8_MMA(ai, bj, At, Bt) do { __builtin_amdgcn_s_setprio(1); _Pragma("unroll") for (int m = 0; m < 4; ++m) _Pragma("unroll") for (int n = 0; n < 2; ++n) _Pragma("unroll") for (int k = 0; k < 2; ++k) \
;         acc[ai][bj][m][n] = __builtin_amdgcn_mfma_f32_16x16x32_bf16(Bt[n][k], At[m][k], acc[ai][bj][m][n], 0, 0, 0); __builtin_amdgcn_s_setprio(0); } while (0)
; #define PG8_WAIT_V(n) asm volatile("s_waitcnt vmcnt(" #n ")" ::: "memory")
; #define PG8_WAIT_L(n) asm volatile("s_waitcnt lgkmcnt(" #n ")" ::: "memory")
; #define PG8_BAR __builtin_amdgcn_s_barrier()
; #define PG8_SCHED __builtin_amdgcn_sched_barrier(0)
; template <class Epi, class Sched, bool ALIGN_EPI = false, bool SP2 = false>
; __device__ __forceinline__ void gemm_phase(PG8_LAS unsigned char* lds, const Gemm g, const Sched& S, const Epi& E) {
;     ...
;             PG8_LDB(B0, 0, 0); PG8_LDB(B1, 0, 1); PG8_SCHED; PG8_LDA(At, 0, 0); PG8_STAGE(PG8_SA(1, 1), a1 + hstep, voffA);
;             PG8_WAIT_V(8); PG8_WAIT_L(0); PG8_BAR; PG8_MMA(0, 0, At, B0); PG8_MMA(0, 1, At, B1); PG8_BAR; PG8_SCHED;
;             PG8_LDA(At, 0, 1); PG8_STAGE(PG8_SB(0, 0), b2, voffB); PG8_STAGE(PG8_SB(0, 1), b2 + hstep, voffB); PG8_STAGE(PG8_SA(0, 0), a2, voffA);
;             PG8_WAIT_V(8); PG8_WAIT_L(0); PG8_BAR; PG8_MMA(1, 0, At, B0); PG8_MMA(1, 1, At, B1); PG8_BAR; PG8_SCHED;
.LBB0_1052:
	ds_read_b128 v[146:149], v153
	ds_read_b128 v[156:159], v153 offset:1024
	ds_read_b128 v[160:163], v153 offset:2048
	ds_read_b128 v[164:167], v153 offset:3072
	ds_read_b128 v[168:171], v154
	ds_read_b128 v[172:175], v154 offset:1024
	ds_read_b128 v[176:179], v154 offset:2048
	ds_read_b128 v[180:183], v154 offset:3072
	s_add_u32 s24, s22, 0x100
	s_addc_u32 s25, s23, 0
	s_cmp_eq_u32 s56, 40
	s_cselect_b32 s29, s3, s25
	s_cselect_b32 s28, s2, s24
	s_cselect_b32 s27, s21, s55
	s_cselect_b32 s26, s20, s54
	s_add_i32 m0, s38, 0xc000
	ds_read_b128 v[184:187], v155
	ds_read_b128 v[188:191], v155 offset:1024
	ds_read_b128 v[192:195], v155 offset:2048
	ds_read_b128 v[196:199], v155 offset:3072
	ds_read_b128 v[200:203], v155 offset:4096
	ds_read_b128 v[204:207], v155 offset:5120
	ds_read_b128 v[208:211], v155 offset:6144
	ds_read_b128 v[212:215], v155 offset:7168
	global_load_lds_dwordx4 v138, s[22:23]
	s_add_i32 m0, s38, 0xe000
	s_nop 0
	global_load_lds_dwordx4 v140, s[22:23]
	s_waitcnt vmcnt(8)
	s_waitcnt lgkmcnt(0)
	s_barrier
	s_setprio 1
	v_mfma_f32_16x16x32_bf16 v[124:127], v[146:149], v[184:187], v[124:127]
	v_mfma_f32_16x16x32_bf16 v[120:123], v[160:163], v[184:187], v[120:123]
	v_mfma_f32_16x16x32_bf16 v[116:119], v[146:149], v[192:195], v[116:119]
	v_mfma_f32_16x16x32_bf16 v[112:115], v[160:163], v[192:195], v[112:115]
	v_mfma_f32_16x16x32_bf16 v[92:95], v[146:149], v[200:203], v[92:95]
	v_mfma_f32_16x16x32_bf16 v[88:91], v[160:163], v[200:203], v[88:91]
	v_mfma_f32_16x16x32_bf16 v[76:79], v[146:149], v[208:211], v[76:79]
	v_mfma_f32_16x16x32_bf16 v[72:75], v[160:163], v[208:211], v[72:75]
	v_mfma_f32_16x16x32_bf16 v[124:127], v[156:159], v[188:191], v[124:127]
	v_mfma_f32_16x16x32_bf16 v[120:123], v[164:167], v[188:191], v[120:123]
	v_mfma_f32_16x16x32_bf16 v[116:119], v[156:159], v[196:199], v[116:119]
	v_mfma_f32_16x16x32_bf16 v[112:115], v[164:167], v[196:199], v[112:115]
	v_mfma_f32_16x16x32_bf16 v[92:95], v[156:159], v[204:207], v[92:95]
	v_mfma_f32_16x16x32_bf16 v[88:91], v[164:167], v[204:207], v[88:91]
	v_mfma_f32_16x16x32_bf16 v[76:79], v[156:159], v[212:215], v[76:79]
	v_mfma_f32_16x16x32_bf16 v[72:75], v[164:167], v[212:215], v[72:75]
	v_mfma_f32_16x16x32_bf16 v[108:111], v[168:171], v[184:187], v[108:111]
	v_mfma_f32_16x16x32_bf16 v[104:107], v[176:179], v[184:187], v[104:107]
	v_mfma_f32_16x16x32_bf16 v[100:103], v[168:171], v[192:195], v[100:103]
	v_mfma_f32_16x16x32_bf16 v[96:99], v[176:179], v[192:195], v[96:99]
	v_mfma_f32_16x16x32_bf16 v[84:87], v[168:171], v[200:203], v[84:87]
	v_mfma_f32_16x16x32_bf16 v[80:83], v[176:179], v[200:203], v[80:83]
	v_mfma_f32_16x16x32_bf16 v[68:71], v[168:171], v[208:211], v[68:71]
	v_mfma_f32_16x16x32_bf16 v[64:67], v[176:179], v[208:211], v[64:67]
	v_mfma_f32_16x16x32_bf16 v[108:111], v[172:175], v[188:191], v[108:111]
	v_mfma_f32_16x16x32_bf16 v[104:107], v[180:183], v[188:191], v[104:107]
	v_mfma_f32_16x16x32_bf16 v[100:103], v[172:175], v[196:199], v[100:103]
	v_mfma_f32_16x16x32_bf16 v[96:99], v[180:183], v[196:199], v[96:99]
	v_mfma_f32_16x16x32_bf16 v[84:87], v[172:175], v[204:207], v[84:87]
	v_mfma_f32_16x16x32_bf16 v[80:83], v[180:183], v[204:207], v[80:83]
	v_mfma_f32_16x16x32_bf16 v[68:71], v[172:175], v[212:215], v[68:71]
	v_mfma_f32_16x16x32_bf16 v[64:67], v[180:183], v[212:215], v[64:67]
	s_setprio 0
	s_barrier
	s_add_i32 s22, s46, s37
	v_lshl_add_u64 v[150:151], s[26:27], 0, v[130:131]
	s_mov_b32 m0, s22
	ds_read_b128 v[184:187], v155 offset:16384
	ds_read_b128 v[188:191], v155 offset:17408
	ds_read_b128 v[192:195], v155 offset:18432
	ds_read_b128 v[196:199], v155 offset:19456
	ds_read_b128 v[200:203], v155 offset:20480
	ds_read_b128 v[204:207], v155 offset:21504
	ds_read_b128 v[208:211], v155 offset:22528
	ds_read_b128 v[212:215], v155 offset:23552
	global_load_lds_dwordx4 v[150:151], off
	s_add_i32 m0, s22, 0x2000
	s_add_u32 s22, s26, 0xb0000
	v_lshl_add_u64 v[216:217], s[26:27], 0, v[134:135]
	s_addc_u32 s23, s27, 0
	s_add_i32 s57, s47, s37
	global_load_lds_dwordx4 v[216:217], off
	s_mov_b32 m0, s57
	v_lshl_add_u64 v[220:221], s[28:29], 0, v[132:133]
	global_load_lds_dwordx4 v130, s[22:23]
	s_add_i32 m0, s57, 0x2000
	s_nop 0
	global_load_lds_dwordx4 v134, s[22:23]
	v_lshl_add_u64 v[218:219], s[28:29], 0, v[128:129]
	s_mov_b32 m0, s38
	s_nop 0
	global_load_lds_dwordx4 v[218:219], off
	s_mov_b32 m0, s39
	s_nop 0
	global_load_lds_dwordx4 v[220:221], off
	s_waitcnt vmcnt(8)
	s_waitcnt lgkmcnt(0)
	s_barrier
	s_setprio 1
	v_mfma_f32_16x16x32_bf16 v[60:63], v[146:149], v[184:187], v[60:63]
	v_mfma_f32_16x16x32_bf16 v[56:59], v[160:163], v[184:187], v[56:59]
	v_mfma_f32_16x16x32_bf16 v[44:47], v[146:149], v[192:195], v[44:47]
	v_mfma_f32_16x16x32_bf16 v[40:43], v[160:163], v[192:195], v[40:43]
	v_mfma_f32_16x16x32_bf16 v[28:31], v[146:149], v[200:203], v[28:31]
	v_mfma_f32_16x16x32_bf16 v[24:27], v[160:163], v[200:203], v[24:27]
	v_mfma_f32_16x16x32_bf16 v[12:15], v[146:149], v[208:211], v[12:15]
	v_mfma_f32_16x16x32_bf16 v[8:11], v[160:163], v[208:211], v[8:11]
	v_mfma_f32_16x16x32_bf16 v[60:63], v[156:159], v[188:191], v[60:63]
	v_mfma_f32_16x16x32_bf16 v[56:59], v[164:167], v[188:191], v[56:59]
	v_mfma_f32_16x16x32_bf16 v[44:47], v[156:159], v[196:199], v[44:47]
	v_mfma_f32_16x16x32_bf16 v[40:43], v[164:167], v[196:199], v[40:43]
	v_mfma_f32_16x16x32_bf16 v[28:31], v[156:159], v[204:207], v[28:31]
	v_mfma_f32_16x16x32_bf16 v[24:27], v[164:167], v[204:207], v[24:27]
	v_mfma_f32_16x16x32_bf16 v[12:15], v[156:159], v[212:215], v[12:15]
	v_mfma_f32_16x16x32_bf16 v[8:11], v[164:167], v[212:215], v[8:11]
	v_mfma_f32_16x16x32_bf16 v[52:55], v[168:171], v[184:187], v[52:55]
	v_mfma_f32_16x16x32_bf16 v[48:51], v[176:179], v[184:187], v[48:51]
	v_mfma_f32_16x16x32_bf16 v[36:39], v[168:171], v[192:195], v[36:39]
	v_mfma_f32_16x16x32_bf16 v[32:35], v[176:179], v[192:195], v[32:35]
	v_mfma_f32_16x16x32_bf16 v[20:23], v[168:171], v[200:203], v[20:23]
	v_mfma_f32_16x16x32_bf16 v[16:19], v[176:179], v[200:203], v[16:19]
	v_mfma_f32_16x16x32_bf16 v[4:7], v[168:171], v[208:211], v[4:7]
	v_mfma_f32_16x16x32_bf16 v[0:3], v[176:179], v[208:211], v[0:3]
	v_mfma_f32_16x16x32_bf16 v[52:55], v[172:175], v[188:191], v[52:55]
	v_mfma_f32_16x16x32_bf16 v[48:51], v[180:183], v[188:191], v[48:51]
	v_mfma_f32_16x16x32_bf16 v[36:39], v[172:175], v[196:199], v[36:39]
	v_mfma_f32_16x16x32_bf16 v[32:35], v[180:183], v[196:199], v[32:35]
	v_mfma_f32_16x16x32_bf16 v[20:23], v[172:175], v[204:207], v[20:23]
	v_mfma_f32_16x16x32_bf16 v[16:19], v[180:183], v[204:207], v[16:19]
	v_mfma_f32_16x16x32_bf16 v[4:7], v[172:175], v[212:215], v[4:7]
	v_mfma_f32_16x16x32_bf16 v[0:3], v[180:183], v[212:215], v[0:3]
	s_setprio 0
	s_barrier
; #define PG8_STAGE(bufoff, gbase, voff) do { _Pragma("unroll") for (int _i = 0; _i < 2; ++_i) \
;         __builtin_amdgcn_global_load_lds((const unsigned*)((const char*)(gbase) + (voff)[_i]), (PG8_LAS unsigned*)(lds + (bufoff) + ldsw + _i * 8192), 16, 0, 0); } while (0)
; #define PG8_LDA(dst, b, h) do { _Pragma("unroll") for (int m = 0; m < 4; ++m) _Pragma("unroll") for (int k = 0; k < 2; ++k) dst[m][k] = *(const PG8_LAS bf16x8*)(lds + PG8_SA(b, h) + aoff + m * 2048 + k * 1024); } while (0)
; #define PG8_LDB(dst, b, h) do { _Pragma("unroll") for (int n = 0; n < 2; ++n) _Pragma("unroll") for (int k = 0; k < 2; ++k) dst[n][k] = *(const PG8_LAS bf16x8*)(lds + PG8_SB(b, h) + boff + n * 2048 + k * 1024); } while (0)
; #define PG8_MMA(ai, bj, At, Bt) do { __builtin_amdgcn_s_setprio(1); _Pragma("unroll") for (int m = 0; m < 4; ++m) _Pragma("unroll") for (int n = 0; n < 2; ++n) _Pragma("unroll") for (int k = 0; k < 2; ++k) \
;         acc[ai][bj][m][n] = __builtin_amdgcn_mfma_f32_16x16x32_bf16(Bt[n][k], At[m][k], acc[ai][bj][m][n], 0, 0, 0); __builtin_amdgcn_s_setprio(0); } while (0)
; #define PG8_WAIT_V(n) asm volatile("s_waitcnt vmcnt(" #n ")" ::: "memory")
; #define PG8_WAIT_L(n) asm volatile("s_waitcnt lgkmcnt(" #n ")" ::: "memory")
; #define PG8_BAR __builtin_amdgcn_s_barrier()
; #define PG8_SCHED __builtin_amdgcn_sched_barrier(0)
; template <class Epi, class Sched, bool ALIGN_EPI = false, bool SP2 = false>
; __device__ __forceinline__ void gemm_phase(PG8_LAS unsigned char* lds, const Gemm g, const Sched& S, const Epi& E) {
;     ...
;         for (int t = 0; t < nt; t += 2) {
;     ...
;             PG8_LDB(B0, 1, 0); PG8_LDB(B1, 1, 1); PG8_SCHED; PG8_LDA(At, 1, 0); PG8_STAGE(PG8_SA(0, 1), a2 + hstep, voffA);
;             PG8_WAIT_V(8); PG8_WAIT_L(0); PG8_BAR; PG8_MMA(0, 0, At, B0); PG8_MMA(0, 1, At, B1); PG8_BAR; PG8_SCHED;
;             PG8_LDA(At, 1, 1); PG8_STAGE(PG8_SB(1, 0), b3, voffB); PG8_STAGE(PG8_SB(1, 1), b3 + hstep, voffB); PG8_STAGE(PG8_SA(1, 0), a3, voffA);
;             PG8_WAIT_V(8); PG8_WAIT_L(0); PG8_BAR; PG8_MMA(1, 0, At, B0); PG8_MMA(1, 1, At, B1); PG8_BAR; PG8_SCHED;
.Lmy_peel_1052_mid:
	s_add_i32 s57, 0, 0x18000
	s_add_i32 s58, 0, 0x1c000
	v_add_u32_e32 v164, s57, v152
	v_add_u32_e32 v180, s58, v152
	ds_read_b128 v[146:149], v164
	ds_read_b128 v[156:159], v164 offset:1024
	ds_read_b128 v[160:163], v164 offset:2048
	ds_read_b128 v[164:167], v164 offset:3072
	ds_read_b128 v[168:171], v180
	ds_read_b128 v[172:175], v180 offset:1024
	ds_read_b128 v[176:179], v180 offset:2048
	ds_read_b128 v[180:183], v180 offset:3072
	s_add_u32 s22, s28, 0xb0000
	s_addc_u32 s23, s29, 0
	s_mov_b32 m0, s40
	ds_read_b128 v[184:187], v155 offset:32768
	ds_read_b128 v[188:191], v155 offset:33792
	ds_read_b128 v[192:195], v155 offset:34816
	ds_read_b128 v[196:199], v155 offset:35840
	ds_read_b128 v[200:203], v155 offset:36864
	ds_read_b128 v[204:207], v155 offset:37888
	ds_read_b128 v[208:211], v155 offset:38912
	ds_read_b128 v[212:215], v155 offset:39936
	global_load_lds_dwordx4 v128, s[22:23]
	s_mov_b32 m0, s41
	s_nop 0
	global_load_lds_dwordx4 v132, s[22:23]
	s_waitcnt vmcnt(8)
	s_waitcnt lgkmcnt(0)
	s_barrier
	s_setprio 1
	v_mfma_f32_16x16x32_bf16 v[124:127], v[146:149], v[184:187], v[124:127]
	v_mfma_f32_16x16x32_bf16 v[120:123], v[160:163], v[184:187], v[120:123]
	v_mfma_f32_16x16x32_bf16 v[116:119], v[146:149], v[192:195], v[116:119]
	v_mfma_f32_16x16x32_bf16 v[112:115], v[160:163], v[192:195], v[112:115]
	v_mfma_f32_16x16x32_bf16 v[92:95], v[146:149], v[200:203], v[92:95]
	v_mfma_f32_16x16x32_bf16 v[88:91], v[160:163], v[200:203], v[88:91]
	v_mfma_f32_16x16x32_bf16 v[76:79], v[146:149], v[208:211], v[76:79]
	v_mfma_f32_16x16x32_bf16 v[72:75], v[160:163], v[208:211], v[72:75]
	v_mfma_f32_16x16x32_bf16 v[124:127], v[156:159], v[188:191], v[124:127]
	v_mfma_f32_16x16x32_bf16 v[120:123], v[164:167], v[188:191], v[120:123]
	v_mfma_f32_16x16x32_bf16 v[116:119], v[156:159], v[196:199], v[116:119]
	v_mfma_f32_16x16x32_bf16 v[112:115], v[164:167], v[196:199], v[112:115]
	v_mfma_f32_16x16x32_bf16 v[92:95], v[156:159], v[204:207], v[92:95]
	v_mfma_f32_16x16x32_bf16 v[88:91], v[164:167], v[204:207], v[88:91]
	v_mfma_f32_16x16x32_bf16 v[76:79], v[156:159], v[212:215], v[76:79]
	v_mfma_f32_16x16x32_bf16 v[72:75], v[164:167], v[212:215], v[72:75]
	v_mfma_f32_16x16x32_bf16 v[108:111], v[168:171], v[184:187], v[108:111]
	v_mfma_f32_16x16x32_bf16 v[104:107], v[176:179], v[184:187], v[104:107]
	v_mfma_f32_16x16x32_bf16 v[100:103], v[168:171], v[192:195], v[100:103]
	v_mfma_f32_16x16x32_bf16 v[96:99], v[176:179], v[192:195], v[96:99]
	v_mfma_f32_16x16x32_bf16 v[84:87], v[168:171], v[200:203], v[84:87]
	v_mfma_f32_16x16x32_bf16 v[80:83], v[176:179], v[200:203], v[80:83]
	v_mfma_f32_16x16x32_bf16 v[68:71], v[168:171], v[208:211], v[68:71]
	v_mfma_f32_16x16x32_bf16 v[64:67], v[176:179], v[208:211], v[64:67]
	v_mfma_f32_16x16x32_bf16 v[108:111], v[172:175], v[188:191], v[108:111]
	v_mfma_f32_16x16x32_bf16 v[104:107], v[180:183], v[188:191], v[104:107]
	v_mfma_f32_16x16x32_bf16 v[100:103], v[172:175], v[196:199], v[100:103]
	v_mfma_f32_16x16x32_bf16 v[96:99], v[180:183], v[196:199], v[96:99]
	v_mfma_f32_16x16x32_bf16 v[84:87], v[172:175], v[204:207], v[84:87]
	v_mfma_f32_16x16x32_bf16 v[80:83], v[180:183], v[204:207], v[80:83]
	v_mfma_f32_16x16x32_bf16 v[68:71], v[172:175], v[212:215], v[68:71]
	v_mfma_f32_16x16x32_bf16 v[64:67], v[180:183], v[212:215], v[64:67]
	s_setprio 0
	s_barrier
	s_add_i32 s22, s57, s37
	v_lshl_add_u64 v[150:151], v[150:151], 0, s[8:9]
	s_mov_b32 m0, s22
	ds_read_b128 v[184:187], v155 offset:49152
	ds_read_b128 v[188:191], v155 offset:50176
	ds_read_b128 v[192:195], v155 offset:51200
	ds_read_b128 v[196:199], v155 offset:52224
	ds_read_b128 v[200:203], v155 offset:53248
	ds_read_b128 v[204:207], v155 offset:54272
	ds_read_b128 v[208:211], v155 offset:55296
	ds_read_b128 v[212:215], v155 offset:56320
	global_load_lds_dwordx4 v[150:151], off
	s_add_i32 m0, s22, 0x2000
	s_add_u32 s22, s26, 0xb0080
	v_lshl_add_u64 v[150:151], v[216:217], 0, s[8:9]
	s_addc_u32 s23, s27, 0
	s_add_i32 s26, s58, s37
	global_load_lds_dwordx4 v[150:151], off
	s_mov_b32 m0, s26
	s_nop 0
	global_load_lds_dwordx4 v130, s[22:23]
	s_add_i32 m0, s26, 0x2000
	s_nop 0
	global_load_lds_dwordx4 v134, s[22:23]
	v_lshl_add_u64 v[150:151], v[218:219], 0, s[8:9]
	s_mov_b32 m0, s43
	s_nop 0
	global_load_lds_dwordx4 v[150:151], off
	v_lshl_add_u64 v[150:151], v[220:221], 0, s[8:9]
	s_mov_b32 m0, s44
	s_nop 0
	global_load_lds_dwordx4 v[150:151], off
	s_waitcnt vmcnt(8)
	s_waitcnt lgkmcnt(0)
	s_barrier
	s_setprio 1
	v_mfma_f32_16x16x32_bf16 v[60:63], v[146:149], v[184:187], v[60:63]
	v_mfma_f32_16x16x32_bf16 v[56:59], v[160:163], v[184:187], v[56:59]
	v_mfma_f32_16x16x32_bf16 v[44:47], v[146:149], v[192:195], v[44:47]
	v_mfma_f32_16x16x32_bf16 v[40:43], v[160:163], v[192:195], v[40:43]
	v_mfma_f32_16x16x32_bf16 v[28:31], v[146:149], v[200:203], v[28:31]
	v_mfma_f32_16x16x32_bf16 v[24:27], v[160:163], v[200:203], v[24:27]
	v_mfma_f32_16x16x32_bf16 v[12:15], v[146:149], v[208:211], v[12:15]
	v_mfma_f32_16x16x32_bf16 v[8:11], v[160:163], v[208:211], v[8:11]
	v_mfma_f32_16x16x32_bf16 v[60:63], v[156:159], v[188:191], v[60:63]
	v_mfma_f32_16x16x32_bf16 v[56:59], v[164:167], v[188:191], v[56:59]
	v_mfma_f32_16x16x32_bf16 v[44:47], v[156:159], v[196:199], v[44:47]
	v_mfma_f32_16x16x32_bf16 v[40:43], v[164:167], v[196:199], v[40:43]
	v_mfma_f32_16x16x32_bf16 v[28:31], v[156:159], v[204:207], v[28:31]
	v_mfma_f32_16x16x32_bf16 v[24:27], v[164:167], v[204:207], v[24:27]
	v_mfma_f32_16x16x32_bf16 v[12:15], v[156:159], v[212:215], v[12:15]
	v_mfma_f32_16x16x32_bf16 v[8:11], v[164:167], v[212:215], v[8:11]
	v_mfma_f32_16x16x32_bf16 v[52:55], v[168:171], v[184:187], v[52:55]
	v_mfma_f32_16x16x32_bf16 v[48:51], v[176:179], v[184:187], v[48:51]
	v_mfma_f32_16x16x32_bf16 v[36:39], v[168:171], v[192:195], v[36:39]
	v_mfma_f32_16x16x32_bf16 v[32:35], v[176:179], v[192:195], v[32:35]
	v_mfma_f32_16x16x32_bf16 v[20:23], v[168:171], v[200:203], v[20:23]
	v_mfma_f32_16x16x32_bf16 v[16:19], v[176:179], v[200:203], v[16:19]
	v_mfma_f32_16x16x32_bf16 v[4:7], v[168:171], v[208:211], v[4:7]
	v_mfma_f32_16x16x32_bf16 v[0:3], v[176:179], v[208:211], v[0:3]
	v_mfma_f32_16x16x32_bf16 v[52:55], v[172:175], v[188:191], v[52:55]
	v_mfma_f32_16x16x32_bf16 v[48:51], v[180:183], v[188:191], v[48:51]
	v_mfma_f32_16x16x32_bf16 v[36:39], v[172:175], v[196:199], v[36:39]
	v_mfma_f32_16x16x32_bf16 v[32:35], v[180:183], v[196:199], v[32:35]
	v_mfma_f32_16x16x32_bf16 v[20:23], v[172:175], v[204:207], v[20:23]
	v_mfma_f32_16x16x32_bf16 v[16:19], v[180:183], v[204:207], v[16:19]
	v_mfma_f32_16x16x32_bf16 v[4:7], v[172:175], v[212:215], v[4:7]
	v_mfma_f32_16x16x32_bf16 v[0:3], v[180:183], v[212:215], v[0:3]
	s_setprio 0
	s_barrier
	s_add_i32 s56, s56, 2
	s_add_u32 s54, s54, 0x100
	s_addc_u32 s55, s55, 0
	s_cmp_gt_u32 s56, 41
	s_mov_b64 s[22:23], s[24:25]
	s_cbranch_scc0 .LBB0_1052
	s_and_b64 vcc, exec, s[10:11]
	s_cbranch_vccz .LBB0_1055
	s_barrier
